# RWKV scan: one merged LDS wait at the start of each step
# baseline (speedup 1.0000x reference)
.Lrw0_noout:
	ds_read_b128 v[30:33], v93 offset:46080
	ds_read_b128 v[34:37], v93 offset:46096
	ds_read_b128 v[38:41], v93 offset:46112
	ds_read_b128 v[42:45], v93 offset:46128
	ds_read_b64 v[70:71], v1 offset:27008
	ds_read_b64 v[72:73], v1 offset:26624
	ds_read_b64 v[74:75], v1 offset:27392
	ds_read_b64 v[76:77], v1 offset:27136
	ds_read_b64 v[78:79], v1 offset:26752
	ds_read_b64 v[80:81], v1 offset:27520
	ds_read_b64 v[82:83], v1 offset:27264
	ds_read_b64 v[84:85], v1 offset:26880
	ds_read_b64 v[96:97], v1 offset:27648
	ds_read_b64 v[128:129], v2 offset:33536
	ds_read_b64 v[130:131], v2 offset:33664
	v_add_u32_e32 v87, s28, v127
	v_cmp_ne_u32_e32 vcc, 0, v87
	s_nop 1
	v_cndmask_b32_e64 v98, 0, 0.5, vcc
	v_cmp_ne_u32_e32 vcc, s29, v87
	s_nop 1
	v_cndmask_b32_e64 v100, 0, 0.5, vcc
	s_waitcnt lgkmcnt(8)
	v_lshlrev_b32_e32 v132, 16, v70
	v_and_b32_e32 v133, 0xffff0000, v70
	v_lshlrev_b32_e32 v134, 16, v71
	v_and_b32_e32 v135, 0xffff0000, v71
	v_lshlrev_b32_e32 v136, 16, v72
	v_and_b32_e32 v137, 0xffff0000, v72
	v_lshlrev_b32_e32 v138, 16, v73
	v_and_b32_e32 v139, 0xffff0000, v73
	v_lshlrev_b32_e32 v140, 16, v74
	v_and_b32_e32 v141, 0xffff0000, v74
	v_lshlrev_b32_e32 v142, 16, v75
	v_and_b32_e32 v143, 0xffff0000, v75
	v_pk_mul_f32 v[136:137], v[136:137], v[98:99] op_sel_hi:[1,0]
	v_pk_fma_f32 v[136:137], v[140:141], v[100:101], v[136:137] op_sel_hi:[1,0,1]
	v_pk_add_f32 v[136:137], v[136:137], v[132:133] neg_lo:[0,1] neg_hi:[0,1]
	v_pk_fma_f32 v[144:145], v[30:31], v[136:137], v[132:133]
	v_pk_mul_f32 v[138:139], v[138:139], v[98:99] op_sel_hi:[1,0]
	v_pk_fma_f32 v[138:139], v[142:143], v[100:101], v[138:139] op_sel_hi:[1,0,1]
	v_pk_add_f32 v[138:139], v[138:139], v[134:135] neg_lo:[0,1] neg_hi:[0,1]
	v_pk_fma_f32 v[146:147], v[32:33], v[138:139], v[134:135]
	ds_read_b128 v[30:33], v93 offset:46144
	s_waitcnt lgkmcnt(6)
	v_lshlrev_b32_e32 v132, 16, v76
	v_and_b32_e32 v133, 0xffff0000, v76
	v_lshlrev_b32_e32 v134, 16, v77
	v_and_b32_e32 v135, 0xffff0000, v77
	v_lshlrev_b32_e32 v136, 16, v78
	v_and_b32_e32 v137, 0xffff0000, v78
	v_lshlrev_b32_e32 v138, 16, v79
	v_and_b32_e32 v139, 0xffff0000, v79
	v_lshlrev_b32_e32 v140, 16, v80
	v_and_b32_e32 v141, 0xffff0000, v80
	v_lshlrev_b32_e32 v142, 16, v81
	v_and_b32_e32 v143, 0xffff0000, v81
	v_pk_mul_f32 v[136:137], v[136:137], v[98:99] op_sel_hi:[1,0]
	v_pk_fma_f32 v[136:137], v[140:141], v[100:101], v[136:137] op_sel_hi:[1,0,1]
	v_pk_add_f32 v[136:137], v[136:137], v[132:133] neg_lo:[0,1] neg_hi:[0,1]
	v_pk_fma_f32 v[102:103], v[34:35], v[136:137], v[132:133]
	v_pk_mul_f32 v[138:139], v[138:139], v[98:99] op_sel_hi:[1,0]
	v_pk_fma_f32 v[138:139], v[142:143], v[100:101], v[138:139] op_sel_hi:[1,0,1]
	v_pk_add_f32 v[138:139], v[138:139], v[134:135] neg_lo:[0,1] neg_hi:[0,1]
	v_pk_fma_f32 v[104:105], v[36:37], v[138:139], v[134:135]
	s_waitcnt lgkmcnt(3)
	v_lshlrev_b32_e32 v132, 16, v82
	v_and_b32_e32 v133, 0xffff0000, v82
	v_lshlrev_b32_e32 v134, 16, v83
	v_and_b32_e32 v135, 0xffff0000, v83
	v_lshlrev_b32_e32 v136, 16, v84
	v_and_b32_e32 v137, 0xffff0000, v84
	v_lshlrev_b32_e32 v138, 16, v85
	v_and_b32_e32 v139, 0xffff0000, v85
	v_lshlrev_b32_e32 v140, 16, v96
	v_and_b32_e32 v141, 0xffff0000, v96
	v_lshlrev_b32_e32 v142, 16, v97
	v_and_b32_e32 v143, 0xffff0000, v97
	v_pk_mul_f32 v[136:137], v[136:137], v[98:99] op_sel_hi:[1,0]
	v_pk_fma_f32 v[136:137], v[140:141], v[100:101], v[136:137] op_sel_hi:[1,0,1]
	v_pk_add_f32 v[136:137], v[136:137], v[132:133] neg_lo:[0,1] neg_hi:[0,1]
	v_pk_fma_f32 v[148:149], v[38:39], v[136:137], v[132:133]
	v_pk_mul_f32 v[138:139], v[138:139], v[98:99] op_sel_hi:[1,0]
	v_pk_fma_f32 v[138:139], v[142:143], v[100:101], v[138:139] op_sel_hi:[1,0,1]
	v_pk_add_f32 v[138:139], v[138:139], v[134:135] neg_lo:[0,1] neg_hi:[0,1]
	v_pk_fma_f32 v[150:151], v[40:41], v[138:139], v[134:135]
	s_waitcnt lgkmcnt(0)
	v_lshlrev_b32_e32 v132, 16, v128
	v_and_b32_e32 v133, 0xffff0000, v128
	v_lshlrev_b32_e32 v134, 16, v129
	v_and_b32_e32 v135, 0xffff0000, v129
	v_lshlrev_b32_e32 v136, 16, v130
	v_and_b32_e32 v137, 0xffff0000, v130
	v_lshlrev_b32_e32 v138, 16, v131
	v_and_b32_e32 v139, 0xffff0000, v131
	s_mov_b32 s98, 0xbf60028b
	v_mul_f32_e32 v132, s98, v132
	v_mul_f32_e32 v133, s98, v133
	v_mul_f32_e32 v134, s98, v134
	v_mul_f32_e32 v135, s98, v135
	v_exp_f32_e32 v132, v132
	v_exp_f32_e32 v133, v133
	v_exp_f32_e32 v134, v134
	v_exp_f32_e32 v135, v135
	v_pk_mul_f32 v[140:141], v[102:103], v[42:43]
	v_pk_mul_f32 v[142:143], v[104:105], v[44:45]
	v_pk_mul_f32 v[106:107], v[140:141], v[140:141]
	v_pk_fma_f32 v[106:107], v[142:143], v[142:143], v[106:107]
	v_add_f32_e32 v106, v106, v107
	s_nop 1
	v_add_f32_dpp v106, v106, v106 row_ror:8 row_mask:0xf bank_mask:0xf bound_ctrl:1
	s_nop 1
	v_add_f32_dpp v106, v106, v106 row_ror:4 row_mask:0xf bank_mask:0xf bound_ctrl:1
	s_nop 1
	v_add_f32_dpp v106, v106, v106 row_ror:2 row_mask:0xf bank_mask:0xf bound_ctrl:1
	s_nop 1
	v_add_f32_dpp v106, v106, v106 row_ror:1 row_mask:0xf bank_mask:0xf bound_ctrl:1
	v_add_f32_e32 v106, 0x2b8cbccc, v106
	v_rsq_f32_e32 v106, v106
	v_pk_mul_f32 v[148:149], v[148:149], s[40:41] op_sel_hi:[1,0]
	v_pk_mul_f32 v[150:151], v[150:151], s[40:41] op_sel_hi:[1,0]
	v_pk_mul_f32 v[140:141], v[140:141], v[106:107] op_sel_hi:[1,0]
	v_pk_mul_f32 v[142:143], v[142:143], v[106:107] op_sel_hi:[1,0]
	v_pk_add_f32 v[70:71], v[136:137], -1.0 op_sel_hi:[1,0]
	v_pk_add_f32 v[72:73], v[138:139], -1.0 op_sel_hi:[1,0]
	v_pk_fma_f32 v[70:71], v[30:31], v[70:71], 1.0 op_sel_hi:[1,1,0]
	v_pk_fma_f32 v[72:73], v[32:33], v[72:73], 1.0 op_sel_hi:[1,1,0]
	v_pk_mul_f32 v[70:71], v[102:103], v[70:71]
	v_pk_mul_f32 v[72:73], v[104:105], v[72:73]
	v_pk_mul_f32 v[74:75], v[140:141], v[136:137]
	v_pk_mul_f32 v[76:77], v[142:143], v[138:139]
	ds_write_b128 v3, v[140:143] offset:0
	ds_write_b128 v3, v[132:135] offset:4096
	ds_write_b128 v3, v[74:77] offset:8192
	ds_write_b128 v3, v[70:73] offset:12288
	ds_write_b128 v3, v[144:147] offset:16384
	ds_write_b128 v4, v[148:151]
	s_waitcnt lgkmcnt(0)
	s_barrier
	s_cmp_eq_u32 s18, 2
	s_cbranch_scc1 .Lrw0_u2s0
	ds_read_b128 v[30:33], v112 offset:0
	ds_read_b128 v[34:37], v112 offset:16
	ds_read_b128 v[78:81], v112 offset:12288
	ds_read_b128 v[82:85], v112 offset:12304
	ds_read_b32 v104, v108 offset:20480
	ds_read_b128 v[38:41], v112 offset:4096
	ds_read_b128 v[42:45], v112 offset:4112
	ds_read_b128 v[70:73], v112 offset:8192
	ds_read_b128 v[74:77], v112 offset:8208
	s_waitcnt lgkmcnt(2)
	v_pk_mul_f32 v[136:137], v[22:23], v[30:31]
	v_pk_fma_f32 v[136:137], v[24:25], v[32:33], v[136:137]
	v_pk_fma_f32 v[136:137], v[26:27], v[34:35], v[136:137]
	v_pk_fma_f32 v[136:137], v[28:29], v[36:37], v[136:137]
	ds_read_b128 v[30:33], v112 offset:256
	ds_read_b128 v[34:37], v112 offset:272
	ds_read_b128 v[96:99], v112 offset:16384
	ds_read_b128 v[100:103], v112 offset:16400
	v_add_f32_e32 v140, v136, v137
	v_pk_mul_f32 v[128:129], v[78:79], v[104:105] op_sel_hi:[1,0]
	s_nop 0
	v_add_f32_dpp v140, v140, v140 row_half_mirror row_mask:0xf bank_mask:0xf
	v_pk_mul_f32 v[130:131], v[80:81], v[104:105] op_sel_hi:[1,0]
	v_pk_mul_f32 v[132:133], v[82:83], v[104:105] op_sel_hi:[1,0]
	v_pk_mul_f32 v[134:135], v[84:85], v[104:105] op_sel_hi:[1,0]
	ds_read_b128 v[78:81], v112 offset:12544
	ds_read_b128 v[82:85], v112 offset:12560
	ds_read_b32 v104, v108 offset:20608
	v_add_f32_dpp v140, v140, v140 quad_perm:[1,0,3,2] row_mask:0xf bank_mask:0xf
	v_pk_fma_f32 v[128:129], v[22:23], v[38:39], v[128:129]
	v_pk_fma_f32 v[130:131], v[24:25], v[40:41], v[130:131]
	v_pk_fma_f32 v[132:133], v[26:27], v[42:43], v[132:133]
	v_add_f32_dpp v140, v140, v140 quad_perm:[2,3,0,1] row_mask:0xf bank_mask:0xf
	v_pk_fma_f32 v[134:135], v[28:29], v[44:45], v[134:135]
	ds_read_b128 v[38:41], v112 offset:4352
	ds_read_b128 v[42:45], v112 offset:4368
	s_waitcnt lgkmcnt(9)
	v_pk_fma_f32 v[22:23], v[140:141], v[70:71], v[128:129] op_sel_hi:[0,1,1] neg_lo:[1,0,0] neg_hi:[1,0,0]
	v_pk_fma_f32 v[24:25], v[140:141], v[72:73], v[130:131] op_sel_hi:[0,1,1] neg_lo:[1,0,0] neg_hi:[1,0,0]
	v_pk_fma_f32 v[26:27], v[140:141], v[74:75], v[132:133] op_sel_hi:[0,1,1] neg_lo:[1,0,0] neg_hi:[1,0,0]
	v_pk_fma_f32 v[28:29], v[140:141], v[76:77], v[134:135] op_sel_hi:[0,1,1] neg_lo:[1,0,0] neg_hi:[1,0,0]
	ds_read_b128 v[70:73], v112 offset:8448
	ds_read_b128 v[74:77], v112 offset:8464
	s_waitcnt lgkmcnt(2)
	v_pk_mul_f32 v[136:137], v[22:23], v[30:31]
	v_pk_mul_f32 v[138:139], v[22:23], v[96:97]
	v_pk_fma_f32 v[136:137], v[24:25], v[32:33], v[136:137]
	v_pk_fma_f32 v[138:139], v[24:25], v[98:99], v[138:139]
	v_pk_fma_f32 v[136:137], v[26:27], v[34:35], v[136:137]
	v_pk_fma_f32 v[138:139], v[26:27], v[100:101], v[138:139]
	v_pk_fma_f32 v[136:137], v[28:29], v[36:37], v[136:137]
	v_pk_fma_f32 v[138:139], v[28:29], v[102:103], v[138:139]
	ds_read_b128 v[30:33], v112 offset:512
	ds_read_b128 v[34:37], v112 offset:528
	ds_read_b128 v[96:99], v112 offset:16640
	ds_read_b128 v[100:103], v112 offset:16656
	v_add_f32_e32 v140, v136, v137
	v_add_f32_e32 v142, v138, v139
	v_pk_mul_f32 v[128:129], v[78:79], v[104:105] op_sel_hi:[1,0]
	v_add_f32_dpp v140, v140, v140 row_half_mirror row_mask:0xf bank_mask:0xf
	v_add_f32_dpp v142, v142, v142 row_half_mirror row_mask:0xf bank_mask:0xf
	v_pk_mul_f32 v[130:131], v[80:81], v[104:105] op_sel_hi:[1,0]
	v_pk_mul_f32 v[132:133], v[82:83], v[104:105] op_sel_hi:[1,0]
	v_add_f32_dpp v140, v140, v140 quad_perm:[1,0,3,2] row_mask:0xf bank_mask:0xf
	v_add_f32_dpp v142, v142, v142 quad_perm:[1,0,3,2] row_mask:0xf bank_mask:0xf
	v_pk_mul_f32 v[134:135], v[84:85], v[104:105] op_sel_hi:[1,0]
	ds_read_b128 v[78:81], v112 offset:12800
	ds_read_b128 v[82:85], v112 offset:12816
	ds_read_b32 v104, v108 offset:20736
	v_pk_fma_f32 v[128:129], v[22:23], v[38:39], v[128:129]
	v_add_f32_dpp v140, v140, v140 quad_perm:[2,3,0,1] row_mask:0xf bank_mask:0xf
	v_add_f32_dpp v142, v142, v142 quad_perm:[2,3,0,1] row_mask:0xf bank_mask:0xf
	v_pk_fma_f32 v[130:131], v[24:25], v[40:41], v[130:131]
	v_pk_fma_f32 v[132:133], v[26:27], v[42:43], v[132:133]
	v_pk_fma_f32 v[134:135], v[28:29], v[44:45], v[134:135]
	ds_read_b128 v[38:41], v112 offset:4608
	ds_read_b128 v[42:45], v112 offset:4624
	s_waitcnt lgkmcnt(9)
	v_pk_fma_f32 v[22:23], v[140:141], v[70:71], v[128:129] op_sel_hi:[0,1,1] neg_lo:[1,0,0] neg_hi:[1,0,0]
	v_pk_fma_f32 v[24:25], v[140:141], v[72:73], v[130:131] op_sel_hi:[0,1,1] neg_lo:[1,0,0] neg_hi:[1,0,0]
	v_pk_fma_f32 v[26:27], v[140:141], v[74:75], v[132:133] op_sel_hi:[0,1,1] neg_lo:[1,0,0] neg_hi:[1,0,0]
	v_pk_fma_f32 v[28:29], v[140:141], v[76:77], v[134:135] op_sel_hi:[0,1,1] neg_lo:[1,0,0] neg_hi:[1,0,0]
	ds_read_b128 v[70:73], v112 offset:8704
	ds_read_b128 v[74:77], v112 offset:8720
	ds_write_b32 v108, v142 offset:22528
	s_waitcnt lgkmcnt(3)
	v_pk_mul_f32 v[136:137], v[22:23], v[30:31]
	v_pk_mul_f32 v[138:139], v[22:23], v[96:97]
	v_pk_fma_f32 v[136:137], v[24:25], v[32:33], v[136:137]
	v_pk_fma_f32 v[138:139], v[24:25], v[98:99], v[138:139]
	v_pk_fma_f32 v[136:137], v[26:27], v[34:35], v[136:137]
	v_pk_fma_f32 v[138:139], v[26:27], v[100:101], v[138:139]
	v_pk_fma_f32 v[136:137], v[28:29], v[36:37], v[136:137]
	v_pk_fma_f32 v[138:139], v[28:29], v[102:103], v[138:139]
	ds_read_b128 v[30:33], v112 offset:768
	ds_read_b128 v[34:37], v112 offset:784
	ds_read_b128 v[96:99], v112 offset:16896
	ds_read_b128 v[100:103], v112 offset:16912
	v_add_f32_e32 v140, v136, v137
	v_add_f32_e32 v142, v138, v139
	v_pk_mul_f32 v[128:129], v[78:79], v[104:105] op_sel_hi:[1,0]
	v_add_f32_dpp v140, v140, v140 row_half_mirror row_mask:0xf bank_mask:0xf
	v_add_f32_dpp v142, v142, v142 row_half_mirror row_mask:0xf bank_mask:0xf
	v_pk_mul_f32 v[130:131], v[80:81], v[104:105] op_sel_hi:[1,0]
	v_pk_mul_f32 v[132:133], v[82:83], v[104:105] op_sel_hi:[1,0]
	v_add_f32_dpp v140, v140, v140 quad_perm:[1,0,3,2] row_mask:0xf bank_mask:0xf
	v_add_f32_dpp v142, v142, v142 quad_perm:[1,0,3,2] row_mask:0xf bank_mask:0xf
	v_pk_mul_f32 v[134:135], v[84:85], v[104:105] op_sel_hi:[1,0]
	ds_read_b128 v[78:81], v112 offset:13056
	ds_read_b128 v[82:85], v112 offset:13072
	ds_read_b32 v104, v108 offset:20864
	v_pk_fma_f32 v[128:129], v[22:23], v[38:39], v[128:129]
	v_add_f32_dpp v140, v140, v140 quad_perm:[2,3,0,1] row_mask:0xf bank_mask:0xf
	v_add_f32_dpp v142, v142, v142 quad_perm:[2,3,0,1] row_mask:0xf bank_mask:0xf
	v_pk_fma_f32 v[130:131], v[24:25], v[40:41], v[130:131]
	v_pk_fma_f32 v[132:133], v[26:27], v[42:43], v[132:133]
	v_pk_fma_f32 v[134:135], v[28:29], v[44:45], v[134:135]
	ds_read_b128 v[38:41], v112 offset:4864
	ds_read_b128 v[42:45], v112 offset:4880
	s_waitcnt lgkmcnt(10)
	v_pk_fma_f32 v[22:23], v[140:141], v[70:71], v[128:129] op_sel_hi:[0,1,1] neg_lo:[1,0,0] neg_hi:[1,0,0]
	v_pk_fma_f32 v[24:25], v[140:141], v[72:73], v[130:131] op_sel_hi:[0,1,1] neg_lo:[1,0,0] neg_hi:[1,0,0]
	v_pk_fma_f32 v[26:27], v[140:141], v[74:75], v[132:133] op_sel_hi:[0,1,1] neg_lo:[1,0,0] neg_hi:[1,0,0]
	v_pk_fma_f32 v[28:29], v[140:141], v[76:77], v[134:135] op_sel_hi:[0,1,1] neg_lo:[1,0,0] neg_hi:[1,0,0]
	ds_read_b128 v[70:73], v112 offset:8960
	ds_read_b128 v[74:77], v112 offset:8976
	ds_write_b32 v108, v142 offset:22656
	s_waitcnt lgkmcnt(3)
	v_pk_mul_f32 v[136:137], v[22:23], v[30:31]
	v_pk_mul_f32 v[138:139], v[22:23], v[96:97]
	v_pk_fma_f32 v[136:137], v[24:25], v[32:33], v[136:137]
	v_pk_fma_f32 v[138:139], v[24:25], v[98:99], v[138:139]
	v_pk_fma_f32 v[136:137], v[26:27], v[34:35], v[136:137]
	v_pk_fma_f32 v[138:139], v[26:27], v[100:101], v[138:139]
	v_pk_fma_f32 v[136:137], v[28:29], v[36:37], v[136:137]
	v_pk_fma_f32 v[138:139], v[28:29], v[102:103], v[138:139]
	ds_read_b128 v[30:33], v112 offset:1024
	ds_read_b128 v[34:37], v112 offset:1040
	ds_read_b128 v[96:99], v112 offset:17152
	ds_read_b128 v[100:103], v112 offset:17168
	v_add_f32_e32 v140, v136, v137
	v_add_f32_e32 v142, v138, v139
	v_pk_mul_f32 v[128:129], v[78:79], v[104:105] op_sel_hi:[1,0]
	v_add_f32_dpp v140, v140, v140 row_half_mirror row_mask:0xf bank_mask:0xf
	v_add_f32_dpp v142, v142, v142 row_half_mirror row_mask:0xf bank_mask:0xf
	v_pk_mul_f32 v[130:131], v[80:81], v[104:105] op_sel_hi:[1,0]
	v_pk_mul_f32 v[132:133], v[82:83], v[104:105] op_sel_hi:[1,0]
	v_add_f32_dpp v140, v140, v140 quad_perm:[1,0,3,2] row_mask:0xf bank_mask:0xf
	v_add_f32_dpp v142, v142, v142 quad_perm:[1,0,3,2] row_mask:0xf bank_mask:0xf
	v_pk_mul_f32 v[134:135], v[84:85], v[104:105] op_sel_hi:[1,0]
	ds_read_b128 v[78:81], v112 offset:13312
	ds_read_b128 v[82:85], v112 offset:13328
	ds_read_b32 v104, v108 offset:20992
	v_pk_fma_f32 v[128:129], v[22:23], v[38:39], v[128:129]
	v_add_f32_dpp v140, v140, v140 quad_perm:[2,3,0,1] row_mask:0xf bank_mask:0xf
	v_add_f32_dpp v142, v142, v142 quad_perm:[2,3,0,1] row_mask:0xf bank_mask:0xf
	v_pk_fma_f32 v[130:131], v[24:25], v[40:41], v[130:131]
	v_pk_fma_f32 v[132:133], v[26:27], v[42:43], v[132:133]
	v_pk_fma_f32 v[134:135], v[28:29], v[44:45], v[134:135]
	ds_read_b128 v[38:41], v112 offset:5120
	ds_read_b128 v[42:45], v112 offset:5136
	s_waitcnt lgkmcnt(10)
	v_pk_fma_f32 v[22:23], v[140:141], v[70:71], v[128:129] op_sel_hi:[0,1,1] neg_lo:[1,0,0] neg_hi:[1,0,0]
	v_pk_fma_f32 v[24:25], v[140:141], v[72:73], v[130:131] op_sel_hi:[0,1,1] neg_lo:[1,0,0] neg_hi:[1,0,0]
	v_pk_fma_f32 v[26:27], v[140:141], v[74:75], v[132:133] op_sel_hi:[0,1,1] neg_lo:[1,0,0] neg_hi:[1,0,0]
	v_pk_fma_f32 v[28:29], v[140:141], v[76:77], v[134:135] op_sel_hi:[0,1,1] neg_lo:[1,0,0] neg_hi:[1,0,0]
	ds_read_b128 v[70:73], v112 offset:9216
	ds_read_b128 v[74:77], v112 offset:9232
	ds_write_b32 v108, v142 offset:22784
	s_waitcnt lgkmcnt(3)
	v_pk_mul_f32 v[136:137], v[22:23], v[30:31]
	v_pk_mul_f32 v[138:139], v[22:23], v[96:97]
	v_pk_fma_f32 v[136:137], v[24:25], v[32:33], v[136:137]
	v_pk_fma_f32 v[138:139], v[24:25], v[98:99], v[138:139]
	v_pk_fma_f32 v[136:137], v[26:27], v[34:35], v[136:137]
	v_pk_fma_f32 v[138:139], v[26:27], v[100:101], v[138:139]
	v_pk_fma_f32 v[136:137], v[28:29], v[36:37], v[136:137]
	v_pk_fma_f32 v[138:139], v[28:29], v[102:103], v[138:139]
	ds_read_b128 v[30:33], v112 offset:1280
	ds_read_b128 v[34:37], v112 offset:1296
	ds_read_b128 v[96:99], v112 offset:17408
	ds_read_b128 v[100:103], v112 offset:17424
	v_add_f32_e32 v140, v136, v137
	v_add_f32_e32 v142, v138, v139
	v_pk_mul_f32 v[128:129], v[78:79], v[104:105] op_sel_hi:[1,0]
	v_add_f32_dpp v140, v140, v140 row_half_mirror row_mask:0xf bank_mask:0xf
	v_add_f32_dpp v142, v142, v142 row_half_mirror row_mask:0xf bank_mask:0xf
	v_pk_mul_f32 v[130:131], v[80:81], v[104:105] op_sel_hi:[1,0]
	v_pk_mul_f32 v[132:133], v[82:83], v[104:105] op_sel_hi:[1,0]
	v_add_f32_dpp v140, v140, v140 quad_perm:[1,0,3,2] row_mask:0xf bank_mask:0xf
	v_add_f32_dpp v142, v142, v142 quad_perm:[1,0,3,2] row_mask:0xf bank_mask:0xf
	v_pk_mul_f32 v[134:135], v[84:85], v[104:105] op_sel_hi:[1,0]
	ds_read_b128 v[78:81], v112 offset:13568
	ds_read_b128 v[82:85], v112 offset:13584
	ds_read_b32 v104, v108 offset:21120
	v_pk_fma_f32 v[128:129], v[22:23], v[38:39], v[128:129]
	v_add_f32_dpp v140, v140, v140 quad_perm:[2,3,0,1] row_mask:0xf bank_mask:0xf
	v_add_f32_dpp v142, v142, v142 quad_perm:[2,3,0,1] row_mask:0xf bank_mask:0xf
	v_pk_fma_f32 v[130:131], v[24:25], v[40:41], v[130:131]
	v_pk_fma_f32 v[132:133], v[26:27], v[42:43], v[132:133]
	v_pk_fma_f32 v[134:135], v[28:29], v[44:45], v[134:135]
	ds_read_b128 v[38:41], v112 offset:5376
	ds_read_b128 v[42:45], v112 offset:5392
	s_waitcnt lgkmcnt(10)
	v_pk_fma_f32 v[22:23], v[140:141], v[70:71], v[128:129] op_sel_hi:[0,1,1] neg_lo:[1,0,0] neg_hi:[1,0,0]
	v_pk_fma_f32 v[24:25], v[140:141], v[72:73], v[130:131] op_sel_hi:[0,1,1] neg_lo:[1,0,0] neg_hi:[1,0,0]
	v_pk_fma_f32 v[26:27], v[140:141], v[74:75], v[132:133] op_sel_hi:[0,1,1] neg_lo:[1,0,0] neg_hi:[1,0,0]
	v_pk_fma_f32 v[28:29], v[140:141], v[76:77], v[134:135] op_sel_hi:[0,1,1] neg_lo:[1,0,0] neg_hi:[1,0,0]
	ds_read_b128 v[70:73], v112 offset:9472
	ds_read_b128 v[74:77], v112 offset:9488
	ds_write_b32 v108, v142 offset:22912
	s_waitcnt lgkmcnt(3)
	v_pk_mul_f32 v[136:137], v[22:23], v[30:31]
	v_pk_mul_f32 v[138:139], v[22:23], v[96:97]
	v_pk_fma_f32 v[136:137], v[24:25], v[32:33], v[136:137]
	v_pk_fma_f32 v[138:139], v[24:25], v[98:99], v[138:139]
	v_pk_fma_f32 v[136:137], v[26:27], v[34:35], v[136:137]
	v_pk_fma_f32 v[138:139], v[26:27], v[100:101], v[138:139]
	v_pk_fma_f32 v[136:137], v[28:29], v[36:37], v[136:137]
	v_pk_fma_f32 v[138:139], v[28:29], v[102:103], v[138:139]
	ds_read_b128 v[30:33], v112 offset:1536
	ds_read_b128 v[34:37], v112 offset:1552
	ds_read_b128 v[96:99], v112 offset:17664
	ds_read_b128 v[100:103], v112 offset:17680
	v_add_f32_e32 v140, v136, v137
	v_add_f32_e32 v142, v138, v139
	v_pk_mul_f32 v[128:129], v[78:79], v[104:105] op_sel_hi:[1,0]
	v_add_f32_dpp v140, v140, v140 row_half_mirror row_mask:0xf bank_mask:0xf
	v_add_f32_dpp v142, v142, v142 row_half_mirror row_mask:0xf bank_mask:0xf
	v_pk_mul_f32 v[130:131], v[80:81], v[104:105] op_sel_hi:[1,0]
	v_pk_mul_f32 v[132:133], v[82:83], v[104:105] op_sel_hi:[1,0]
	v_add_f32_dpp v140, v140, v140 quad_perm:[1,0,3,2] row_mask:0xf bank_mask:0xf
	v_add_f32_dpp v142, v142, v142 quad_perm:[1,0,3,2] row_mask:0xf bank_mask:0xf
	v_pk_mul_f32 v[134:135], v[84:85], v[104:105] op_sel_hi:[1,0]
	ds_read_b128 v[78:81], v112 offset:13824
	ds_read_b128 v[82:85], v112 offset:13840
	ds_read_b32 v104, v108 offset:21248
	v_pk_fma_f32 v[128:129], v[22:23], v[38:39], v[128:129]
	v_add_f32_dpp v140, v140, v140 quad_perm:[2,3,0,1] row_mask:0xf bank_mask:0xf
	v_add_f32_dpp v142, v142, v142 quad_perm:[2,3,0,1] row_mask:0xf bank_mask:0xf
	v_pk_fma_f32 v[130:131], v[24:25], v[40:41], v[130:131]
	v_pk_fma_f32 v[132:133], v[26:27], v[42:43], v[132:133]
	v_pk_fma_f32 v[134:135], v[28:29], v[44:45], v[134:135]
	ds_read_b128 v[38:41], v112 offset:5632
	ds_read_b128 v[42:45], v112 offset:5648
	s_waitcnt lgkmcnt(10)
	v_pk_fma_f32 v[22:23], v[140:141], v[70:71], v[128:129] op_sel_hi:[0,1,1] neg_lo:[1,0,0] neg_hi:[1,0,0]
	v_pk_fma_f32 v[24:25], v[140:141], v[72:73], v[130:131] op_sel_hi:[0,1,1] neg_lo:[1,0,0] neg_hi:[1,0,0]
	v_pk_fma_f32 v[26:27], v[140:141], v[74:75], v[132:133] op_sel_hi:[0,1,1] neg_lo:[1,0,0] neg_hi:[1,0,0]
	v_pk_fma_f32 v[28:29], v[140:141], v[76:77], v[134:135] op_sel_hi:[0,1,1] neg_lo:[1,0,0] neg_hi:[1,0,0]
	ds_read_b128 v[70:73], v112 offset:9728
	ds_read_b128 v[74:77], v112 offset:9744
	ds_write_b32 v108, v142 offset:23040
	s_waitcnt lgkmcnt(3)
	v_pk_mul_f32 v[136:137], v[22:23], v[30:31]
	v_pk_mul_f32 v[138:139], v[22:23], v[96:97]
	v_pk_fma_f32 v[136:137], v[24:25], v[32:33], v[136:137]
	v_pk_fma_f32 v[138:139], v[24:25], v[98:99], v[138:139]
	v_pk_fma_f32 v[136:137], v[26:27], v[34:35], v[136:137]
	v_pk_fma_f32 v[138:139], v[26:27], v[100:101], v[138:139]
	v_pk_fma_f32 v[136:137], v[28:29], v[36:37], v[136:137]
	v_pk_fma_f32 v[138:139], v[28:29], v[102:103], v[138:139]
	ds_read_b128 v[30:33], v112 offset:1792
	ds_read_b128 v[34:37], v112 offset:1808
	ds_read_b128 v[96:99], v112 offset:17920
	ds_read_b128 v[100:103], v112 offset:17936
	v_add_f32_e32 v140, v136, v137
	v_add_f32_e32 v142, v138, v139
	v_pk_mul_f32 v[128:129], v[78:79], v[104:105] op_sel_hi:[1,0]
	v_add_f32_dpp v140, v140, v140 row_half_mirror row_mask:0xf bank_mask:0xf
	v_add_f32_dpp v142, v142, v142 row_half_mirror row_mask:0xf bank_mask:0xf
	v_pk_mul_f32 v[130:131], v[80:81], v[104:105] op_sel_hi:[1,0]
	v_pk_mul_f32 v[132:133], v[82:83], v[104:105] op_sel_hi:[1,0]
	v_add_f32_dpp v140, v140, v140 quad_perm:[1,0,3,2] row_mask:0xf bank_mask:0xf
	v_add_f32_dpp v142, v142, v142 quad_perm:[1,0,3,2] row_mask:0xf bank_mask:0xf
	v_pk_mul_f32 v[134:135], v[84:85], v[104:105] op_sel_hi:[1,0]
	ds_read_b128 v[78:81], v112 offset:14080
	ds_read_b128 v[82:85], v112 offset:14096
	ds_read_b32 v104, v108 offset:21376
	v_pk_fma_f32 v[128:129], v[22:23], v[38:39], v[128:129]
	v_add_f32_dpp v140, v140, v140 quad_perm:[2,3,0,1] row_mask:0xf bank_mask:0xf
	v_add_f32_dpp v142, v142, v142 quad_perm:[2,3,0,1] row_mask:0xf bank_mask:0xf
	v_pk_fma_f32 v[130:131], v[24:25], v[40:41], v[130:131]
	v_pk_fma_f32 v[132:133], v[26:27], v[42:43], v[132:133]
	v_pk_fma_f32 v[134:135], v[28:29], v[44:45], v[134:135]
	ds_read_b128 v[38:41], v112 offset:5888
	ds_read_b128 v[42:45], v112 offset:5904
	s_waitcnt lgkmcnt(10)
	v_pk_fma_f32 v[22:23], v[140:141], v[70:71], v[128:129] op_sel_hi:[0,1,1] neg_lo:[1,0,0] neg_hi:[1,0,0]
	v_pk_fma_f32 v[24:25], v[140:141], v[72:73], v[130:131] op_sel_hi:[0,1,1] neg_lo:[1,0,0] neg_hi:[1,0,0]
	v_pk_fma_f32 v[26:27], v[140:141], v[74:75], v[132:133] op_sel_hi:[0,1,1] neg_lo:[1,0,0] neg_hi:[1,0,0]
	v_pk_fma_f32 v[28:29], v[140:141], v[76:77], v[134:135] op_sel_hi:[0,1,1] neg_lo:[1,0,0] neg_hi:[1,0,0]
	ds_read_b128 v[70:73], v112 offset:9984
	ds_read_b128 v[74:77], v112 offset:10000
	ds_write_b32 v108, v142 offset:23168
	s_waitcnt lgkmcnt(3)
	v_pk_mul_f32 v[136:137], v[22:23], v[30:31]
	v_pk_mul_f32 v[138:139], v[22:23], v[96:97]
	v_pk_fma_f32 v[136:137], v[24:25], v[32:33], v[136:137]
	v_pk_fma_f32 v[138:139], v[24:25], v[98:99], v[138:139]
	v_pk_fma_f32 v[136:137], v[26:27], v[34:35], v[136:137]
	v_pk_fma_f32 v[138:139], v[26:27], v[100:101], v[138:139]
	v_pk_fma_f32 v[136:137], v[28:29], v[36:37], v[136:137]
	v_pk_fma_f32 v[138:139], v[28:29], v[102:103], v[138:139]
	ds_read_b128 v[30:33], v112 offset:2048
	ds_read_b128 v[34:37], v112 offset:2064
	ds_read_b128 v[96:99], v112 offset:18176
	ds_read_b128 v[100:103], v112 offset:18192
	v_add_f32_e32 v140, v136, v137
	v_add_f32_e32 v142, v138, v139
	v_pk_mul_f32 v[128:129], v[78:79], v[104:105] op_sel_hi:[1,0]
	v_add_f32_dpp v140, v140, v140 row_half_mirror row_mask:0xf bank_mask:0xf
	v_add_f32_dpp v142, v142, v142 row_half_mirror row_mask:0xf bank_mask:0xf
	v_pk_mul_f32 v[130:131], v[80:81], v[104:105] op_sel_hi:[1,0]
	v_pk_mul_f32 v[132:133], v[82:83], v[104:105] op_sel_hi:[1,0]
	v_add_f32_dpp v140, v140, v140 quad_perm:[1,0,3,2] row_mask:0xf bank_mask:0xf
	v_add_f32_dpp v142, v142, v142 quad_perm:[1,0,3,2] row_mask:0xf bank_mask:0xf
	v_pk_mul_f32 v[134:135], v[84:85], v[104:105] op_sel_hi:[1,0]
	ds_read_b128 v[78:81], v112 offset:14336
	ds_read_b128 v[82:85], v112 offset:14352
	ds_read_b32 v104, v108 offset:21504
	v_pk_fma_f32 v[128:129], v[22:23], v[38:39], v[128:129]
	v_add_f32_dpp v140, v140, v140 quad_perm:[2,3,0,1] row_mask:0xf bank_mask:0xf
	v_add_f32_dpp v142, v142, v142 quad_perm:[2,3,0,1] row_mask:0xf bank_mask:0xf
	v_pk_fma_f32 v[130:131], v[24:25], v[40:41], v[130:131]
	v_pk_fma_f32 v[132:133], v[26:27], v[42:43], v[132:133]
	v_pk_fma_f32 v[134:135], v[28:29], v[44:45], v[134:135]
	ds_read_b128 v[38:41], v112 offset:6144
	ds_read_b128 v[42:45], v112 offset:6160
	s_waitcnt lgkmcnt(10)
	v_pk_fma_f32 v[22:23], v[140:141], v[70:71], v[128:129] op_sel_hi:[0,1,1] neg_lo:[1,0,0] neg_hi:[1,0,0]
	v_pk_fma_f32 v[24:25], v[140:141], v[72:73], v[130:131] op_sel_hi:[0,1,1] neg_lo:[1,0,0] neg_hi:[1,0,0]
	v_pk_fma_f32 v[26:27], v[140:141], v[74:75], v[132:133] op_sel_hi:[0,1,1] neg_lo:[1,0,0] neg_hi:[1,0,0]
	v_pk_fma_f32 v[28:29], v[140:141], v[76:77], v[134:135] op_sel_hi:[0,1,1] neg_lo:[1,0,0] neg_hi:[1,0,0]
	ds_read_b128 v[70:73], v112 offset:10240
	ds_read_b128 v[74:77], v112 offset:10256
	ds_write_b32 v108, v142 offset:23296
	s_waitcnt lgkmcnt(3)
	v_pk_mul_f32 v[136:137], v[22:23], v[30:31]
	v_pk_mul_f32 v[138:139], v[22:23], v[96:97]
	v_pk_fma_f32 v[136:137], v[24:25], v[32:33], v[136:137]
	v_pk_fma_f32 v[138:139], v[24:25], v[98:99], v[138:139]
	v_pk_fma_f32 v[136:137], v[26:27], v[34:35], v[136:137]
	v_pk_fma_f32 v[138:139], v[26:27], v[100:101], v[138:139]
	v_pk_fma_f32 v[136:137], v[28:29], v[36:37], v[136:137]
	v_pk_fma_f32 v[138:139], v[28:29], v[102:103], v[138:139]
	ds_read_b128 v[30:33], v112 offset:2304
	ds_read_b128 v[34:37], v112 offset:2320
	ds_read_b128 v[96:99], v112 offset:18432
	ds_read_b128 v[100:103], v112 offset:18448
	v_add_f32_e32 v140, v136, v137
	v_add_f32_e32 v142, v138, v139
	v_pk_mul_f32 v[128:129], v[78:79], v[104:105] op_sel_hi:[1,0]
	v_add_f32_dpp v140, v140, v140 row_half_mirror row_mask:0xf bank_mask:0xf
	v_add_f32_dpp v142, v142, v142 row_half_mirror row_mask:0xf bank_mask:0xf
	v_pk_mul_f32 v[130:131], v[80:81], v[104:105] op_sel_hi:[1,0]
	v_pk_mul_f32 v[132:133], v[82:83], v[104:105] op_sel_hi:[1,0]
	v_add_f32_dpp v140, v140, v140 quad_perm:[1,0,3,2] row_mask:0xf bank_mask:0xf
	v_add_f32_dpp v142, v142, v142 quad_perm:[1,0,3,2] row_mask:0xf bank_mask:0xf
	v_pk_mul_f32 v[134:135], v[84:85], v[104:105] op_sel_hi:[1,0]
	ds_read_b128 v[78:81], v112 offset:14592
	ds_read_b128 v[82:85], v112 offset:14608
	ds_read_b32 v104, v108 offset:21632
	v_pk_fma_f32 v[128:129], v[22:23], v[38:39], v[128:129]
	v_add_f32_dpp v140, v140, v140 quad_perm:[2,3,0,1] row_mask:0xf bank_mask:0xf
	v_add_f32_dpp v142, v142, v142 quad_perm:[2,3,0,1] row_mask:0xf bank_mask:0xf
	v_pk_fma_f32 v[130:131], v[24:25], v[40:41], v[130:131]
	v_pk_fma_f32 v[132:133], v[26:27], v[42:43], v[132:133]
	v_pk_fma_f32 v[134:135], v[28:29], v[44:45], v[134:135]
	ds_read_b128 v[38:41], v112 offset:6400
	ds_read_b128 v[42:45], v112 offset:6416
	s_waitcnt lgkmcnt(10)
	v_pk_fma_f32 v[22:23], v[140:141], v[70:71], v[128:129] op_sel_hi:[0,1,1] neg_lo:[1,0,0] neg_hi:[1,0,0]
	v_pk_fma_f32 v[24:25], v[140:141], v[72:73], v[130:131] op_sel_hi:[0,1,1] neg_lo:[1,0,0] neg_hi:[1,0,0]
	v_pk_fma_f32 v[26:27], v[140:141], v[74:75], v[132:133] op_sel_hi:[0,1,1] neg_lo:[1,0,0] neg_hi:[1,0,0]
	v_pk_fma_f32 v[28:29], v[140:141], v[76:77], v[134:135] op_sel_hi:[0,1,1] neg_lo:[1,0,0] neg_hi:[1,0,0]
	ds_read_b128 v[70:73], v112 offset:10496
	ds_read_b128 v[74:77], v112 offset:10512
	ds_write_b32 v108, v142 offset:23424
	s_waitcnt lgkmcnt(3)
	v_pk_mul_f32 v[136:137], v[22:23], v[30:31]
	v_pk_mul_f32 v[138:139], v[22:23], v[96:97]
	v_pk_fma_f32 v[136:137], v[24:25], v[32:33], v[136:137]
	v_pk_fma_f32 v[138:139], v[24:25], v[98:99], v[138:139]
	v_pk_fma_f32 v[136:137], v[26:27], v[34:35], v[136:137]
	v_pk_fma_f32 v[138:139], v[26:27], v[100:101], v[138:139]
	v_pk_fma_f32 v[136:137], v[28:29], v[36:37], v[136:137]
	v_pk_fma_f32 v[138:139], v[28:29], v[102:103], v[138:139]
	ds_read_b128 v[30:33], v112 offset:2560
	ds_read_b128 v[34:37], v112 offset:2576
	ds_read_b128 v[96:99], v112 offset:18688
	ds_read_b128 v[100:103], v112 offset:18704
	v_add_f32_e32 v140, v136, v137
	v_add_f32_e32 v142, v138, v139
	v_pk_mul_f32 v[128:129], v[78:79], v[104:105] op_sel_hi:[1,0]
	v_add_f32_dpp v140, v140, v140 row_half_mirror row_mask:0xf bank_mask:0xf
	v_add_f32_dpp v142, v142, v142 row_half_mirror row_mask:0xf bank_mask:0xf
	v_pk_mul_f32 v[130:131], v[80:81], v[104:105] op_sel_hi:[1,0]
	v_pk_mul_f32 v[132:133], v[82:83], v[104:105] op_sel_hi:[1,0]
	v_add_f32_dpp v140, v140, v140 quad_perm:[1,0,3,2] row_mask:0xf bank_mask:0xf
	v_add_f32_dpp v142, v142, v142 quad_perm:[1,0,3,2] row_mask:0xf bank_mask:0xf
	v_pk_mul_f32 v[134:135], v[84:85], v[104:105] op_sel_hi:[1,0]
	ds_read_b128 v[78:81], v112 offset:14848
	ds_read_b128 v[82:85], v112 offset:14864
	ds_read_b32 v104, v108 offset:21760
	v_pk_fma_f32 v[128:129], v[22:23], v[38:39], v[128:129]
	v_add_f32_dpp v140, v140, v140 quad_perm:[2,3,0,1] row_mask:0xf bank_mask:0xf
	v_add_f32_dpp v142, v142, v142 quad_perm:[2,3,0,1] row_mask:0xf bank_mask:0xf
	v_pk_fma_f32 v[130:131], v[24:25], v[40:41], v[130:131]
	v_pk_fma_f32 v[132:133], v[26:27], v[42:43], v[132:133]
	v_pk_fma_f32 v[134:135], v[28:29], v[44:45], v[134:135]
	ds_read_b128 v[38:41], v112 offset:6656
	ds_read_b128 v[42:45], v112 offset:6672
	s_waitcnt lgkmcnt(10)
	v_pk_fma_f32 v[22:23], v[140:141], v[70:71], v[128:129] op_sel_hi:[0,1,1] neg_lo:[1,0,0] neg_hi:[1,0,0]
	v_pk_fma_f32 v[24:25], v[140:141], v[72:73], v[130:131] op_sel_hi:[0,1,1] neg_lo:[1,0,0] neg_hi:[1,0,0]
	v_pk_fma_f32 v[26:27], v[140:141], v[74:75], v[132:133] op_sel_hi:[0,1,1] neg_lo:[1,0,0] neg_hi:[1,0,0]
	v_pk_fma_f32 v[28:29], v[140:141], v[76:77], v[134:135] op_sel_hi:[0,1,1] neg_lo:[1,0,0] neg_hi:[1,0,0]
	ds_read_b128 v[70:73], v112 offset:10752
	ds_read_b128 v[74:77], v112 offset:10768
	ds_write_b32 v108, v142 offset:23552
	s_waitcnt lgkmcnt(3)
	v_pk_mul_f32 v[136:137], v[22:23], v[30:31]
	v_pk_mul_f32 v[138:139], v[22:23], v[96:97]
	v_pk_fma_f32 v[136:137], v[24:25], v[32:33], v[136:137]
	v_pk_fma_f32 v[138:139], v[24:25], v[98:99], v[138:139]
	v_pk_fma_f32 v[136:137], v[26:27], v[34:35], v[136:137]
	v_pk_fma_f32 v[138:139], v[26:27], v[100:101], v[138:139]
	v_pk_fma_f32 v[136:137], v[28:29], v[36:37], v[136:137]
	v_pk_fma_f32 v[138:139], v[28:29], v[102:103], v[138:139]
	ds_read_b128 v[30:33], v112 offset:2816
	ds_read_b128 v[34:37], v112 offset:2832
	ds_read_b128 v[96:99], v112 offset:18944
	ds_read_b128 v[100:103], v112 offset:18960
	v_add_f32_e32 v140, v136, v137
	v_add_f32_e32 v142, v138, v139
	v_pk_mul_f32 v[128:129], v[78:79], v[104:105] op_sel_hi:[1,0]
	v_add_f32_dpp v140, v140, v140 row_half_mirror row_mask:0xf bank_mask:0xf
	v_add_f32_dpp v142, v142, v142 row_half_mirror row_mask:0xf bank_mask:0xf
	v_pk_mul_f32 v[130:131], v[80:81], v[104:105] op_sel_hi:[1,0]
	v_pk_mul_f32 v[132:133], v[82:83], v[104:105] op_sel_hi:[1,0]
	v_add_f32_dpp v140, v140, v140 quad_perm:[1,0,3,2] row_mask:0xf bank_mask:0xf
	v_add_f32_dpp v142, v142, v142 quad_perm:[1,0,3,2] row_mask:0xf bank_mask:0xf
	v_pk_mul_f32 v[134:135], v[84:85], v[104:105] op_sel_hi:[1,0]
	ds_read_b128 v[78:81], v112 offset:15104
	ds_read_b128 v[82:85], v112 offset:15120
	ds_read_b32 v104, v108 offset:21888
	v_pk_fma_f32 v[128:129], v[22:23], v[38:39], v[128:129]
	v_add_f32_dpp v140, v140, v140 quad_perm:[2,3,0,1] row_mask:0xf bank_mask:0xf
	v_add_f32_dpp v142, v142, v142 quad_perm:[2,3,0,1] row_mask:0xf bank_mask:0xf
	v_pk_fma_f32 v[130:131], v[24:25], v[40:41], v[130:131]
	v_pk_fma_f32 v[132:133], v[26:27], v[42:43], v[132:133]
	v_pk_fma_f32 v[134:135], v[28:29], v[44:45], v[134:135]
	ds_read_b128 v[38:41], v112 offset:6912
	ds_read_b128 v[42:45], v112 offset:6928
	s_waitcnt lgkmcnt(10)
	v_pk_fma_f32 v[22:23], v[140:141], v[70:71], v[128:129] op_sel_hi:[0,1,1] neg_lo:[1,0,0] neg_hi:[1,0,0]
	v_pk_fma_f32 v[24:25], v[140:141], v[72:73], v[130:131] op_sel_hi:[0,1,1] neg_lo:[1,0,0] neg_hi:[1,0,0]
	v_pk_fma_f32 v[26:27], v[140:141], v[74:75], v[132:133] op_sel_hi:[0,1,1] neg_lo:[1,0,0] neg_hi:[1,0,0]
	v_pk_fma_f32 v[28:29], v[140:141], v[76:77], v[134:135] op_sel_hi:[0,1,1] neg_lo:[1,0,0] neg_hi:[1,0,0]
	ds_read_b128 v[70:73], v112 offset:11008
	ds_read_b128 v[74:77], v112 offset:11024
	ds_write_b32 v108, v142 offset:23680
	s_waitcnt lgkmcnt(3)
	v_pk_mul_f32 v[136:137], v[22:23], v[30:31]
	v_pk_mul_f32 v[138:139], v[22:23], v[96:97]
	v_pk_fma_f32 v[136:137], v[24:25], v[32:33], v[136:137]
	v_pk_fma_f32 v[138:139], v[24:25], v[98:99], v[138:139]
	v_pk_fma_f32 v[136:137], v[26:27], v[34:35], v[136:137]
	v_pk_fma_f32 v[138:139], v[26:27], v[100:101], v[138:139]
	v_pk_fma_f32 v[136:137], v[28:29], v[36:37], v[136:137]
	v_pk_fma_f32 v[138:139], v[28:29], v[102:103], v[138:139]
	ds_read_b128 v[30:33], v112 offset:3072
	ds_read_b128 v[34:37], v112 offset:3088
	ds_read_b128 v[96:99], v112 offset:19200
	ds_read_b128 v[100:103], v112 offset:19216
	v_add_f32_e32 v140, v136, v137
	v_add_f32_e32 v142, v138, v139
	v_pk_mul_f32 v[128:129], v[78:79], v[104:105] op_sel_hi:[1,0]
	v_add_f32_dpp v140, v140, v140 row_half_mirror row_mask:0xf bank_mask:0xf
	v_add_f32_dpp v142, v142, v142 row_half_mirror row_mask:0xf bank_mask:0xf
	v_pk_mul_f32 v[130:131], v[80:81], v[104:105] op_sel_hi:[1,0]
	v_pk_mul_f32 v[132:133], v[82:83], v[104:105] op_sel_hi:[1,0]
	v_add_f32_dpp v140, v140, v140 quad_perm:[1,0,3,2] row_mask:0xf bank_mask:0xf
	v_add_f32_dpp v142, v142, v142 quad_perm:[1,0,3,2] row_mask:0xf bank_mask:0xf
	v_pk_mul_f32 v[134:135], v[84:85], v[104:105] op_sel_hi:[1,0]
	ds_read_b128 v[78:81], v112 offset:15360
	ds_read_b128 v[82:85], v112 offset:15376
	ds_read_b32 v104, v108 offset:22016
	v_pk_fma_f32 v[128:129], v[22:23], v[38:39], v[128:129]
	v_add_f32_dpp v140, v140, v140 quad_perm:[2,3,0,1] row_mask:0xf bank_mask:0xf
	v_add_f32_dpp v142, v142, v142 quad_perm:[2,3,0,1] row_mask:0xf bank_mask:0xf
	v_pk_fma_f32 v[130:131], v[24:25], v[40:41], v[130:131]
	v_pk_fma_f32 v[132:133], v[26:27], v[42:43], v[132:133]
	v_pk_fma_f32 v[134:135], v[28:29], v[44:45], v[134:135]
	ds_read_b128 v[38:41], v112 offset:7168
	ds_read_b128 v[42:45], v112 offset:7184
	s_waitcnt lgkmcnt(10)
	v_pk_fma_f32 v[22:23], v[140:141], v[70:71], v[128:129] op_sel_hi:[0,1,1] neg_lo:[1,0,0] neg_hi:[1,0,0]
	v_pk_fma_f32 v[24:25], v[140:141], v[72:73], v[130:131] op_sel_hi:[0,1,1] neg_lo:[1,0,0] neg_hi:[1,0,0]
	v_pk_fma_f32 v[26:27], v[140:141], v[74:75], v[132:133] op_sel_hi:[0,1,1] neg_lo:[1,0,0] neg_hi:[1,0,0]
	v_pk_fma_f32 v[28:29], v[140:141], v[76:77], v[134:135] op_sel_hi:[0,1,1] neg_lo:[1,0,0] neg_hi:[1,0,0]
	ds_read_b128 v[70:73], v112 offset:11264
	ds_read_b128 v[74:77], v112 offset:11280
	ds_write_b32 v108, v142 offset:23808
	s_waitcnt lgkmcnt(3)
	v_pk_mul_f32 v[136:137], v[22:23], v[30:31]
	v_pk_mul_f32 v[138:139], v[22:23], v[96:97]
	v_pk_fma_f32 v[136:137], v[24:25], v[32:33], v[136:137]
	v_pk_fma_f32 v[138:139], v[24:25], v[98:99], v[138:139]
	v_pk_fma_f32 v[136:137], v[26:27], v[34:35], v[136:137]
	v_pk_fma_f32 v[138:139], v[26:27], v[100:101], v[138:139]
	v_pk_fma_f32 v[136:137], v[28:29], v[36:37], v[136:137]
	v_pk_fma_f32 v[138:139], v[28:29], v[102:103], v[138:139]
	ds_read_b128 v[30:33], v112 offset:3328
	ds_read_b128 v[34:37], v112 offset:3344
	ds_read_b128 v[96:99], v112 offset:19456
	ds_read_b128 v[100:103], v112 offset:19472
	v_add_f32_e32 v140, v136, v137
	v_add_f32_e32 v142, v138, v139
	v_pk_mul_f32 v[128:129], v[78:79], v[104:105] op_sel_hi:[1,0]
	v_add_f32_dpp v140, v140, v140 row_half_mirror row_mask:0xf bank_mask:0xf
	v_add_f32_dpp v142, v142, v142 row_half_mirror row_mask:0xf bank_mask:0xf
	v_pk_mul_f32 v[130:131], v[80:81], v[104:105] op_sel_hi:[1,0]
	v_pk_mul_f32 v[132:133], v[82:83], v[104:105] op_sel_hi:[1,0]
	v_add_f32_dpp v140, v140, v140 quad_perm:[1,0,3,2] row_mask:0xf bank_mask:0xf
	v_add_f32_dpp v142, v142, v142 quad_perm:[1,0,3,2] row_mask:0xf bank_mask:0xf
	v_pk_mul_f32 v[134:135], v[84:85], v[104:105] op_sel_hi:[1,0]
	ds_read_b128 v[78:81], v112 offset:15616
	ds_read_b128 v[82:85], v112 offset:15632
	ds_read_b32 v104, v108 offset:22144
	v_pk_fma_f32 v[128:129], v[22:23], v[38:39], v[128:129]
	v_add_f32_dpp v140, v140, v140 quad_perm:[2,3,0,1] row_mask:0xf bank_mask:0xf
	v_add_f32_dpp v142, v142, v142 quad_perm:[2,3,0,1] row_mask:0xf bank_mask:0xf
	v_pk_fma_f32 v[130:131], v[24:25], v[40:41], v[130:131]
	v_pk_fma_f32 v[132:133], v[26:27], v[42:43], v[132:133]
	v_pk_fma_f32 v[134:135], v[28:29], v[44:45], v[134:135]
	ds_read_b128 v[38:41], v112 offset:7424
	ds_read_b128 v[42:45], v112 offset:7440
	s_waitcnt lgkmcnt(10)
	v_pk_fma_f32 v[22:23], v[140:141], v[70:71], v[128:129] op_sel_hi:[0,1,1] neg_lo:[1,0,0] neg_hi:[1,0,0]
	v_pk_fma_f32 v[24:25], v[140:141], v[72:73], v[130:131] op_sel_hi:[0,1,1] neg_lo:[1,0,0] neg_hi:[1,0,0]
	v_pk_fma_f32 v[26:27], v[140:141], v[74:75], v[132:133] op_sel_hi:[0,1,1] neg_lo:[1,0,0] neg_hi:[1,0,0]
	v_pk_fma_f32 v[28:29], v[140:141], v[76:77], v[134:135] op_sel_hi:[0,1,1] neg_lo:[1,0,0] neg_hi:[1,0,0]
	ds_read_b128 v[70:73], v112 offset:11520
	ds_read_b128 v[74:77], v112 offset:11536
	ds_write_b32 v108, v142 offset:23936
	s_waitcnt lgkmcnt(3)
	v_pk_mul_f32 v[136:137], v[22:23], v[30:31]
	v_pk_mul_f32 v[138:139], v[22:23], v[96:97]
	v_pk_fma_f32 v[136:137], v[24:25], v[32:33], v[136:137]
	v_pk_fma_f32 v[138:139], v[24:25], v[98:99], v[138:139]
	v_pk_fma_f32 v[136:137], v[26:27], v[34:35], v[136:137]
	v_pk_fma_f32 v[138:139], v[26:27], v[100:101], v[138:139]
	v_pk_fma_f32 v[136:137], v[28:29], v[36:37], v[136:137]
	v_pk_fma_f32 v[138:139], v[28:29], v[102:103], v[138:139]
	ds_read_b128 v[30:33], v112 offset:3584
	ds_read_b128 v[34:37], v112 offset:3600
	ds_read_b128 v[96:99], v112 offset:19712
	ds_read_b128 v[100:103], v112 offset:19728
	v_add_f32_e32 v140, v136, v137
	v_add_f32_e32 v142, v138, v139
	v_pk_mul_f32 v[128:129], v[78:79], v[104:105] op_sel_hi:[1,0]
	v_add_f32_dpp v140, v140, v140 row_half_mirror row_mask:0xf bank_mask:0xf
	v_add_f32_dpp v142, v142, v142 row_half_mirror row_mask:0xf bank_mask:0xf
	v_pk_mul_f32 v[130:131], v[80:81], v[104:105] op_sel_hi:[1,0]
	v_pk_mul_f32 v[132:133], v[82:83], v[104:105] op_sel_hi:[1,0]
	v_add_f32_dpp v140, v140, v140 quad_perm:[1,0,3,2] row_mask:0xf bank_mask:0xf
	v_add_f32_dpp v142, v142, v142 quad_perm:[1,0,3,2] row_mask:0xf bank_mask:0xf
	v_pk_mul_f32 v[134:135], v[84:85], v[104:105] op_sel_hi:[1,0]
	ds_read_b128 v[78:81], v112 offset:15872
	ds_read_b128 v[82:85], v112 offset:15888
	ds_read_b32 v104, v108 offset:22272
	v_pk_fma_f32 v[128:129], v[22:23], v[38:39], v[128:129]
	v_add_f32_dpp v140, v140, v140 quad_perm:[2,3,0,1] row_mask:0xf bank_mask:0xf
	v_add_f32_dpp v142, v142, v142 quad_perm:[2,3,0,1] row_mask:0xf bank_mask:0xf
	v_pk_fma_f32 v[130:131], v[24:25], v[40:41], v[130:131]
	v_pk_fma_f32 v[132:133], v[26:27], v[42:43], v[132:133]
	v_pk_fma_f32 v[134:135], v[28:29], v[44:45], v[134:135]
	ds_read_b128 v[38:41], v112 offset:7680
	ds_read_b128 v[42:45], v112 offset:7696
	s_waitcnt lgkmcnt(10)
	v_pk_fma_f32 v[22:23], v[140:141], v[70:71], v[128:129] op_sel_hi:[0,1,1] neg_lo:[1,0,0] neg_hi:[1,0,0]
	v_pk_fma_f32 v[24:25], v[140:141], v[72:73], v[130:131] op_sel_hi:[0,1,1] neg_lo:[1,0,0] neg_hi:[1,0,0]
	v_pk_fma_f32 v[26:27], v[140:141], v[74:75], v[132:133] op_sel_hi:[0,1,1] neg_lo:[1,0,0] neg_hi:[1,0,0]
	v_pk_fma_f32 v[28:29], v[140:141], v[76:77], v[134:135] op_sel_hi:[0,1,1] neg_lo:[1,0,0] neg_hi:[1,0,0]
	ds_read_b128 v[70:73], v112 offset:11776
	ds_read_b128 v[74:77], v112 offset:11792
	ds_write_b32 v108, v142 offset:24064
	s_waitcnt lgkmcnt(3)
	v_pk_mul_f32 v[136:137], v[22:23], v[30:31]
	v_pk_mul_f32 v[138:139], v[22:23], v[96:97]
	v_pk_fma_f32 v[136:137], v[24:25], v[32:33], v[136:137]
	v_pk_fma_f32 v[138:139], v[24:25], v[98:99], v[138:139]
	v_pk_fma_f32 v[136:137], v[26:27], v[34:35], v[136:137]
	v_pk_fma_f32 v[138:139], v[26:27], v[100:101], v[138:139]
	v_pk_fma_f32 v[136:137], v[28:29], v[36:37], v[136:137]
	v_pk_fma_f32 v[138:139], v[28:29], v[102:103], v[138:139]
	ds_read_b128 v[30:33], v112 offset:3840
	ds_read_b128 v[34:37], v112 offset:3856
	ds_read_b128 v[96:99], v112 offset:19968
	ds_read_b128 v[100:103], v112 offset:19984
	v_add_f32_e32 v140, v136, v137
	v_add_f32_e32 v142, v138, v139
	v_pk_mul_f32 v[128:129], v[78:79], v[104:105] op_sel_hi:[1,0]
	v_add_f32_dpp v140, v140, v140 row_half_mirror row_mask:0xf bank_mask:0xf
	v_add_f32_dpp v142, v142, v142 row_half_mirror row_mask:0xf bank_mask:0xf
	v_pk_mul_f32 v[130:131], v[80:81], v[104:105] op_sel_hi:[1,0]
	v_pk_mul_f32 v[132:133], v[82:83], v[104:105] op_sel_hi:[1,0]
	v_add_f32_dpp v140, v140, v140 quad_perm:[1,0,3,2] row_mask:0xf bank_mask:0xf
	v_add_f32_dpp v142, v142, v142 quad_perm:[1,0,3,2] row_mask:0xf bank_mask:0xf
	v_pk_mul_f32 v[134:135], v[84:85], v[104:105] op_sel_hi:[1,0]
	ds_read_b128 v[78:81], v112 offset:16128
	ds_read_b128 v[82:85], v112 offset:16144
	ds_read_b32 v104, v108 offset:22400
	v_pk_fma_f32 v[128:129], v[22:23], v[38:39], v[128:129]
	v_add_f32_dpp v140, v140, v140 quad_perm:[2,3,0,1] row_mask:0xf bank_mask:0xf
	v_add_f32_dpp v142, v142, v142 quad_perm:[2,3,0,1] row_mask:0xf bank_mask:0xf
	v_pk_fma_f32 v[130:131], v[24:25], v[40:41], v[130:131]
	v_pk_fma_f32 v[132:133], v[26:27], v[42:43], v[132:133]
	v_pk_fma_f32 v[134:135], v[28:29], v[44:45], v[134:135]
	ds_read_b128 v[38:41], v112 offset:7936
	ds_read_b128 v[42:45], v112 offset:7952
	s_waitcnt lgkmcnt(10)
	v_pk_fma_f32 v[22:23], v[140:141], v[70:71], v[128:129] op_sel_hi:[0,1,1] neg_lo:[1,0,0] neg_hi:[1,0,0]
	v_pk_fma_f32 v[24:25], v[140:141], v[72:73], v[130:131] op_sel_hi:[0,1,1] neg_lo:[1,0,0] neg_hi:[1,0,0]
	v_pk_fma_f32 v[26:27], v[140:141], v[74:75], v[132:133] op_sel_hi:[0,1,1] neg_lo:[1,0,0] neg_hi:[1,0,0]
	v_pk_fma_f32 v[28:29], v[140:141], v[76:77], v[134:135] op_sel_hi:[0,1,1] neg_lo:[1,0,0] neg_hi:[1,0,0]
	ds_read_b128 v[70:73], v112 offset:12032
	ds_read_b128 v[74:77], v112 offset:12048
	ds_write_b32 v108, v142 offset:24192
	s_waitcnt lgkmcnt(3)
	v_pk_mul_f32 v[136:137], v[22:23], v[30:31]
	v_pk_mul_f32 v[138:139], v[22:23], v[96:97]
	v_pk_fma_f32 v[136:137], v[24:25], v[32:33], v[136:137]
	v_pk_fma_f32 v[138:139], v[24:25], v[98:99], v[138:139]
	v_pk_fma_f32 v[136:137], v[26:27], v[34:35], v[136:137]
	v_pk_fma_f32 v[138:139], v[26:27], v[100:101], v[138:139]
	v_pk_fma_f32 v[136:137], v[28:29], v[36:37], v[136:137]
	v_pk_fma_f32 v[138:139], v[28:29], v[102:103], v[138:139]
	ds_read_b128 v[96:99], v112 offset:20224
	ds_read_b128 v[100:103], v112 offset:20240
	v_add_f32_e32 v140, v136, v137
	v_add_f32_e32 v142, v138, v139
	v_pk_mul_f32 v[128:129], v[78:79], v[104:105] op_sel_hi:[1,0]
	v_add_f32_dpp v140, v140, v140 row_half_mirror row_mask:0xf bank_mask:0xf
	v_add_f32_dpp v142, v142, v142 row_half_mirror row_mask:0xf bank_mask:0xf
	v_pk_mul_f32 v[130:131], v[80:81], v[104:105] op_sel_hi:[1,0]
	v_pk_mul_f32 v[132:133], v[82:83], v[104:105] op_sel_hi:[1,0]
	v_add_f32_dpp v140, v140, v140 quad_perm:[1,0,3,2] row_mask:0xf bank_mask:0xf
	v_add_f32_dpp v142, v142, v142 quad_perm:[1,0,3,2] row_mask:0xf bank_mask:0xf
	v_pk_mul_f32 v[134:135], v[84:85], v[104:105] op_sel_hi:[1,0]
	v_pk_fma_f32 v[128:129], v[22:23], v[38:39], v[128:129]
	v_add_f32_dpp v140, v140, v140 quad_perm:[2,3,0,1] row_mask:0xf bank_mask:0xf
	v_add_f32_dpp v142, v142, v142 quad_perm:[2,3,0,1] row_mask:0xf bank_mask:0xf
	v_pk_fma_f32 v[130:131], v[24:25], v[40:41], v[130:131]
	v_pk_fma_f32 v[132:133], v[26:27], v[42:43], v[132:133]
	v_pk_fma_f32 v[134:135], v[28:29], v[44:45], v[134:135]
	s_waitcnt lgkmcnt(3)
	v_pk_fma_f32 v[22:23], v[140:141], v[70:71], v[128:129] op_sel_hi:[0,1,1] neg_lo:[1,0,0] neg_hi:[1,0,0]
	v_pk_fma_f32 v[24:25], v[140:141], v[72:73], v[130:131] op_sel_hi:[0,1,1] neg_lo:[1,0,0] neg_hi:[1,0,0]
	v_pk_fma_f32 v[26:27], v[140:141], v[74:75], v[132:133] op_sel_hi:[0,1,1] neg_lo:[1,0,0] neg_hi:[1,0,0]
	v_pk_fma_f32 v[28:29], v[140:141], v[76:77], v[134:135] op_sel_hi:[0,1,1] neg_lo:[1,0,0] neg_hi:[1,0,0]
	ds_write_b32 v108, v142 offset:24320
	s_waitcnt lgkmcnt(1)
	v_pk_mul_f32 v[138:139], v[22:23], v[96:97]
	v_pk_fma_f32 v[138:139], v[24:25], v[98:99], v[138:139]
	v_pk_fma_f32 v[138:139], v[26:27], v[100:101], v[138:139]
	v_pk_fma_f32 v[138:139], v[28:29], v[102:103], v[138:139]
	v_add_f32_e32 v142, v138, v139
	s_nop 1
	v_add_f32_dpp v142, v142, v142 row_half_mirror row_mask:0xf bank_mask:0xf
	s_nop 1
	v_add_f32_dpp v142, v142, v142 quad_perm:[1,0,3,2] row_mask:0xf bank_mask:0xf
	s_nop 1
	v_add_f32_dpp v142, v142, v142 quad_perm:[2,3,0,1] row_mask:0xf bank_mask:0xf
	ds_write_b32 v108, v142 offset:24448
	s_branch .Lrw0_u2e0
.Lrw0_u2s0:
	ds_read_b128 v[30:33], v112 offset:0
	ds_read_b128 v[34:37], v112 offset:16
	ds_read_b128 v[38:41], v112 offset:4096
	ds_read_b128 v[42:45], v112 offset:4112
	ds_read_b128 v[70:73], v112 offset:8192
	ds_read_b128 v[74:77], v112 offset:8208
	s_waitcnt lgkmcnt(2)
	v_pk_mul_f32 v[136:137], v[22:23], v[30:31]
	v_pk_fma_f32 v[136:137], v[24:25], v[32:33], v[136:137]
	v_pk_fma_f32 v[136:137], v[26:27], v[34:35], v[136:137]
	v_pk_fma_f32 v[136:137], v[28:29], v[36:37], v[136:137]
	ds_read_b128 v[30:33], v112 offset:256
	ds_read_b128 v[34:37], v112 offset:272
	ds_read_b128 v[96:99], v112 offset:16384
	ds_read_b128 v[100:103], v112 offset:16400
	v_add_f32_e32 v140, v136, v137
	v_pk_mul_f32 v[128:129], v[22:23], v[38:39]
	s_nop 0
	v_add_f32_dpp v140, v140, v140 row_half_mirror row_mask:0xf bank_mask:0xf
	v_pk_mul_f32 v[130:131], v[24:25], v[40:41]
	v_pk_mul_f32 v[132:133], v[26:27], v[42:43]
	v_pk_mul_f32 v[134:135], v[28:29], v[44:45]
	ds_read_b128 v[38:41], v112 offset:4352
	ds_read_b128 v[42:45], v112 offset:4368
	v_add_f32_dpp v140, v140, v140 quad_perm:[1,0,3,2] row_mask:0xf bank_mask:0xf
	s_nop 1
	v_add_f32_dpp v140, v140, v140 quad_perm:[2,3,0,1] row_mask:0xf bank_mask:0xf
	s_waitcnt lgkmcnt(6)
	v_pk_fma_f32 v[22:23], v[140:141], v[70:71], v[128:129] op_sel_hi:[0,1,1] neg_lo:[1,0,0] neg_hi:[1,0,0]
	v_pk_fma_f32 v[24:25], v[140:141], v[72:73], v[130:131] op_sel_hi:[0,1,1] neg_lo:[1,0,0] neg_hi:[1,0,0]
	v_pk_fma_f32 v[26:27], v[140:141], v[74:75], v[132:133] op_sel_hi:[0,1,1] neg_lo:[1,0,0] neg_hi:[1,0,0]
	v_pk_fma_f32 v[28:29], v[140:141], v[76:77], v[134:135] op_sel_hi:[0,1,1] neg_lo:[1,0,0] neg_hi:[1,0,0]
	ds_read_b128 v[70:73], v112 offset:8448
	ds_read_b128 v[74:77], v112 offset:8464
	s_waitcnt lgkmcnt(2)
	v_pk_mul_f32 v[136:137], v[22:23], v[30:31]
	v_pk_mul_f32 v[138:139], v[22:23], v[96:97]
	v_pk_fma_f32 v[136:137], v[24:25], v[32:33], v[136:137]
	v_pk_fma_f32 v[138:139], v[24:25], v[98:99], v[138:139]
	v_pk_fma_f32 v[136:137], v[26:27], v[34:35], v[136:137]
	v_pk_fma_f32 v[138:139], v[26:27], v[100:101], v[138:139]
	v_pk_fma_f32 v[136:137], v[28:29], v[36:37], v[136:137]
	v_pk_fma_f32 v[138:139], v[28:29], v[102:103], v[138:139]
	ds_read_b128 v[30:33], v112 offset:512
	ds_read_b128 v[34:37], v112 offset:528
	ds_read_b128 v[96:99], v112 offset:16640
	ds_read_b128 v[100:103], v112 offset:16656
	v_add_f32_e32 v140, v136, v137
	v_add_f32_e32 v142, v138, v139
	v_pk_mul_f32 v[128:129], v[22:23], v[38:39]
	v_add_f32_dpp v140, v140, v140 row_half_mirror row_mask:0xf bank_mask:0xf
	v_add_f32_dpp v142, v142, v142 row_half_mirror row_mask:0xf bank_mask:0xf
	v_pk_mul_f32 v[130:131], v[24:25], v[40:41]
	v_pk_mul_f32 v[132:133], v[26:27], v[42:43]
	v_add_f32_dpp v140, v140, v140 quad_perm:[1,0,3,2] row_mask:0xf bank_mask:0xf
	v_add_f32_dpp v142, v142, v142 quad_perm:[1,0,3,2] row_mask:0xf bank_mask:0xf
	v_pk_mul_f32 v[134:135], v[28:29], v[44:45]
	ds_read_b128 v[38:41], v112 offset:4608
	ds_read_b128 v[42:45], v112 offset:4624
	v_add_f32_dpp v140, v140, v140 quad_perm:[2,3,0,1] row_mask:0xf bank_mask:0xf
	v_add_f32_dpp v142, v142, v142 quad_perm:[2,3,0,1] row_mask:0xf bank_mask:0xf
	s_waitcnt lgkmcnt(6)
	v_pk_fma_f32 v[22:23], v[140:141], v[70:71], v[128:129] op_sel_hi:[0,1,1] neg_lo:[1,0,0] neg_hi:[1,0,0]
	v_pk_fma_f32 v[24:25], v[140:141], v[72:73], v[130:131] op_sel_hi:[0,1,1] neg_lo:[1,0,0] neg_hi:[1,0,0]
	v_pk_fma_f32 v[26:27], v[140:141], v[74:75], v[132:133] op_sel_hi:[0,1,1] neg_lo:[1,0,0] neg_hi:[1,0,0]
	v_pk_fma_f32 v[28:29], v[140:141], v[76:77], v[134:135] op_sel_hi:[0,1,1] neg_lo:[1,0,0] neg_hi:[1,0,0]
	ds_read_b128 v[70:73], v112 offset:8704
	ds_read_b128 v[74:77], v112 offset:8720
	ds_write_b32 v108, v142 offset:22528
	s_waitcnt lgkmcnt(3)
	v_pk_mul_f32 v[136:137], v[22:23], v[30:31]
	v_pk_mul_f32 v[138:139], v[22:23], v[96:97]
	v_pk_fma_f32 v[136:137], v[24:25], v[32:33], v[136:137]
	v_pk_fma_f32 v[138:139], v[24:25], v[98:99], v[138:139]
	v_pk_fma_f32 v[136:137], v[26:27], v[34:35], v[136:137]
	v_pk_fma_f32 v[138:139], v[26:27], v[100:101], v[138:139]
	v_pk_fma_f32 v[136:137], v[28:29], v[36:37], v[136:137]
	v_pk_fma_f32 v[138:139], v[28:29], v[102:103], v[138:139]
	ds_read_b128 v[30:33], v112 offset:768
	ds_read_b128 v[34:37], v112 offset:784
	ds_read_b128 v[96:99], v112 offset:16896
	ds_read_b128 v[100:103], v112 offset:16912
	v_add_f32_e32 v140, v136, v137
	v_add_f32_e32 v142, v138, v139
	v_pk_mul_f32 v[128:129], v[22:23], v[38:39]
	v_add_f32_dpp v140, v140, v140 row_half_mirror row_mask:0xf bank_mask:0xf
	v_add_f32_dpp v142, v142, v142 row_half_mirror row_mask:0xf bank_mask:0xf
	v_pk_mul_f32 v[130:131], v[24:25], v[40:41]
	v_pk_mul_f32 v[132:133], v[26:27], v[42:43]
	v_add_f32_dpp v140, v140, v140 quad_perm:[1,0,3,2] row_mask:0xf bank_mask:0xf
	v_add_f32_dpp v142, v142, v142 quad_perm:[1,0,3,2] row_mask:0xf bank_mask:0xf
	v_pk_mul_f32 v[134:135], v[28:29], v[44:45]
	ds_read_b128 v[38:41], v112 offset:4864
	ds_read_b128 v[42:45], v112 offset:4880
	v_add_f32_dpp v140, v140, v140 quad_perm:[2,3,0,1] row_mask:0xf bank_mask:0xf
	v_add_f32_dpp v142, v142, v142 quad_perm:[2,3,0,1] row_mask:0xf bank_mask:0xf
	s_waitcnt lgkmcnt(7)
	v_pk_fma_f32 v[22:23], v[140:141], v[70:71], v[128:129] op_sel_hi:[0,1,1] neg_lo:[1,0,0] neg_hi:[1,0,0]
	v_pk_fma_f32 v[24:25], v[140:141], v[72:73], v[130:131] op_sel_hi:[0,1,1] neg_lo:[1,0,0] neg_hi:[1,0,0]
	v_pk_fma_f32 v[26:27], v[140:141], v[74:75], v[132:133] op_sel_hi:[0,1,1] neg_lo:[1,0,0] neg_hi:[1,0,0]
	v_pk_fma_f32 v[28:29], v[140:141], v[76:77], v[134:135] op_sel_hi:[0,1,1] neg_lo:[1,0,0] neg_hi:[1,0,0]
	ds_read_b128 v[70:73], v112 offset:8960
	ds_read_b128 v[74:77], v112 offset:8976
	ds_write_b32 v108, v142 offset:22656
	s_waitcnt lgkmcnt(3)
	v_pk_mul_f32 v[136:137], v[22:23], v[30:31]
	v_pk_mul_f32 v[138:139], v[22:23], v[96:97]
	v_pk_fma_f32 v[136:137], v[24:25], v[32:33], v[136:137]
	v_pk_fma_f32 v[138:139], v[24:25], v[98:99], v[138:139]
	v_pk_fma_f32 v[136:137], v[26:27], v[34:35], v[136:137]
	v_pk_fma_f32 v[138:139], v[26:27], v[100:101], v[138:139]
	v_pk_fma_f32 v[136:137], v[28:29], v[36:37], v[136:137]
	v_pk_fma_f32 v[138:139], v[28:29], v[102:103], v[138:139]
	ds_read_b128 v[30:33], v112 offset:1024
	ds_read_b128 v[34:37], v112 offset:1040
	ds_read_b128 v[96:99], v112 offset:17152
	ds_read_b128 v[100:103], v112 offset:17168
	v_add_f32_e32 v140, v136, v137
	v_add_f32_e32 v142, v138, v139
	v_pk_mul_f32 v[128:129], v[22:23], v[38:39]
	v_add_f32_dpp v140, v140, v140 row_half_mirror row_mask:0xf bank_mask:0xf
	v_add_f32_dpp v142, v142, v142 row_half_mirror row_mask:0xf bank_mask:0xf
	v_pk_mul_f32 v[130:131], v[24:25], v[40:41]
	v_pk_mul_f32 v[132:133], v[26:27], v[42:43]
	v_add_f32_dpp v140, v140, v140 quad_perm:[1,0,3,2] row_mask:0xf bank_mask:0xf
	v_add_f32_dpp v142, v142, v142 quad_perm:[1,0,3,2] row_mask:0xf bank_mask:0xf
	v_pk_mul_f32 v[134:135], v[28:29], v[44:45]
	ds_read_b128 v[38:41], v112 offset:5120
	ds_read_b128 v[42:45], v112 offset:5136
	v_add_f32_dpp v140, v140, v140 quad_perm:[2,3,0,1] row_mask:0xf bank_mask:0xf
	v_add_f32_dpp v142, v142, v142 quad_perm:[2,3,0,1] row_mask:0xf bank_mask:0xf
	s_waitcnt lgkmcnt(7)
	v_pk_fma_f32 v[22:23], v[140:141], v[70:71], v[128:129] op_sel_hi:[0,1,1] neg_lo:[1,0,0] neg_hi:[1,0,0]
	v_pk_fma_f32 v[24:25], v[140:141], v[72:73], v[130:131] op_sel_hi:[0,1,1] neg_lo:[1,0,0] neg_hi:[1,0,0]
	v_pk_fma_f32 v[26:27], v[140:141], v[74:75], v[132:133] op_sel_hi:[0,1,1] neg_lo:[1,0,0] neg_hi:[1,0,0]
	v_pk_fma_f32 v[28:29], v[140:141], v[76:77], v[134:135] op_sel_hi:[0,1,1] neg_lo:[1,0,0] neg_hi:[1,0,0]
	ds_read_b128 v[70:73], v112 offset:9216
	ds_read_b128 v[74:77], v112 offset:9232
	ds_write_b32 v108, v142 offset:22784
	s_waitcnt lgkmcnt(3)
	v_pk_mul_f32 v[136:137], v[22:23], v[30:31]
	v_pk_mul_f32 v[138:139], v[22:23], v[96:97]
	v_pk_fma_f32 v[136:137], v[24:25], v[32:33], v[136:137]
	v_pk_fma_f32 v[138:139], v[24:25], v[98:99], v[138:139]
	v_pk_fma_f32 v[136:137], v[26:27], v[34:35], v[136:137]
	v_pk_fma_f32 v[138:139], v[26:27], v[100:101], v[138:139]
	v_pk_fma_f32 v[136:137], v[28:29], v[36:37], v[136:137]
	v_pk_fma_f32 v[138:139], v[28:29], v[102:103], v[138:139]
	ds_read_b128 v[30:33], v112 offset:1280
	ds_read_b128 v[34:37], v112 offset:1296
	ds_read_b128 v[96:99], v112 offset:17408
	ds_read_b128 v[100:103], v112 offset:17424
	v_add_f32_e32 v140, v136, v137
	v_add_f32_e32 v142, v138, v139
	v_pk_mul_f32 v[128:129], v[22:23], v[38:39]
	v_add_f32_dpp v140, v140, v140 row_half_mirror row_mask:0xf bank_mask:0xf
	v_add_f32_dpp v142, v142, v142 row_half_mirror row_mask:0xf bank_mask:0xf
	v_pk_mul_f32 v[130:131], v[24:25], v[40:41]
	v_pk_mul_f32 v[132:133], v[26:27], v[42:43]
	v_add_f32_dpp v140, v140, v140 quad_perm:[1,0,3,2] row_mask:0xf bank_mask:0xf
	v_add_f32_dpp v142, v142, v142 quad_perm:[1,0,3,2] row_mask:0xf bank_mask:0xf
	v_pk_mul_f32 v[134:135], v[28:29], v[44:45]
	ds_read_b128 v[38:41], v112 offset:5376
	ds_read_b128 v[42:45], v112 offset:5392
	v_add_f32_dpp v140, v140, v140 quad_perm:[2,3,0,1] row_mask:0xf bank_mask:0xf
	v_add_f32_dpp v142, v142, v142 quad_perm:[2,3,0,1] row_mask:0xf bank_mask:0xf
	s_waitcnt lgkmcnt(7)
	v_pk_fma_f32 v[22:23], v[140:141], v[70:71], v[128:129] op_sel_hi:[0,1,1] neg_lo:[1,0,0] neg_hi:[1,0,0]
	v_pk_fma_f32 v[24:25], v[140:141], v[72:73], v[130:131] op_sel_hi:[0,1,1] neg_lo:[1,0,0] neg_hi:[1,0,0]
	v_pk_fma_f32 v[26:27], v[140:141], v[74:75], v[132:133] op_sel_hi:[0,1,1] neg_lo:[1,0,0] neg_hi:[1,0,0]
	v_pk_fma_f32 v[28:29], v[140:141], v[76:77], v[134:135] op_sel_hi:[0,1,1] neg_lo:[1,0,0] neg_hi:[1,0,0]
	ds_read_b128 v[70:73], v112 offset:9472
	ds_read_b128 v[74:77], v112 offset:9488
	ds_write_b32 v108, v142 offset:22912
	s_waitcnt lgkmcnt(3)
	v_pk_mul_f32 v[136:137], v[22:23], v[30:31]
	v_pk_mul_f32 v[138:139], v[22:23], v[96:97]
	v_pk_fma_f32 v[136:137], v[24:25], v[32:33], v[136:137]
	v_pk_fma_f32 v[138:139], v[24:25], v[98:99], v[138:139]
	v_pk_fma_f32 v[136:137], v[26:27], v[34:35], v[136:137]
	v_pk_fma_f32 v[138:139], v[26:27], v[100:101], v[138:139]
	v_pk_fma_f32 v[136:137], v[28:29], v[36:37], v[136:137]
	v_pk_fma_f32 v[138:139], v[28:29], v[102:103], v[138:139]
	ds_read_b128 v[30:33], v112 offset:1536
	ds_read_b128 v[34:37], v112 offset:1552
	ds_read_b128 v[96:99], v112 offset:17664
	ds_read_b128 v[100:103], v112 offset:17680
	v_add_f32_e32 v140, v136, v137
	v_add_f32_e32 v142, v138, v139
	v_pk_mul_f32 v[128:129], v[22:23], v[38:39]
	v_add_f32_dpp v140, v140, v140 row_half_mirror row_mask:0xf bank_mask:0xf
	v_add_f32_dpp v142, v142, v142 row_half_mirror row_mask:0xf bank_mask:0xf
	v_pk_mul_f32 v[130:131], v[24:25], v[40:41]
	v_pk_mul_f32 v[132:133], v[26:27], v[42:43]
	v_add_f32_dpp v140, v140, v140 quad_perm:[1,0,3,2] row_mask:0xf bank_mask:0xf
	v_add_f32_dpp v142, v142, v142 quad_perm:[1,0,3,2] row_mask:0xf bank_mask:0xf
	v_pk_mul_f32 v[134:135], v[28:29], v[44:45]
	ds_read_b128 v[38:41], v112 offset:5632
	ds_read_b128 v[42:45], v112 offset:5648
	v_add_f32_dpp v140, v140, v140 quad_perm:[2,3,0,1] row_mask:0xf bank_mask:0xf
	v_add_f32_dpp v142, v142, v142 quad_perm:[2,3,0,1] row_mask:0xf bank_mask:0xf
	s_waitcnt lgkmcnt(7)
	v_pk_fma_f32 v[22:23], v[140:141], v[70:71], v[128:129] op_sel_hi:[0,1,1] neg_lo:[1,0,0] neg_hi:[1,0,0]
	v_pk_fma_f32 v[24:25], v[140:141], v[72:73], v[130:131] op_sel_hi:[0,1,1] neg_lo:[1,0,0] neg_hi:[1,0,0]
	v_pk_fma_f32 v[26:27], v[140:141], v[74:75], v[132:133] op_sel_hi:[0,1,1] neg_lo:[1,0,0] neg_hi:[1,0,0]
	v_pk_fma_f32 v[28:29], v[140:141], v[76:77], v[134:135] op_sel_hi:[0,1,1] neg_lo:[1,0,0] neg_hi:[1,0,0]
	ds_read_b128 v[70:73], v112 offset:9728
	ds_read_b128 v[74:77], v112 offset:9744
	ds_write_b32 v108, v142 offset:23040
	s_waitcnt lgkmcnt(3)
	v_pk_mul_f32 v[136:137], v[22:23], v[30:31]
	v_pk_mul_f32 v[138:139], v[22:23], v[96:97]
	v_pk_fma_f32 v[136:137], v[24:25], v[32:33], v[136:137]
	v_pk_fma_f32 v[138:139], v[24:25], v[98:99], v[138:139]
	v_pk_fma_f32 v[136:137], v[26:27], v[34:35], v[136:137]
	v_pk_fma_f32 v[138:139], v[26:27], v[100:101], v[138:139]
	v_pk_fma_f32 v[136:137], v[28:29], v[36:37], v[136:137]
	v_pk_fma_f32 v[138:139], v[28:29], v[102:103], v[138:139]
	ds_read_b128 v[30:33], v112 offset:1792
	ds_read_b128 v[34:37], v112 offset:1808
	ds_read_b128 v[96:99], v112 offset:17920
	ds_read_b128 v[100:103], v112 offset:17936
	v_add_f32_e32 v140, v136, v137
	v_add_f32_e32 v142, v138, v139
	v_pk_mul_f32 v[128:129], v[22:23], v[38:39]
	v_add_f32_dpp v140, v140, v140 row_half_mirror row_mask:0xf bank_mask:0xf
	v_add_f32_dpp v142, v142, v142 row_half_mirror row_mask:0xf bank_mask:0xf
	v_pk_mul_f32 v[130:131], v[24:25], v[40:41]
	v_pk_mul_f32 v[132:133], v[26:27], v[42:43]
	v_add_f32_dpp v140, v140, v140 quad_perm:[1,0,3,2] row_mask:0xf bank_mask:0xf
	v_add_f32_dpp v142, v142, v142 quad_perm:[1,0,3,2] row_mask:0xf bank_mask:0xf
	v_pk_mul_f32 v[134:135], v[28:29], v[44:45]
	ds_read_b128 v[38:41], v112 offset:5888
	ds_read_b128 v[42:45], v112 offset:5904
	v_add_f32_dpp v140, v140, v140 quad_perm:[2,3,0,1] row_mask:0xf bank_mask:0xf
	v_add_f32_dpp v142, v142, v142 quad_perm:[2,3,0,1] row_mask:0xf bank_mask:0xf
	s_waitcnt lgkmcnt(7)
	v_pk_fma_f32 v[22:23], v[140:141], v[70:71], v[128:129] op_sel_hi:[0,1,1] neg_lo:[1,0,0] neg_hi:[1,0,0]
	v_pk_fma_f32 v[24:25], v[140:141], v[72:73], v[130:131] op_sel_hi:[0,1,1] neg_lo:[1,0,0] neg_hi:[1,0,0]
	v_pk_fma_f32 v[26:27], v[140:141], v[74:75], v[132:133] op_sel_hi:[0,1,1] neg_lo:[1,0,0] neg_hi:[1,0,0]
	v_pk_fma_f32 v[28:29], v[140:141], v[76:77], v[134:135] op_sel_hi:[0,1,1] neg_lo:[1,0,0] neg_hi:[1,0,0]
	ds_read_b128 v[70:73], v112 offset:9984
	ds_read_b128 v[74:77], v112 offset:10000
	ds_write_b32 v108, v142 offset:23168
	s_waitcnt lgkmcnt(3)
	v_pk_mul_f32 v[136:137], v[22:23], v[30:31]
	v_pk_mul_f32 v[138:139], v[22:23], v[96:97]
	v_pk_fma_f32 v[136:137], v[24:25], v[32:33], v[136:137]
	v_pk_fma_f32 v[138:139], v[24:25], v[98:99], v[138:139]
	v_pk_fma_f32 v[136:137], v[26:27], v[34:35], v[136:137]
	v_pk_fma_f32 v[138:139], v[26:27], v[100:101], v[138:139]
	v_pk_fma_f32 v[136:137], v[28:29], v[36:37], v[136:137]
	v_pk_fma_f32 v[138:139], v[28:29], v[102:103], v[138:139]
	ds_read_b128 v[30:33], v112 offset:2048
	ds_read_b128 v[34:37], v112 offset:2064
	ds_read_b128 v[96:99], v112 offset:18176
	ds_read_b128 v[100:103], v112 offset:18192
	v_add_f32_e32 v140, v136, v137
	v_add_f32_e32 v142, v138, v139
	v_pk_mul_f32 v[128:129], v[22:23], v[38:39]
	v_add_f32_dpp v140, v140, v140 row_half_mirror row_mask:0xf bank_mask:0xf
	v_add_f32_dpp v142, v142, v142 row_half_mirror row_mask:0xf bank_mask:0xf
	v_pk_mul_f32 v[130:131], v[24:25], v[40:41]
	v_pk_mul_f32 v[132:133], v[26:27], v[42:43]
	v_add_f32_dpp v140, v140, v140 quad_perm:[1,0,3,2] row_mask:0xf bank_mask:0xf
	v_add_f32_dpp v142, v142, v142 quad_perm:[1,0,3,2] row_mask:0xf bank_mask:0xf
	v_pk_mul_f32 v[134:135], v[28:29], v[44:45]
	ds_read_b128 v[38:41], v112 offset:6144
	ds_read_b128 v[42:45], v112 offset:6160
	v_add_f32_dpp v140, v140, v140 quad_perm:[2,3,0,1] row_mask:0xf bank_mask:0xf
	v_add_f32_dpp v142, v142, v142 quad_perm:[2,3,0,1] row_mask:0xf bank_mask:0xf
	s_waitcnt lgkmcnt(7)
	v_pk_fma_f32 v[22:23], v[140:141], v[70:71], v[128:129] op_sel_hi:[0,1,1] neg_lo:[1,0,0] neg_hi:[1,0,0]
	v_pk_fma_f32 v[24:25], v[140:141], v[72:73], v[130:131] op_sel_hi:[0,1,1] neg_lo:[1,0,0] neg_hi:[1,0,0]
	v_pk_fma_f32 v[26:27], v[140:141], v[74:75], v[132:133] op_sel_hi:[0,1,1] neg_lo:[1,0,0] neg_hi:[1,0,0]
	v_pk_fma_f32 v[28:29], v[140:141], v[76:77], v[134:135] op_sel_hi:[0,1,1] neg_lo:[1,0,0] neg_hi:[1,0,0]
	ds_read_b128 v[70:73], v112 offset:10240
	ds_read_b128 v[74:77], v112 offset:10256
	ds_write_b32 v108, v142 offset:23296
	s_waitcnt lgkmcnt(3)
	v_pk_mul_f32 v[136:137], v[22:23], v[30:31]
	v_pk_mul_f32 v[138:139], v[22:23], v[96:97]
	v_pk_fma_f32 v[136:137], v[24:25], v[32:33], v[136:137]
	v_pk_fma_f32 v[138:139], v[24:25], v[98:99], v[138:139]
	v_pk_fma_f32 v[136:137], v[26:27], v[34:35], v[136:137]
	v_pk_fma_f32 v[138:139], v[26:27], v[100:101], v[138:139]
	v_pk_fma_f32 v[136:137], v[28:29], v[36:37], v[136:137]
	v_pk_fma_f32 v[138:139], v[28:29], v[102:103], v[138:139]
	ds_read_b128 v[30:33], v112 offset:2304
	ds_read_b128 v[34:37], v112 offset:2320
	ds_read_b128 v[96:99], v112 offset:18432
	ds_read_b128 v[100:103], v112 offset:18448
	v_add_f32_e32 v140, v136, v137
	v_add_f32_e32 v142, v138, v139
	v_pk_mul_f32 v[128:129], v[22:23], v[38:39]
	v_add_f32_dpp v140, v140, v140 row_half_mirror row_mask:0xf bank_mask:0xf
	v_add_f32_dpp v142, v142, v142 row_half_mirror row_mask:0xf bank_mask:0xf
	v_pk_mul_f32 v[130:131], v[24:25], v[40:41]
	v_pk_mul_f32 v[132:133], v[26:27], v[42:43]
	v_add_f32_dpp v140, v140, v140 quad_perm:[1,0,3,2] row_mask:0xf bank_mask:0xf
	v_add_f32_dpp v142, v142, v142 quad_perm:[1,0,3,2] row_mask:0xf bank_mask:0xf
	v_pk_mul_f32 v[134:135], v[28:29], v[44:45]
	ds_read_b128 v[38:41], v112 offset:6400
	ds_read_b128 v[42:45], v112 offset:6416
	v_add_f32_dpp v140, v140, v140 quad_perm:[2,3,0,1] row_mask:0xf bank_mask:0xf
	v_add_f32_dpp v142, v142, v142 quad_perm:[2,3,0,1] row_mask:0xf bank_mask:0xf
	s_waitcnt lgkmcnt(7)
	v_pk_fma_f32 v[22:23], v[140:141], v[70:71], v[128:129] op_sel_hi:[0,1,1] neg_lo:[1,0,0] neg_hi:[1,0,0]
	v_pk_fma_f32 v[24:25], v[140:141], v[72:73], v[130:131] op_sel_hi:[0,1,1] neg_lo:[1,0,0] neg_hi:[1,0,0]
	v_pk_fma_f32 v[26:27], v[140:141], v[74:75], v[132:133] op_sel_hi:[0,1,1] neg_lo:[1,0,0] neg_hi:[1,0,0]
	v_pk_fma_f32 v[28:29], v[140:141], v[76:77], v[134:135] op_sel_hi:[0,1,1] neg_lo:[1,0,0] neg_hi:[1,0,0]
	ds_read_b128 v[70:73], v112 offset:10496
	ds_read_b128 v[74:77], v112 offset:10512
	ds_write_b32 v108, v142 offset:23424
	s_waitcnt lgkmcnt(3)
	v_pk_mul_f32 v[136:137], v[22:23], v[30:31]
	v_pk_mul_f32 v[138:139], v[22:23], v[96:97]
	v_pk_fma_f32 v[136:137], v[24:25], v[32:33], v[136:137]
	v_pk_fma_f32 v[138:139], v[24:25], v[98:99], v[138:139]
	v_pk_fma_f32 v[136:137], v[26:27], v[34:35], v[136:137]
	v_pk_fma_f32 v[138:139], v[26:27], v[100:101], v[138:139]
	v_pk_fma_f32 v[136:137], v[28:29], v[36:37], v[136:137]
	v_pk_fma_f32 v[138:139], v[28:29], v[102:103], v[138:139]
	ds_read_b128 v[30:33], v112 offset:2560
	ds_read_b128 v[34:37], v112 offset:2576
	ds_read_b128 v[96:99], v112 offset:18688
	ds_read_b128 v[100:103], v112 offset:18704
	v_add_f32_e32 v140, v136, v137
	v_add_f32_e32 v142, v138, v139
	v_pk_mul_f32 v[128:129], v[22:23], v[38:39]
	v_add_f32_dpp v140, v140, v140 row_half_mirror row_mask:0xf bank_mask:0xf
	v_add_f32_dpp v142, v142, v142 row_half_mirror row_mask:0xf bank_mask:0xf
	v_pk_mul_f32 v[130:131], v[24:25], v[40:41]
	v_pk_mul_f32 v[132:133], v[26:27], v[42:43]
	v_add_f32_dpp v140, v140, v140 quad_perm:[1,0,3,2] row_mask:0xf bank_mask:0xf
	v_add_f32_dpp v142, v142, v142 quad_perm:[1,0,3,2] row_mask:0xf bank_mask:0xf
	v_pk_mul_f32 v[134:135], v[28:29], v[44:45]
	ds_read_b128 v[38:41], v112 offset:6656
	ds_read_b128 v[42:45], v112 offset:6672
	v_add_f32_dpp v140, v140, v140 quad_perm:[2,3,0,1] row_mask:0xf bank_mask:0xf
	v_add_f32_dpp v142, v142, v142 quad_perm:[2,3,0,1] row_mask:0xf bank_mask:0xf
	s_waitcnt lgkmcnt(7)
	v_pk_fma_f32 v[22:23], v[140:141], v[70:71], v[128:129] op_sel_hi:[0,1,1] neg_lo:[1,0,0] neg_hi:[1,0,0]
	v_pk_fma_f32 v[24:25], v[140:141], v[72:73], v[130:131] op_sel_hi:[0,1,1] neg_lo:[1,0,0] neg_hi:[1,0,0]
	v_pk_fma_f32 v[26:27], v[140:141], v[74:75], v[132:133] op_sel_hi:[0,1,1] neg_lo:[1,0,0] neg_hi:[1,0,0]
	v_pk_fma_f32 v[28:29], v[140:141], v[76:77], v[134:135] op_sel_hi:[0,1,1] neg_lo:[1,0,0] neg_hi:[1,0,0]
	ds_read_b128 v[70:73], v112 offset:10752
	ds_read_b128 v[74:77], v112 offset:10768
	ds_write_b32 v108, v142 offset:23552
	s_waitcnt lgkmcnt(3)
	v_pk_mul_f32 v[136:137], v[22:23], v[30:31]
	v_pk_mul_f32 v[138:139], v[22:23], v[96:97]
	v_pk_fma_f32 v[136:137], v[24:25], v[32:33], v[136:137]
	v_pk_fma_f32 v[138:139], v[24:25], v[98:99], v[138:139]
	v_pk_fma_f32 v[136:137], v[26:27], v[34:35], v[136:137]
	v_pk_fma_f32 v[138:139], v[26:27], v[100:101], v[138:139]
	v_pk_fma_f32 v[136:137], v[28:29], v[36:37], v[136:137]
	v_pk_fma_f32 v[138:139], v[28:29], v[102:103], v[138:139]
	ds_read_b128 v[30:33], v112 offset:2816
	ds_read_b128 v[34:37], v112 offset:2832
	ds_read_b128 v[96:99], v112 offset:18944
	ds_read_b128 v[100:103], v112 offset:18960
	v_add_f32_e32 v140, v136, v137
	v_add_f32_e32 v142, v138, v139
	v_pk_mul_f32 v[128:129], v[22:23], v[38:39]
	v_add_f32_dpp v140, v140, v140 row_half_mirror row_mask:0xf bank_mask:0xf
	v_add_f32_dpp v142, v142, v142 row_half_mirror row_mask:0xf bank_mask:0xf
	v_pk_mul_f32 v[130:131], v[24:25], v[40:41]
	v_pk_mul_f32 v[132:133], v[26:27], v[42:43]
	v_add_f32_dpp v140, v140, v140 quad_perm:[1,0,3,2] row_mask:0xf bank_mask:0xf
	v_add_f32_dpp v142, v142, v142 quad_perm:[1,0,3,2] row_mask:0xf bank_mask:0xf
	v_pk_mul_f32 v[134:135], v[28:29], v[44:45]
	ds_read_b128 v[38:41], v112 offset:6912
	ds_read_b128 v[42:45], v112 offset:6928
	v_add_f32_dpp v140, v140, v140 quad_perm:[2,3,0,1] row_mask:0xf bank_mask:0xf
	v_add_f32_dpp v142, v142, v142 quad_perm:[2,3,0,1] row_mask:0xf bank_mask:0xf
	s_waitcnt lgkmcnt(7)
	v_pk_fma_f32 v[22:23], v[140:141], v[70:71], v[128:129] op_sel_hi:[0,1,1] neg_lo:[1,0,0] neg_hi:[1,0,0]
	v_pk_fma_f32 v[24:25], v[140:141], v[72:73], v[130:131] op_sel_hi:[0,1,1] neg_lo:[1,0,0] neg_hi:[1,0,0]
	v_pk_fma_f32 v[26:27], v[140:141], v[74:75], v[132:133] op_sel_hi:[0,1,1] neg_lo:[1,0,0] neg_hi:[1,0,0]
	v_pk_fma_f32 v[28:29], v[140:141], v[76:77], v[134:135] op_sel_hi:[0,1,1] neg_lo:[1,0,0] neg_hi:[1,0,0]
	ds_read_b128 v[70:73], v112 offset:11008
	ds_read_b128 v[74:77], v112 offset:11024
	ds_write_b32 v108, v142 offset:23680
	s_waitcnt lgkmcnt(3)
	v_pk_mul_f32 v[136:137], v[22:23], v[30:31]
	v_pk_mul_f32 v[138:139], v[22:23], v[96:97]
	v_pk_fma_f32 v[136:137], v[24:25], v[32:33], v[136:137]
	v_pk_fma_f32 v[138:139], v[24:25], v[98:99], v[138:139]
	v_pk_fma_f32 v[136:137], v[26:27], v[34:35], v[136:137]
	v_pk_fma_f32 v[138:139], v[26:27], v[100:101], v[138:139]
	v_pk_fma_f32 v[136:137], v[28:29], v[36:37], v[136:137]
	v_pk_fma_f32 v[138:139], v[28:29], v[102:103], v[138:139]
	ds_read_b128 v[30:33], v112 offset:3072
	ds_read_b128 v[34:37], v112 offset:3088
	ds_read_b128 v[96:99], v112 offset:19200
	ds_read_b128 v[100:103], v112 offset:19216
	v_add_f32_e32 v140, v136, v137
	v_add_f32_e32 v142, v138, v139
	v_pk_mul_f32 v[128:129], v[22:23], v[38:39]
	v_add_f32_dpp v140, v140, v140 row_half_mirror row_mask:0xf bank_mask:0xf
	v_add_f32_dpp v142, v142, v142 row_half_mirror row_mask:0xf bank_mask:0xf
	v_pk_mul_f32 v[130:131], v[24:25], v[40:41]
	v_pk_mul_f32 v[132:133], v[26:27], v[42:43]
	v_add_f32_dpp v140, v140, v140 quad_perm:[1,0,3,2] row_mask:0xf bank_mask:0xf
	v_add_f32_dpp v142, v142, v142 quad_perm:[1,0,3,2] row_mask:0xf bank_mask:0xf
	v_pk_mul_f32 v[134:135], v[28:29], v[44:45]
	ds_read_b128 v[38:41], v112 offset:7168
	ds_read_b128 v[42:45], v112 offset:7184
	v_add_f32_dpp v140, v140, v140 quad_perm:[2,3,0,1] row_mask:0xf bank_mask:0xf
	v_add_f32_dpp v142, v142, v142 quad_perm:[2,3,0,1] row_mask:0xf bank_mask:0xf
	s_waitcnt lgkmcnt(7)
	v_pk_fma_f32 v[22:23], v[140:141], v[70:71], v[128:129] op_sel_hi:[0,1,1] neg_lo:[1,0,0] neg_hi:[1,0,0]
	v_pk_fma_f32 v[24:25], v[140:141], v[72:73], v[130:131] op_sel_hi:[0,1,1] neg_lo:[1,0,0] neg_hi:[1,0,0]
	v_pk_fma_f32 v[26:27], v[140:141], v[74:75], v[132:133] op_sel_hi:[0,1,1] neg_lo:[1,0,0] neg_hi:[1,0,0]
	v_pk_fma_f32 v[28:29], v[140:141], v[76:77], v[134:135] op_sel_hi:[0,1,1] neg_lo:[1,0,0] neg_hi:[1,0,0]
	ds_read_b128 v[70:73], v112 offset:11264
	ds_read_b128 v[74:77], v112 offset:11280
	ds_write_b32 v108, v142 offset:23808
	s_waitcnt lgkmcnt(3)
	v_pk_mul_f32 v[136:137], v[22:23], v[30:31]
	v_pk_mul_f32 v[138:139], v[22:23], v[96:97]
	v_pk_fma_f32 v[136:137], v[24:25], v[32:33], v[136:137]
	v_pk_fma_f32 v[138:139], v[24:25], v[98:99], v[138:139]
	v_pk_fma_f32 v[136:137], v[26:27], v[34:35], v[136:137]
	v_pk_fma_f32 v[138:139], v[26:27], v[100:101], v[138:139]
	v_pk_fma_f32 v[136:137], v[28:29], v[36:37], v[136:137]
	v_pk_fma_f32 v[138:139], v[28:29], v[102:103], v[138:139]
	ds_read_b128 v[30:33], v112 offset:3328
	ds_read_b128 v[34:37], v112 offset:3344
	ds_read_b128 v[96:99], v112 offset:19456
	ds_read_b128 v[100:103], v112 offset:19472
	v_add_f32_e32 v140, v136, v137
	v_add_f32_e32 v142, v138, v139
	v_pk_mul_f32 v[128:129], v[22:23], v[38:39]
	v_add_f32_dpp v140, v140, v140 row_half_mirror row_mask:0xf bank_mask:0xf
	v_add_f32_dpp v142, v142, v142 row_half_mirror row_mask:0xf bank_mask:0xf
	v_pk_mul_f32 v[130:131], v[24:25], v[40:41]
	v_pk_mul_f32 v[132:133], v[26:27], v[42:43]
	v_add_f32_dpp v140, v140, v140 quad_perm:[1,0,3,2] row_mask:0xf bank_mask:0xf
	v_add_f32_dpp v142, v142, v142 quad_perm:[1,0,3,2] row_mask:0xf bank_mask:0xf
	v_pk_mul_f32 v[134:135], v[28:29], v[44:45]
	ds_read_b128 v[38:41], v112 offset:7424
	ds_read_b128 v[42:45], v112 offset:7440
	v_add_f32_dpp v140, v140, v140 quad_perm:[2,3,0,1] row_mask:0xf bank_mask:0xf
	v_add_f32_dpp v142, v142, v142 quad_perm:[2,3,0,1] row_mask:0xf bank_mask:0xf
	s_waitcnt lgkmcnt(7)
	v_pk_fma_f32 v[22:23], v[140:141], v[70:71], v[128:129] op_sel_hi:[0,1,1] neg_lo:[1,0,0] neg_hi:[1,0,0]
	v_pk_fma_f32 v[24:25], v[140:141], v[72:73], v[130:131] op_sel_hi:[0,1,1] neg_lo:[1,0,0] neg_hi:[1,0,0]
	v_pk_fma_f32 v[26:27], v[140:141], v[74:75], v[132:133] op_sel_hi:[0,1,1] neg_lo:[1,0,0] neg_hi:[1,0,0]
	v_pk_fma_f32 v[28:29], v[140:141], v[76:77], v[134:135] op_sel_hi:[0,1,1] neg_lo:[1,0,0] neg_hi:[1,0,0]
	ds_read_b128 v[70:73], v112 offset:11520
	ds_read_b128 v[74:77], v112 offset:11536
	ds_write_b32 v108, v142 offset:23936
	s_waitcnt lgkmcnt(3)
	v_pk_mul_f32 v[136:137], v[22:23], v[30:31]
	v_pk_mul_f32 v[138:139], v[22:23], v[96:97]
	v_pk_fma_f32 v[136:137], v[24:25], v[32:33], v[136:137]
	v_pk_fma_f32 v[138:139], v[24:25], v[98:99], v[138:139]
	v_pk_fma_f32 v[136:137], v[26:27], v[34:35], v[136:137]
	v_pk_fma_f32 v[138:139], v[26:27], v[100:101], v[138:139]
	v_pk_fma_f32 v[136:137], v[28:29], v[36:37], v[136:137]
	v_pk_fma_f32 v[138:139], v[28:29], v[102:103], v[138:139]
	ds_read_b128 v[30:33], v112 offset:3584
	ds_read_b128 v[34:37], v112 offset:3600
	ds_read_b128 v[96:99], v112 offset:19712
	ds_read_b128 v[100:103], v112 offset:19728
	v_add_f32_e32 v140, v136, v137
	v_add_f32_e32 v142, v138, v139
	v_pk_mul_f32 v[128:129], v[22:23], v[38:39]
	v_add_f32_dpp v140, v140, v140 row_half_mirror row_mask:0xf bank_mask:0xf
	v_add_f32_dpp v142, v142, v142 row_half_mirror row_mask:0xf bank_mask:0xf
	v_pk_mul_f32 v[130:131], v[24:25], v[40:41]
	v_pk_mul_f32 v[132:133], v[26:27], v[42:43]
	v_add_f32_dpp v140, v140, v140 quad_perm:[1,0,3,2] row_mask:0xf bank_mask:0xf
	v_add_f32_dpp v142, v142, v142 quad_perm:[1,0,3,2] row_mask:0xf bank_mask:0xf
	v_pk_mul_f32 v[134:135], v[28:29], v[44:45]
	ds_read_b128 v[38:41], v112 offset:7680
	ds_read_b128 v[42:45], v112 offset:7696
	v_add_f32_dpp v140, v140, v140 quad_perm:[2,3,0,1] row_mask:0xf bank_mask:0xf
	v_add_f32_dpp v142, v142, v142 quad_perm:[2,3,0,1] row_mask:0xf bank_mask:0xf
	s_waitcnt lgkmcnt(7)
	v_pk_fma_f32 v[22:23], v[140:141], v[70:71], v[128:129] op_sel_hi:[0,1,1] neg_lo:[1,0,0] neg_hi:[1,0,0]
	v_pk_fma_f32 v[24:25], v[140:141], v[72:73], v[130:131] op_sel_hi:[0,1,1] neg_lo:[1,0,0] neg_hi:[1,0,0]
	v_pk_fma_f32 v[26:27], v[140:141], v[74:75], v[132:133] op_sel_hi:[0,1,1] neg_lo:[1,0,0] neg_hi:[1,0,0]
	v_pk_fma_f32 v[28:29], v[140:141], v[76:77], v[134:135] op_sel_hi:[0,1,1] neg_lo:[1,0,0] neg_hi:[1,0,0]
	ds_read_b128 v[70:73], v112 offset:11776
	ds_read_b128 v[74:77], v112 offset:11792
	ds_write_b32 v108, v142 offset:24064
	s_waitcnt lgkmcnt(3)
	v_pk_mul_f32 v[136:137], v[22:23], v[30:31]
	v_pk_mul_f32 v[138:139], v[22:23], v[96:97]
	v_pk_fma_f32 v[136:137], v[24:25], v[32:33], v[136:137]
	v_pk_fma_f32 v[138:139], v[24:25], v[98:99], v[138:139]
	v_pk_fma_f32 v[136:137], v[26:27], v[34:35], v[136:137]
	v_pk_fma_f32 v[138:139], v[26:27], v[100:101], v[138:139]
	v_pk_fma_f32 v[136:137], v[28:29], v[36:37], v[136:137]
	v_pk_fma_f32 v[138:139], v[28:29], v[102:103], v[138:139]
	ds_read_b128 v[30:33], v112 offset:3840
	ds_read_b128 v[34:37], v112 offset:3856
	ds_read_b128 v[96:99], v112 offset:19968
	ds_read_b128 v[100:103], v112 offset:19984
	v_add_f32_e32 v140, v136, v137
	v_add_f32_e32 v142, v138, v139
	v_pk_mul_f32 v[128:129], v[22:23], v[38:39]
	v_add_f32_dpp v140, v140, v140 row_half_mirror row_mask:0xf bank_mask:0xf
	v_add_f32_dpp v142, v142, v142 row_half_mirror row_mask:0xf bank_mask:0xf
	v_pk_mul_f32 v[130:131], v[24:25], v[40:41]
	v_pk_mul_f32 v[132:133], v[26:27], v[42:43]
	v_add_f32_dpp v140, v140, v140 quad_perm:[1,0,3,2] row_mask:0xf bank_mask:0xf
	v_add_f32_dpp v142, v142, v142 quad_perm:[1,0,3,2] row_mask:0xf bank_mask:0xf
	v_pk_mul_f32 v[134:135], v[28:29], v[44:45]
	ds_read_b128 v[38:41], v112 offset:7936
	ds_read_b128 v[42:45], v112 offset:7952
	v_add_f32_dpp v140, v140, v140 quad_perm:[2,3,0,1] row_mask:0xf bank_mask:0xf
	v_add_f32_dpp v142, v142, v142 quad_perm:[2,3,0,1] row_mask:0xf bank_mask:0xf
	s_waitcnt lgkmcnt(7)
	v_pk_fma_f32 v[22:23], v[140:141], v[70:71], v[128:129] op_sel_hi:[0,1,1] neg_lo:[1,0,0] neg_hi:[1,0,0]
	v_pk_fma_f32 v[24:25], v[140:141], v[72:73], v[130:131] op_sel_hi:[0,1,1] neg_lo:[1,0,0] neg_hi:[1,0,0]
	v_pk_fma_f32 v[26:27], v[140:141], v[74:75], v[132:133] op_sel_hi:[0,1,1] neg_lo:[1,0,0] neg_hi:[1,0,0]
	v_pk_fma_f32 v[28:29], v[140:141], v[76:77], v[134:135] op_sel_hi:[0,1,1] neg_lo:[1,0,0] neg_hi:[1,0,0]
	ds_read_b128 v[70:73], v112 offset:12032
	ds_read_b128 v[74:77], v112 offset:12048
	ds_write_b32 v108, v142 offset:24192
	s_waitcnt lgkmcnt(3)
	v_pk_mul_f32 v[136:137], v[22:23], v[30:31]
	v_pk_mul_f32 v[138:139], v[22:23], v[96:97]
	v_pk_fma_f32 v[136:137], v[24:25], v[32:33], v[136:137]
	v_pk_fma_f32 v[138:139], v[24:25], v[98:99], v[138:139]
	v_pk_fma_f32 v[136:137], v[26:27], v[34:35], v[136:137]
	v_pk_fma_f32 v[138:139], v[26:27], v[100:101], v[138:139]
	v_pk_fma_f32 v[136:137], v[28:29], v[36:37], v[136:137]
	v_pk_fma_f32 v[138:139], v[28:29], v[102:103], v[138:139]
	ds_read_b128 v[96:99], v112 offset:20224
	ds_read_b128 v[100:103], v112 offset:20240
	v_add_f32_e32 v140, v136, v137
	v_add_f32_e32 v142, v138, v139
	v_pk_mul_f32 v[128:129], v[22:23], v[38:39]
	v_add_f32_dpp v140, v140, v140 row_half_mirror row_mask:0xf bank_mask:0xf
	v_add_f32_dpp v142, v142, v142 row_half_mirror row_mask:0xf bank_mask:0xf
	v_pk_mul_f32 v[130:131], v[24:25], v[40:41]
	v_pk_mul_f32 v[132:133], v[26:27], v[42:43]
	v_add_f32_dpp v140, v140, v140 quad_perm:[1,0,3,2] row_mask:0xf bank_mask:0xf
	v_add_f32_dpp v142, v142, v142 quad_perm:[1,0,3,2] row_mask:0xf bank_mask:0xf
	v_pk_mul_f32 v[134:135], v[28:29], v[44:45]
	v_add_f32_dpp v140, v140, v140 quad_perm:[2,3,0,1] row_mask:0xf bank_mask:0xf
	v_add_f32_dpp v142, v142, v142 quad_perm:[2,3,0,1] row_mask:0xf bank_mask:0xf
	s_waitcnt lgkmcnt(3)
	v_pk_fma_f32 v[22:23], v[140:141], v[70:71], v[128:129] op_sel_hi:[0,1,1] neg_lo:[1,0,0] neg_hi:[1,0,0]
	v_pk_fma_f32 v[24:25], v[140:141], v[72:73], v[130:131] op_sel_hi:[0,1,1] neg_lo:[1,0,0] neg_hi:[1,0,0]
	v_pk_fma_f32 v[26:27], v[140:141], v[74:75], v[132:133] op_sel_hi:[0,1,1] neg_lo:[1,0,0] neg_hi:[1,0,0]
	v_pk_fma_f32 v[28:29], v[140:141], v[76:77], v[134:135] op_sel_hi:[0,1,1] neg_lo:[1,0,0] neg_hi:[1,0,0]
	ds_write_b32 v108, v142 offset:24320
	s_waitcnt lgkmcnt(1)
	v_pk_mul_f32 v[138:139], v[22:23], v[96:97]
	v_pk_fma_f32 v[138:139], v[24:25], v[98:99], v[138:139]
	v_pk_fma_f32 v[138:139], v[26:27], v[100:101], v[138:139]
	v_pk_fma_f32 v[138:139], v[28:29], v[102:103], v[138:139]
	v_add_f32_e32 v142, v138, v139
	s_nop 1
	v_add_f32_dpp v142, v142, v142 row_half_mirror row_mask:0xf bank_mask:0xf
	s_nop 1
	v_add_f32_dpp v142, v142, v142 quad_perm:[1,0,3,2] row_mask:0xf bank_mask:0xf
	s_nop 1
	v_add_f32_dpp v142, v142, v142 quad_perm:[2,3,0,1] row_mask:0xf bank_mask:0xf
	ds_write_b32 v108, v142 offset:24448
.Lrw0_u2e0:
	s_add_u32 s28, s28, 16
	s_mov_b32 s35, 1
	s_waitcnt vmcnt(0)
	ds_write_b128 v110, v[58:61] offset:26624
	ds_write_b128 v110, v[62:65] offset:30720
	ds_write_b128 v110, v[66:69] offset:34816
	s_waitcnt lgkmcnt(0)
	s_barrier
	s_add_u32 s30, s28, 32
	v_add_u32_e32 v87, s30, v15
	v_med3_i32 v87, v87, 0, s29
	v_mad_i64_i32 v[104:105], vcc, v87, v12, v[6:7]
	global_load_dwordx4 v[58:61], v[104:105], off
	v_add_u32_e32 v87, s30, v16
	v_med3_i32 v87, v87, 0, s29
	v_mad_i64_i32 v[104:105], vcc, v87, v13, v[8:9]
	global_load_dwordx4 v[62:65], v[104:105], off
	v_add_u32_e32 v87, s30, v17
	v_med3_i32 v87, v87, 0, s29
	v_mad_i64_i32 v[104:105], vcc, v87, v14, v[10:11]
	global_load_dwordx4 v[66:69], v[104:105], off
	ds_read_b32 v89, v5 offset:22528
	ds_read_b32 v90, v5 offset:22592
	s_sub_u32 s98, s28, 16
	v_add_u32_e32 v87, s98, v127
	v_mad_i64_i32 v[104:105], vcc, v87, v20, v[18:19]
	s_waitcnt lgkmcnt(0)
	v_cvt_pk_bf16_f32 v89, v89, v90
	global_store_short v[104:105], v89, off
	global_store_short_d16_hi v[104:105], v89, off offset:32
	ds_read_b128 v[30:33], v93 offset:46080
	ds_read_b128 v[34:37], v93 offset:46096
	ds_read_b128 v[38:41], v93 offset:46112
	ds_read_b128 v[42:45], v93 offset:46128
	ds_read_b64 v[70:71], v1 offset:27008
	ds_read_b64 v[72:73], v1 offset:26624
	ds_read_b64 v[74:75], v1 offset:27392
	ds_read_b64 v[76:77], v1 offset:27136
	ds_read_b64 v[78:79], v1 offset:26752
	ds_read_b64 v[80:81], v1 offset:27520
	ds_read_b64 v[82:83], v1 offset:27264
	ds_read_b64 v[84:85], v1 offset:26880
	ds_read_b64 v[96:97], v1 offset:27648
	ds_read_b64 v[128:129], v2 offset:33536
	ds_read_b64 v[130:131], v2 offset:33664
	v_add_u32_e32 v87, s28, v127
	v_cmp_ne_u32_e32 vcc, 0, v87
	s_nop 1
	v_cndmask_b32_e64 v98, 0, 0.5, vcc
	v_cmp_ne_u32_e32 vcc, s29, v87
	s_nop 1
	v_cndmask_b32_e64 v100, 0, 0.5, vcc
	s_waitcnt lgkmcnt(8)
	v_lshlrev_b32_e32 v132, 16, v70
	v_and_b32_e32 v133, 0xffff0000, v70
	v_lshlrev_b32_e32 v134, 16, v71
	v_and_b32_e32 v135, 0xffff0000, v71
	v_lshlrev_b32_e32 v136, 16, v72
	v_and_b32_e32 v137, 0xffff0000, v72
	v_lshlrev_b32_e32 v138, 16, v73
	v_and_b32_e32 v139, 0xffff0000, v73
	v_lshlrev_b32_e32 v140, 16, v74
	v_and_b32_e32 v141, 0xffff0000, v74
	v_lshlrev_b32_e32 v142, 16, v75
	v_and_b32_e32 v143, 0xffff0000, v75
	v_pk_mul_f32 v[136:137], v[136:137], v[98:99] op_sel_hi:[1,0]
	v_pk_fma_f32 v[136:137], v[140:141], v[100:101], v[136:137] op_sel_hi:[1,0,1]
	v_pk_add_f32 v[136:137], v[136:137], v[132:133] neg_lo:[0,1] neg_hi:[0,1]
	v_pk_fma_f32 v[144:145], v[30:31], v[136:137], v[132:133]
	v_pk_mul_f32 v[138:139], v[138:139], v[98:99] op_sel_hi:[1,0]
	v_pk_fma_f32 v[138:139], v[142:143], v[100:101], v[138:139] op_sel_hi:[1,0,1]
	v_pk_add_f32 v[138:139], v[138:139], v[134:135] neg_lo:[0,1] neg_hi:[0,1]
	v_pk_fma_f32 v[146:147], v[32:33], v[138:139], v[134:135]
	ds_read_b128 v[30:33], v93 offset:46144
	s_waitcnt lgkmcnt(6)
	v_lshlrev_b32_e32 v132, 16, v76
	v_and_b32_e32 v133, 0xffff0000, v76
	v_lshlrev_b32_e32 v134, 16, v77
	v_and_b32_e32 v135, 0xffff0000, v77
	v_lshlrev_b32_e32 v136, 16, v78
	v_and_b32_e32 v137, 0xffff0000, v78
	v_lshlrev_b32_e32 v138, 16, v79
	v_and_b32_e32 v139, 0xffff0000, v79
	v_lshlrev_b32_e32 v140, 16, v80
	v_and_b32_e32 v141, 0xffff0000, v80
	v_lshlrev_b32_e32 v142, 16, v81
	v_and_b32_e32 v143, 0xffff0000, v81
	v_pk_mul_f32 v[136:137], v[136:137], v[98:99] op_sel_hi:[1,0]
	v_pk_fma_f32 v[136:137], v[140:141], v[100:101], v[136:137] op_sel_hi:[1,0,1]
	v_pk_add_f32 v[136:137], v[136:137], v[132:133] neg_lo:[0,1] neg_hi:[0,1]
	v_pk_fma_f32 v[102:103], v[34:35], v[136:137], v[132:133]
	v_pk_mul_f32 v[138:139], v[138:139], v[98:99] op_sel_hi:[1,0]
	v_pk_fma_f32 v[138:139], v[142:143], v[100:101], v[138:139] op_sel_hi:[1,0,1]
	v_pk_add_f32 v[138:139], v[138:139], v[134:135] neg_lo:[0,1] neg_hi:[0,1]
	v_pk_fma_f32 v[104:105], v[36:37], v[138:139], v[134:135]
	s_waitcnt lgkmcnt(3)
	v_lshlrev_b32_e32 v132, 16, v82
	v_and_b32_e32 v133, 0xffff0000, v82
	v_lshlrev_b32_e32 v134, 16, v83
	v_and_b32_e32 v135, 0xffff0000, v83
	v_lshlrev_b32_e32 v136, 16, v84
	v_and_b32_e32 v137, 0xffff0000, v84
	v_lshlrev_b32_e32 v138, 16, v85
	v_and_b32_e32 v139, 0xffff0000, v85
	v_lshlrev_b32_e32 v140, 16, v96
	v_and_b32_e32 v141, 0xffff0000, v96
	v_lshlrev_b32_e32 v142, 16, v97
	v_and_b32_e32 v143, 0xffff0000, v97
	v_pk_mul_f32 v[136:137], v[136:137], v[98:99] op_sel_hi:[1,0]
	v_pk_fma_f32 v[136:137], v[140:141], v[100:101], v[136:137] op_sel_hi:[1,0,1]
	v_pk_add_f32 v[136:137], v[136:137], v[132:133] neg_lo:[0,1] neg_hi:[0,1]
	v_pk_fma_f32 v[148:149], v[38:39], v[136:137], v[132:133]
	v_pk_mul_f32 v[138:139], v[138:139], v[98:99] op_sel_hi:[1,0]
	v_pk_fma_f32 v[138:139], v[142:143], v[100:101], v[138:139] op_sel_hi:[1,0,1]
	v_pk_add_f32 v[138:139], v[138:139], v[134:135] neg_lo:[0,1] neg_hi:[0,1]
	v_pk_fma_f32 v[150:151], v[40:41], v[138:139], v[134:135]
	s_waitcnt lgkmcnt(0)
	v_lshlrev_b32_e32 v132, 16, v128
	v_and_b32_e32 v133, 0xffff0000, v128
	v_lshlrev_b32_e32 v134, 16, v129
	v_and_b32_e32 v135, 0xffff0000, v129
	v_lshlrev_b32_e32 v136, 16, v130
	v_and_b32_e32 v137, 0xffff0000, v130
	v_lshlrev_b32_e32 v138, 16, v131
	v_and_b32_e32 v139, 0xffff0000, v131
	s_mov_b32 s98, 0xbf60028b
	v_mul_f32_e32 v132, s98, v132
	v_mul_f32_e32 v133, s98, v133
	v_mul_f32_e32 v134, s98, v134
	v_mul_f32_e32 v135, s98, v135
	v_exp_f32_e32 v132, v132
	v_exp_f32_e32 v133, v133
	v_exp_f32_e32 v134, v134
	v_exp_f32_e32 v135, v135
	v_pk_mul_f32 v[140:141], v[102:103], v[42:43]
	v_pk_mul_f32 v[142:143], v[104:105], v[44:45]
	v_pk_mul_f32 v[106:107], v[140:141], v[140:141]
	v_pk_fma_f32 v[106:107], v[142:143], v[142:143], v[106:107]
	v_add_f32_e32 v106, v106, v107
	s_nop 1
	v_add_f32_dpp v106, v106, v106 row_ror:8 row_mask:0xf bank_mask:0xf bound_ctrl:1
	s_nop 1
	v_add_f32_dpp v106, v106, v106 row_ror:4 row_mask:0xf bank_mask:0xf bound_ctrl:1
	s_nop 1
	v_add_f32_dpp v106, v106, v106 row_ror:2 row_mask:0xf bank_mask:0xf bound_ctrl:1
	s_nop 1
	v_add_f32_dpp v106, v106, v106 row_ror:1 row_mask:0xf bank_mask:0xf bound_ctrl:1
	v_add_f32_e32 v106, 0x2b8cbccc, v106
	v_rsq_f32_e32 v106, v106
	v_pk_mul_f32 v[148:149], v[148:149], s[40:41] op_sel_hi:[1,0]
	v_pk_mul_f32 v[150:151], v[150:151], s[40:41] op_sel_hi:[1,0]
	v_pk_mul_f32 v[140:141], v[140:141], v[106:107] op_sel_hi:[1,0]
	v_pk_mul_f32 v[142:143], v[142:143], v[106:107] op_sel_hi:[1,0]
	v_pk_add_f32 v[70:71], v[136:137], -1.0 op_sel_hi:[1,0]
	v_pk_add_f32 v[72:73], v[138:139], -1.0 op_sel_hi:[1,0]
	v_pk_fma_f32 v[70:71], v[30:31], v[70:71], 1.0 op_sel_hi:[1,1,0]
	v_pk_fma_f32 v[72:73], v[32:33], v[72:73], 1.0 op_sel_hi:[1,1,0]
	v_pk_mul_f32 v[70:71], v[102:103], v[70:71]
	v_pk_mul_f32 v[72:73], v[104:105], v[72:73]
	v_pk_mul_f32 v[74:75], v[140:141], v[136:137]
	v_pk_mul_f32 v[76:77], v[142:143], v[138:139]
	ds_write_b128 v3, v[140:143] offset:0
	ds_write_b128 v3, v[132:135] offset:4096
	ds_write_b128 v3, v[74:77] offset:8192
	ds_write_b128 v3, v[70:73] offset:12288
	ds_write_b128 v3, v[144:147] offset:16384
	ds_write_b128 v4, v[148:151]
	s_waitcnt lgkmcnt(0)
	s_barrier
	s_cmp_eq_u32 s18, 2
	s_cbranch_scc1 .Lrw0_u2s1
	ds_read_b128 v[30:33], v112 offset:0
	ds_read_b128 v[34:37], v112 offset:16
	ds_read_b128 v[78:81], v112 offset:12288
	ds_read_b128 v[82:85], v112 offset:12304
	ds_read_b32 v104, v108 offset:20480
	ds_read_b128 v[38:41], v112 offset:4096
	ds_read_b128 v[42:45], v112 offset:4112
	ds_read_b128 v[70:73], v112 offset:8192
	ds_read_b128 v[74:77], v112 offset:8208
	s_waitcnt lgkmcnt(2)
	v_pk_mul_f32 v[136:137], v[22:23], v[30:31]
	v_pk_fma_f32 v[136:137], v[24:25], v[32:33], v[136:137]
	v_pk_fma_f32 v[136:137], v[26:27], v[34:35], v[136:137]
	v_pk_fma_f32 v[136:137], v[28:29], v[36:37], v[136:137]
	ds_read_b128 v[30:33], v112 offset:256
	ds_read_b128 v[34:37], v112 offset:272
	ds_read_b128 v[96:99], v112 offset:16384
	ds_read_b128 v[100:103], v112 offset:16400
	v_add_f32_e32 v140, v136, v137
	v_pk_mul_f32 v[128:129], v[78:79], v[104:105] op_sel_hi:[1,0]
	s_nop 0
	v_add_f32_dpp v140, v140, v140 row_half_mirror row_mask:0xf bank_mask:0xf
	v_pk_mul_f32 v[130:131], v[80:81], v[104:105] op_sel_hi:[1,0]
	v_pk_mul_f32 v[132:133], v[82:83], v[104:105] op_sel_hi:[1,0]
	v_pk_mul_f32 v[134:135], v[84:85], v[104:105] op_sel_hi:[1,0]
	ds_read_b128 v[78:81], v112 offset:12544
	ds_read_b128 v[82:85], v112 offset:12560
	ds_read_b32 v104, v108 offset:20608
	v_add_f32_dpp v140, v140, v140 quad_perm:[1,0,3,2] row_mask:0xf bank_mask:0xf
	v_pk_fma_f32 v[128:129], v[22:23], v[38:39], v[128:129]
	v_pk_fma_f32 v[130:131], v[24:25], v[40:41], v[130:131]
	v_pk_fma_f32 v[132:133], v[26:27], v[42:43], v[132:133]
	v_add_f32_dpp v140, v140, v140 quad_perm:[2,3,0,1] row_mask:0xf bank_mask:0xf
	v_pk_fma_f32 v[134:135], v[28:29], v[44:45], v[134:135]
	ds_read_b128 v[38:41], v112 offset:4352
	ds_read_b128 v[42:45], v112 offset:4368
	s_waitcnt lgkmcnt(9)
	v_pk_fma_f32 v[22:23], v[140:141], v[70:71], v[128:129] op_sel_hi:[0,1,1] neg_lo:[1,0,0] neg_hi:[1,0,0]
	v_pk_fma_f32 v[24:25], v[140:141], v[72:73], v[130:131] op_sel_hi:[0,1,1] neg_lo:[1,0,0] neg_hi:[1,0,0]
	v_pk_fma_f32 v[26:27], v[140:141], v[74:75], v[132:133] op_sel_hi:[0,1,1] neg_lo:[1,0,0] neg_hi:[1,0,0]
	v_pk_fma_f32 v[28:29], v[140:141], v[76:77], v[134:135] op_sel_hi:[0,1,1] neg_lo:[1,0,0] neg_hi:[1,0,0]
	ds_read_b128 v[70:73], v112 offset:8448
	ds_read_b128 v[74:77], v112 offset:8464
	s_waitcnt lgkmcnt(2)
	v_pk_mul_f32 v[136:137], v[22:23], v[30:31]
	v_pk_mul_f32 v[138:139], v[22:23], v[96:97]
	v_pk_fma_f32 v[136:137], v[24:25], v[32:33], v[136:137]
	v_pk_fma_f32 v[138:139], v[24:25], v[98:99], v[138:139]
	v_pk_fma_f32 v[136:137], v[26:27], v[34:35], v[136:137]
	v_pk_fma_f32 v[138:139], v[26:27], v[100:101], v[138:139]
	v_pk_fma_f32 v[136:137], v[28:29], v[36:37], v[136:137]
	v_pk_fma_f32 v[138:139], v[28:29], v[102:103], v[138:139]
	ds_read_b128 v[30:33], v112 offset:512
	ds_read_b128 v[34:37], v112 offset:528
	ds_read_b128 v[96:99], v112 offset:16640
	ds_read_b128 v[100:103], v112 offset:16656
	v_add_f32_e32 v140, v136, v137
	v_add_f32_e32 v142, v138, v139
	v_pk_mul_f32 v[128:129], v[78:79], v[104:105] op_sel_hi:[1,0]
	v_add_f32_dpp v140, v140, v140 row_half_mirror row_mask:0xf bank_mask:0xf
	v_add_f32_dpp v142, v142, v142 row_half_mirror row_mask:0xf bank_mask:0xf
	v_pk_mul_f32 v[130:131], v[80:81], v[104:105] op_sel_hi:[1,0]
	v_pk_mul_f32 v[132:133], v[82:83], v[104:105] op_sel_hi:[1,0]
	v_add_f32_dpp v140, v140, v140 quad_perm:[1,0,3,2] row_mask:0xf bank_mask:0xf
	v_add_f32_dpp v142, v142, v142 quad_perm:[1,0,3,2] row_mask:0xf bank_mask:0xf
	v_pk_mul_f32 v[134:135], v[84:85], v[104:105] op_sel_hi:[1,0]
	ds_read_b128 v[78:81], v112 offset:12800
	ds_read_b128 v[82:85], v112 offset:12816
	ds_read_b32 v104, v108 offset:20736
	v_pk_fma_f32 v[128:129], v[22:23], v[38:39], v[128:129]
	v_add_f32_dpp v140, v140, v140 quad_perm:[2,3,0,1] row_mask:0xf bank_mask:0xf
	v_add_f32_dpp v142, v142, v142 quad_perm:[2,3,0,1] row_mask:0xf bank_mask:0xf
	v_pk_fma_f32 v[130:131], v[24:25], v[40:41], v[130:131]
	v_pk_fma_f32 v[132:133], v[26:27], v[42:43], v[132:133]
	v_pk_fma_f32 v[134:135], v[28:29], v[44:45], v[134:135]
	ds_read_b128 v[38:41], v112 offset:4608
	ds_read_b128 v[42:45], v112 offset:4624
	s_waitcnt lgkmcnt(9)
	v_pk_fma_f32 v[22:23], v[140:141], v[70:71], v[128:129] op_sel_hi:[0,1,1] neg_lo:[1,0,0] neg_hi:[1,0,0]
	v_pk_fma_f32 v[24:25], v[140:141], v[72:73], v[130:131] op_sel_hi:[0,1,1] neg_lo:[1,0,0] neg_hi:[1,0,0]
	v_pk_fma_f32 v[26:27], v[140:141], v[74:75], v[132:133] op_sel_hi:[0,1,1] neg_lo:[1,0,0] neg_hi:[1,0,0]
	v_pk_fma_f32 v[28:29], v[140:141], v[76:77], v[134:135] op_sel_hi:[0,1,1] neg_lo:[1,0,0] neg_hi:[1,0,0]
	ds_read_b128 v[70:73], v112 offset:8704
	ds_read_b128 v[74:77], v112 offset:8720
	ds_write_b32 v108, v142 offset:24576
	s_waitcnt lgkmcnt(3)
	v_pk_mul_f32 v[136:137], v[22:23], v[30:31]
	v_pk_mul_f32 v[138:139], v[22:23], v[96:97]
	v_pk_fma_f32 v[136:137], v[24:25], v[32:33], v[136:137]
	v_pk_fma_f32 v[138:139], v[24:25], v[98:99], v[138:139]
	v_pk_fma_f32 v[136:137], v[26:27], v[34:35], v[136:137]
	v_pk_fma_f32 v[138:139], v[26:27], v[100:101], v[138:139]
	v_pk_fma_f32 v[136:137], v[28:29], v[36:37], v[136:137]
	v_pk_fma_f32 v[138:139], v[28:29], v[102:103], v[138:139]
	ds_read_b128 v[30:33], v112 offset:768
	ds_read_b128 v[34:37], v112 offset:784
	ds_read_b128 v[96:99], v112 offset:16896
	ds_read_b128 v[100:103], v112 offset:16912
	v_add_f32_e32 v140, v136, v137
	v_add_f32_e32 v142, v138, v139
	v_pk_mul_f32 v[128:129], v[78:79], v[104:105] op_sel_hi:[1,0]
	v_add_f32_dpp v140, v140, v140 row_half_mirror row_mask:0xf bank_mask:0xf
	v_add_f32_dpp v142, v142, v142 row_half_mirror row_mask:0xf bank_mask:0xf
	v_pk_mul_f32 v[130:131], v[80:81], v[104:105] op_sel_hi:[1,0]
	v_pk_mul_f32 v[132:133], v[82:83], v[104:105] op_sel_hi:[1,0]
	v_add_f32_dpp v140, v140, v140 quad_perm:[1,0,3,2] row_mask:0xf bank_mask:0xf
	v_add_f32_dpp v142, v142, v142 quad_perm:[1,0,3,2] row_mask:0xf bank_mask:0xf
	v_pk_mul_f32 v[134:135], v[84:85], v[104:105] op_sel_hi:[1,0]
	ds_read_b128 v[78:81], v112 offset:13056
	ds_read_b128 v[82:85], v112 offset:13072
	ds_read_b32 v104, v108 offset:20864
	v_pk_fma_f32 v[128:129], v[22:23], v[38:39], v[128:129]
	v_add_f32_dpp v140, v140, v140 quad_perm:[2,3,0,1] row_mask:0xf bank_mask:0xf
	v_add_f32_dpp v142, v142, v142 quad_perm:[2,3,0,1] row_mask:0xf bank_mask:0xf
	v_pk_fma_f32 v[130:131], v[24:25], v[40:41], v[130:131]
	v_pk_fma_f32 v[132:133], v[26:27], v[42:43], v[132:133]
	v_pk_fma_f32 v[134:135], v[28:29], v[44:45], v[134:135]
	ds_read_b128 v[38:41], v112 offset:4864
	ds_read_b128 v[42:45], v112 offset:4880
	s_waitcnt lgkmcnt(10)
	v_pk_fma_f32 v[22:23], v[140:141], v[70:71], v[128:129] op_sel_hi:[0,1,1] neg_lo:[1,0,0] neg_hi:[1,0,0]
	v_pk_fma_f32 v[24:25], v[140:141], v[72:73], v[130:131] op_sel_hi:[0,1,1] neg_lo:[1,0,0] neg_hi:[1,0,0]
	v_pk_fma_f32 v[26:27], v[140:141], v[74:75], v[132:133] op_sel_hi:[0,1,1] neg_lo:[1,0,0] neg_hi:[1,0,0]
	v_pk_fma_f32 v[28:29], v[140:141], v[76:77], v[134:135] op_sel_hi:[0,1,1] neg_lo:[1,0,0] neg_hi:[1,0,0]
	ds_read_b128 v[70:73], v112 offset:8960
	ds_read_b128 v[74:77], v112 offset:8976
	ds_write_b32 v108, v142 offset:24704
	s_waitcnt lgkmcnt(3)
	v_pk_mul_f32 v[136:137], v[22:23], v[30:31]
	v_pk_mul_f32 v[138:139], v[22:23], v[96:97]
	v_pk_fma_f32 v[136:137], v[24:25], v[32:33], v[136:137]
	v_pk_fma_f32 v[138:139], v[24:25], v[98:99], v[138:139]
	v_pk_fma_f32 v[136:137], v[26:27], v[34:35], v[136:137]
	v_pk_fma_f32 v[138:139], v[26:27], v[100:101], v[138:139]
	v_pk_fma_f32 v[136:137], v[28:29], v[36:37], v[136:137]
	v_pk_fma_f32 v[138:139], v[28:29], v[102:103], v[138:139]
	ds_read_b128 v[30:33], v112 offset:1024
	ds_read_b128 v[34:37], v112 offset:1040
	ds_read_b128 v[96:99], v112 offset:17152
	ds_read_b128 v[100:103], v112 offset:17168
	v_add_f32_e32 v140, v136, v137
	v_add_f32_e32 v142, v138, v139
	v_pk_mul_f32 v[128:129], v[78:79], v[104:105] op_sel_hi:[1,0]
	v_add_f32_dpp v140, v140, v140 row_half_mirror row_mask:0xf bank_mask:0xf
	v_add_f32_dpp v142, v142, v142 row_half_mirror row_mask:0xf bank_mask:0xf
	v_pk_mul_f32 v[130:131], v[80:81], v[104:105] op_sel_hi:[1,0]
	v_pk_mul_f32 v[132:133], v[82:83], v[104:105] op_sel_hi:[1,0]
	v_add_f32_dpp v140, v140, v140 quad_perm:[1,0,3,2] row_mask:0xf bank_mask:0xf
	v_add_f32_dpp v142, v142, v142 quad_perm:[1,0,3,2] row_mask:0xf bank_mask:0xf
	v_pk_mul_f32 v[134:135], v[84:85], v[104:105] op_sel_hi:[1,0]
	ds_read_b128 v[78:81], v112 offset:13312
	ds_read_b128 v[82:85], v112 offset:13328
	ds_read_b32 v104, v108 offset:20992
	v_pk_fma_f32 v[128:129], v[22:23], v[38:39], v[128:129]
	v_add_f32_dpp v140, v140, v140 quad_perm:[2,3,0,1] row_mask:0xf bank_mask:0xf
	v_add_f32_dpp v142, v142, v142 quad_perm:[2,3,0,1] row_mask:0xf bank_mask:0xf
	v_pk_fma_f32 v[130:131], v[24:25], v[40:41], v[130:131]
	v_pk_fma_f32 v[132:133], v[26:27], v[42:43], v[132:133]
	v_pk_fma_f32 v[134:135], v[28:29], v[44:45], v[134:135]
	ds_read_b128 v[38:41], v112 offset:5120
	ds_read_b128 v[42:45], v112 offset:5136
	s_waitcnt lgkmcnt(10)
	v_pk_fma_f32 v[22:23], v[140:141], v[70:71], v[128:129] op_sel_hi:[0,1,1] neg_lo:[1,0,0] neg_hi:[1,0,0]
	v_pk_fma_f32 v[24:25], v[140:141], v[72:73], v[130:131] op_sel_hi:[0,1,1] neg_lo:[1,0,0] neg_hi:[1,0,0]
	v_pk_fma_f32 v[26:27], v[140:141], v[74:75], v[132:133] op_sel_hi:[0,1,1] neg_lo:[1,0,0] neg_hi:[1,0,0]
	v_pk_fma_f32 v[28:29], v[140:141], v[76:77], v[134:135] op_sel_hi:[0,1,1] neg_lo:[1,0,0] neg_hi:[1,0,0]
	ds_read_b128 v[70:73], v112 offset:9216
	ds_read_b128 v[74:77], v112 offset:9232
	ds_write_b32 v108, v142 offset:24832
	s_waitcnt lgkmcnt(3)
	v_pk_mul_f32 v[136:137], v[22:23], v[30:31]
	v_pk_mul_f32 v[138:139], v[22:23], v[96:97]
	v_pk_fma_f32 v[136:137], v[24:25], v[32:33], v[136:137]
	v_pk_fma_f32 v[138:139], v[24:25], v[98:99], v[138:139]
	v_pk_fma_f32 v[136:137], v[26:27], v[34:35], v[136:137]
	v_pk_fma_f32 v[138:139], v[26:27], v[100:101], v[138:139]
	v_pk_fma_f32 v[136:137], v[28:29], v[36:37], v[136:137]
	v_pk_fma_f32 v[138:139], v[28:29], v[102:103], v[138:139]
	ds_read_b128 v[30:33], v112 offset:1280
	ds_read_b128 v[34:37], v112 offset:1296
	ds_read_b128 v[96:99], v112 offset:17408
	ds_read_b128 v[100:103], v112 offset:17424
	v_add_f32_e32 v140, v136, v137
	v_add_f32_e32 v142, v138, v139
	v_pk_mul_f32 v[128:129], v[78:79], v[104:105] op_sel_hi:[1,0]
	v_add_f32_dpp v140, v140, v140 row_half_mirror row_mask:0xf bank_mask:0xf
	v_add_f32_dpp v142, v142, v142 row_half_mirror row_mask:0xf bank_mask:0xf
	v_pk_mul_f32 v[130:131], v[80:81], v[104:105] op_sel_hi:[1,0]
	v_pk_mul_f32 v[132:133], v[82:83], v[104:105] op_sel_hi:[1,0]
	v_add_f32_dpp v140, v140, v140 quad_perm:[1,0,3,2] row_mask:0xf bank_mask:0xf
	v_add_f32_dpp v142, v142, v142 quad_perm:[1,0,3,2] row_mask:0xf bank_mask:0xf
	v_pk_mul_f32 v[134:135], v[84:85], v[104:105] op_sel_hi:[1,0]
	ds_read_b128 v[78:81], v112 offset:13568
	ds_read_b128 v[82:85], v112 offset:13584
	ds_read_b32 v104, v108 offset:21120
	v_pk_fma_f32 v[128:129], v[22:23], v[38:39], v[128:129]
	v_add_f32_dpp v140, v140, v140 quad_perm:[2,3,0,1] row_mask:0xf bank_mask:0xf
	v_add_f32_dpp v142, v142, v142 quad_perm:[2,3,0,1] row_mask:0xf bank_mask:0xf
	v_pk_fma_f32 v[130:131], v[24:25], v[40:41], v[130:131]
	v_pk_fma_f32 v[132:133], v[26:27], v[42:43], v[132:133]
	v_pk_fma_f32 v[134:135], v[28:29], v[44:45], v[134:135]
	ds_read_b128 v[38:41], v112 offset:5376
	ds_read_b128 v[42:45], v112 offset:5392
	s_waitcnt lgkmcnt(10)
	v_pk_fma_f32 v[22:23], v[140:141], v[70:71], v[128:129] op_sel_hi:[0,1,1] neg_lo:[1,0,0] neg_hi:[1,0,0]
	v_pk_fma_f32 v[24:25], v[140:141], v[72:73], v[130:131] op_sel_hi:[0,1,1] neg_lo:[1,0,0] neg_hi:[1,0,0]
	v_pk_fma_f32 v[26:27], v[140:141], v[74:75], v[132:133] op_sel_hi:[0,1,1] neg_lo:[1,0,0] neg_hi:[1,0,0]
	v_pk_fma_f32 v[28:29], v[140:141], v[76:77], v[134:135] op_sel_hi:[0,1,1] neg_lo:[1,0,0] neg_hi:[1,0,0]
	ds_read_b128 v[70:73], v112 offset:9472
	ds_read_b128 v[74:77], v112 offset:9488
	ds_write_b32 v108, v142 offset:24960
	s_waitcnt lgkmcnt(3)
	v_pk_mul_f32 v[136:137], v[22:23], v[30:31]
	v_pk_mul_f32 v[138:139], v[22:23], v[96:97]
	v_pk_fma_f32 v[136:137], v[24:25], v[32:33], v[136:137]
	v_pk_fma_f32 v[138:139], v[24:25], v[98:99], v[138:139]
	v_pk_fma_f32 v[136:137], v[26:27], v[34:35], v[136:137]
	v_pk_fma_f32 v[138:139], v[26:27], v[100:101], v[138:139]
	v_pk_fma_f32 v[136:137], v[28:29], v[36:37], v[136:137]
	v_pk_fma_f32 v[138:139], v[28:29], v[102:103], v[138:139]
	ds_read_b128 v[30:33], v112 offset:1536
	ds_read_b128 v[34:37], v112 offset:1552
	ds_read_b128 v[96:99], v112 offset:17664
	ds_read_b128 v[100:103], v112 offset:17680
	v_add_f32_e32 v140, v136, v137
	v_add_f32_e32 v142, v138, v139
	v_pk_mul_f32 v[128:129], v[78:79], v[104:105] op_sel_hi:[1,0]
	v_add_f32_dpp v140, v140, v140 row_half_mirror row_mask:0xf bank_mask:0xf
	v_add_f32_dpp v142, v142, v142 row_half_mirror row_mask:0xf bank_mask:0xf
	v_pk_mul_f32 v[130:131], v[80:81], v[104:105] op_sel_hi:[1,0]
	v_pk_mul_f32 v[132:133], v[82:83], v[104:105] op_sel_hi:[1,0]
	v_add_f32_dpp v140, v140, v140 quad_perm:[1,0,3,2] row_mask:0xf bank_mask:0xf
	v_add_f32_dpp v142, v142, v142 quad_perm:[1,0,3,2] row_mask:0xf bank_mask:0xf
	v_pk_mul_f32 v[134:135], v[84:85], v[104:105] op_sel_hi:[1,0]
	ds_read_b128 v[78:81], v112 offset:13824
	ds_read_b128 v[82:85], v112 offset:13840
	ds_read_b32 v104, v108 offset:21248
	v_pk_fma_f32 v[128:129], v[22:23], v[38:39], v[128:129]
	v_add_f32_dpp v140, v140, v140 quad_perm:[2,3,0,1] row_mask:0xf bank_mask:0xf
	v_add_f32_dpp v142, v142, v142 quad_perm:[2,3,0,1] row_mask:0xf bank_mask:0xf
	v_pk_fma_f32 v[130:131], v[24:25], v[40:41], v[130:131]
	v_pk_fma_f32 v[132:133], v[26:27], v[42:43], v[132:133]
	v_pk_fma_f32 v[134:135], v[28:29], v[44:45], v[134:135]
	ds_read_b128 v[38:41], v112 offset:5632
	ds_read_b128 v[42:45], v112 offset:5648
	s_waitcnt lgkmcnt(10)
	v_pk_fma_f32 v[22:23], v[140:141], v[70:71], v[128:129] op_sel_hi:[0,1,1] neg_lo:[1,0,0] neg_hi:[1,0,0]
	v_pk_fma_f32 v[24:25], v[140:141], v[72:73], v[130:131] op_sel_hi:[0,1,1] neg_lo:[1,0,0] neg_hi:[1,0,0]
	v_pk_fma_f32 v[26:27], v[140:141], v[74:75], v[132:133] op_sel_hi:[0,1,1] neg_lo:[1,0,0] neg_hi:[1,0,0]
	v_pk_fma_f32 v[28:29], v[140:141], v[76:77], v[134:135] op_sel_hi:[0,1,1] neg_lo:[1,0,0] neg_hi:[1,0,0]
	ds_read_b128 v[70:73], v112 offset:9728
	ds_read_b128 v[74:77], v112 offset:9744
	ds_write_b32 v108, v142 offset:25088
	s_waitcnt lgkmcnt(3)
	v_pk_mul_f32 v[136:137], v[22:23], v[30:31]
	v_pk_mul_f32 v[138:139], v[22:23], v[96:97]
	v_pk_fma_f32 v[136:137], v[24:25], v[32:33], v[136:137]
	v_pk_fma_f32 v[138:139], v[24:25], v[98:99], v[138:139]
	v_pk_fma_f32 v[136:137], v[26:27], v[34:35], v[136:137]
	v_pk_fma_f32 v[138:139], v[26:27], v[100:101], v[138:139]
	v_pk_fma_f32 v[136:137], v[28:29], v[36:37], v[136:137]
	v_pk_fma_f32 v[138:139], v[28:29], v[102:103], v[138:139]
	ds_read_b128 v[30:33], v112 offset:1792
	ds_read_b128 v[34:37], v112 offset:1808
	ds_read_b128 v[96:99], v112 offset:17920
	ds_read_b128 v[100:103], v112 offset:17936
	v_add_f32_e32 v140, v136, v137
	v_add_f32_e32 v142, v138, v139
	v_pk_mul_f32 v[128:129], v[78:79], v[104:105] op_sel_hi:[1,0]
	v_add_f32_dpp v140, v140, v140 row_half_mirror row_mask:0xf bank_mask:0xf
	v_add_f32_dpp v142, v142, v142 row_half_mirror row_mask:0xf bank_mask:0xf
	v_pk_mul_f32 v[130:131], v[80:81], v[104:105] op_sel_hi:[1,0]
	v_pk_mul_f32 v[132:133], v[82:83], v[104:105] op_sel_hi:[1,0]
	v_add_f32_dpp v140, v140, v140 quad_perm:[1,0,3,2] row_mask:0xf bank_mask:0xf
	v_add_f32_dpp v142, v142, v142 quad_perm:[1,0,3,2] row_mask:0xf bank_mask:0xf
	v_pk_mul_f32 v[134:135], v[84:85], v[104:105] op_sel_hi:[1,0]
	ds_read_b128 v[78:81], v112 offset:14080
	ds_read_b128 v[82:85], v112 offset:14096
	ds_read_b32 v104, v108 offset:21376
	v_pk_fma_f32 v[128:129], v[22:23], v[38:39], v[128:129]
	v_add_f32_dpp v140, v140, v140 quad_perm:[2,3,0,1] row_mask:0xf bank_mask:0xf
	v_add_f32_dpp v142, v142, v142 quad_perm:[2,3,0,1] row_mask:0xf bank_mask:0xf
	v_pk_fma_f32 v[130:131], v[24:25], v[40:41], v[130:131]
	v_pk_fma_f32 v[132:133], v[26:27], v[42:43], v[132:133]
	v_pk_fma_f32 v[134:135], v[28:29], v[44:45], v[134:135]
	ds_read_b128 v[38:41], v112 offset:5888
	ds_read_b128 v[42:45], v112 offset:5904
	s_waitcnt lgkmcnt(10)
	v_pk_fma_f32 v[22:23], v[140:141], v[70:71], v[128:129] op_sel_hi:[0,1,1] neg_lo:[1,0,0] neg_hi:[1,0,0]
	v_pk_fma_f32 v[24:25], v[140:141], v[72:73], v[130:131] op_sel_hi:[0,1,1] neg_lo:[1,0,0] neg_hi:[1,0,0]
	v_pk_fma_f32 v[26:27], v[140:141], v[74:75], v[132:133] op_sel_hi:[0,1,1] neg_lo:[1,0,0] neg_hi:[1,0,0]
	v_pk_fma_f32 v[28:29], v[140:141], v[76:77], v[134:135] op_sel_hi:[0,1,1] neg_lo:[1,0,0] neg_hi:[1,0,0]
	ds_read_b128 v[70:73], v112 offset:9984
	ds_read_b128 v[74:77], v112 offset:10000
	ds_write_b32 v108, v142 offset:25216
	s_waitcnt lgkmcnt(3)
	v_pk_mul_f32 v[136:137], v[22:23], v[30:31]
	v_pk_mul_f32 v[138:139], v[22:23], v[96:97]
	v_pk_fma_f32 v[136:137], v[24:25], v[32:33], v[136:137]
	v_pk_fma_f32 v[138:139], v[24:25], v[98:99], v[138:139]
	v_pk_fma_f32 v[136:137], v[26:27], v[34:35], v[136:137]
	v_pk_fma_f32 v[138:139], v[26:27], v[100:101], v[138:139]
	v_pk_fma_f32 v[136:137], v[28:29], v[36:37], v[136:137]
	v_pk_fma_f32 v[138:139], v[28:29], v[102:103], v[138:139]
	ds_read_b128 v[30:33], v112 offset:2048
	ds_read_b128 v[34:37], v112 offset:2064
	ds_read_b128 v[96:99], v112 offset:18176
	ds_read_b128 v[100:103], v112 offset:18192
	v_add_f32_e32 v140, v136, v137
	v_add_f32_e32 v142, v138, v139
	v_pk_mul_f32 v[128:129], v[78:79], v[104:105] op_sel_hi:[1,0]
	v_add_f32_dpp v140, v140, v140 row_half_mirror row_mask:0xf bank_mask:0xf
	v_add_f32_dpp v142, v142, v142 row_half_mirror row_mask:0xf bank_mask:0xf
	v_pk_mul_f32 v[130:131], v[80:81], v[104:105] op_sel_hi:[1,0]
	v_pk_mul_f32 v[132:133], v[82:83], v[104:105] op_sel_hi:[1,0]
	v_add_f32_dpp v140, v140, v140 quad_perm:[1,0,3,2] row_mask:0xf bank_mask:0xf
	v_add_f32_dpp v142, v142, v142 quad_perm:[1,0,3,2] row_mask:0xf bank_mask:0xf
	v_pk_mul_f32 v[134:135], v[84:85], v[104:105] op_sel_hi:[1,0]
	ds_read_b128 v[78:81], v112 offset:14336
	ds_read_b128 v[82:85], v112 offset:14352
	ds_read_b32 v104, v108 offset:21504
	v_pk_fma_f32 v[128:129], v[22:23], v[38:39], v[128:129]
	v_add_f32_dpp v140, v140, v140 quad_perm:[2,3,0,1] row_mask:0xf bank_mask:0xf
	v_add_f32_dpp v142, v142, v142 quad_perm:[2,3,0,1] row_mask:0xf bank_mask:0xf
	v_pk_fma_f32 v[130:131], v[24:25], v[40:41], v[130:131]
	v_pk_fma_f32 v[132:133], v[26:27], v[42:43], v[132:133]
	v_pk_fma_f32 v[134:135], v[28:29], v[44:45], v[134:135]
	ds_read_b128 v[38:41], v112 offset:6144
	ds_read_b128 v[42:45], v112 offset:6160
	s_waitcnt lgkmcnt(10)
	v_pk_fma_f32 v[22:23], v[140:141], v[70:71], v[128:129] op_sel_hi:[0,1,1] neg_lo:[1,0,0] neg_hi:[1,0,0]
	v_pk_fma_f32 v[24:25], v[140:141], v[72:73], v[130:131] op_sel_hi:[0,1,1] neg_lo:[1,0,0] neg_hi:[1,0,0]
	v_pk_fma_f32 v[26:27], v[140:141], v[74:75], v[132:133] op_sel_hi:[0,1,1] neg_lo:[1,0,0] neg_hi:[1,0,0]
	v_pk_fma_f32 v[28:29], v[140:141], v[76:77], v[134:135] op_sel_hi:[0,1,1] neg_lo:[1,0,0] neg_hi:[1,0,0]
	ds_read_b128 v[70:73], v112 offset:10240
	ds_read_b128 v[74:77], v112 offset:10256
	ds_write_b32 v108, v142 offset:25344
	s_waitcnt lgkmcnt(3)
	v_pk_mul_f32 v[136:137], v[22:23], v[30:31]
	v_pk_mul_f32 v[138:139], v[22:23], v[96:97]
	v_pk_fma_f32 v[136:137], v[24:25], v[32:33], v[136:137]
	v_pk_fma_f32 v[138:139], v[24:25], v[98:99], v[138:139]
	v_pk_fma_f32 v[136:137], v[26:27], v[34:35], v[136:137]
	v_pk_fma_f32 v[138:139], v[26:27], v[100:101], v[138:139]
	v_pk_fma_f32 v[136:137], v[28:29], v[36:37], v[136:137]
	v_pk_fma_f32 v[138:139], v[28:29], v[102:103], v[138:139]
	ds_read_b128 v[30:33], v112 offset:2304
	ds_read_b128 v[34:37], v112 offset:2320
	ds_read_b128 v[96:99], v112 offset:18432
	ds_read_b128 v[100:103], v112 offset:18448
	v_add_f32_e32 v140, v136, v137
	v_add_f32_e32 v142, v138, v139
	v_pk_mul_f32 v[128:129], v[78:79], v[104:105] op_sel_hi:[1,0]
	v_add_f32_dpp v140, v140, v140 row_half_mirror row_mask:0xf bank_mask:0xf
	v_add_f32_dpp v142, v142, v142 row_half_mirror row_mask:0xf bank_mask:0xf
	v_pk_mul_f32 v[130:131], v[80:81], v[104:105] op_sel_hi:[1,0]
	v_pk_mul_f32 v[132:133], v[82:83], v[104:105] op_sel_hi:[1,0]
	v_add_f32_dpp v140, v140, v140 quad_perm:[1,0,3,2] row_mask:0xf bank_mask:0xf
	v_add_f32_dpp v142, v142, v142 quad_perm:[1,0,3,2] row_mask:0xf bank_mask:0xf
	v_pk_mul_f32 v[134:135], v[84:85], v[104:105] op_sel_hi:[1,0]
	ds_read_b128 v[78:81], v112 offset:14592
	ds_read_b128 v[82:85], v112 offset:14608
	ds_read_b32 v104, v108 offset:21632
	v_pk_fma_f32 v[128:129], v[22:23], v[38:39], v[128:129]
	v_add_f32_dpp v140, v140, v140 quad_perm:[2,3,0,1] row_mask:0xf bank_mask:0xf
	v_add_f32_dpp v142, v142, v142 quad_perm:[2,3,0,1] row_mask:0xf bank_mask:0xf
	v_pk_fma_f32 v[130:131], v[24:25], v[40:41], v[130:131]
	v_pk_fma_f32 v[132:133], v[26:27], v[42:43], v[132:133]
	v_pk_fma_f32 v[134:135], v[28:29], v[44:45], v[134:135]
	ds_read_b128 v[38:41], v112 offset:6400
	ds_read_b128 v[42:45], v112 offset:6416
	s_waitcnt lgkmcnt(10)
	v_pk_fma_f32 v[22:23], v[140:141], v[70:71], v[128:129] op_sel_hi:[0,1,1] neg_lo:[1,0,0] neg_hi:[1,0,0]
	v_pk_fma_f32 v[24:25], v[140:141], v[72:73], v[130:131] op_sel_hi:[0,1,1] neg_lo:[1,0,0] neg_hi:[1,0,0]
	v_pk_fma_f32 v[26:27], v[140:141], v[74:75], v[132:133] op_sel_hi:[0,1,1] neg_lo:[1,0,0] neg_hi:[1,0,0]
	v_pk_fma_f32 v[28:29], v[140:141], v[76:77], v[134:135] op_sel_hi:[0,1,1] neg_lo:[1,0,0] neg_hi:[1,0,0]
	ds_read_b128 v[70:73], v112 offset:10496
	ds_read_b128 v[74:77], v112 offset:10512
	ds_write_b32 v108, v142 offset:25472
	s_waitcnt lgkmcnt(3)
	v_pk_mul_f32 v[136:137], v[22:23], v[30:31]
	v_pk_mul_f32 v[138:139], v[22:23], v[96:97]
	v_pk_fma_f32 v[136:137], v[24:25], v[32:33], v[136:137]
	v_pk_fma_f32 v[138:139], v[24:25], v[98:99], v[138:139]
	v_pk_fma_f32 v[136:137], v[26:27], v[34:35], v[136:137]
	v_pk_fma_f32 v[138:139], v[26:27], v[100:101], v[138:139]
	v_pk_fma_f32 v[136:137], v[28:29], v[36:37], v[136:137]
	v_pk_fma_f32 v[138:139], v[28:29], v[102:103], v[138:139]
	ds_read_b128 v[30:33], v112 offset:2560
	ds_read_b128 v[34:37], v112 offset:2576
	ds_read_b128 v[96:99], v112 offset:18688
	ds_read_b128 v[100:103], v112 offset:18704
	v_add_f32_e32 v140, v136, v137
	v_add_f32_e32 v142, v138, v139
	v_pk_mul_f32 v[128:129], v[78:79], v[104:105] op_sel_hi:[1,0]
	v_add_f32_dpp v140, v140, v140 row_half_mirror row_mask:0xf bank_mask:0xf
	v_add_f32_dpp v142, v142, v142 row_half_mirror row_mask:0xf bank_mask:0xf
	v_pk_mul_f32 v[130:131], v[80:81], v[104:105] op_sel_hi:[1,0]
	v_pk_mul_f32 v[132:133], v[82:83], v[104:105] op_sel_hi:[1,0]
	v_add_f32_dpp v140, v140, v140 quad_perm:[1,0,3,2] row_mask:0xf bank_mask:0xf
	v_add_f32_dpp v142, v142, v142 quad_perm:[1,0,3,2] row_mask:0xf bank_mask:0xf
	v_pk_mul_f32 v[134:135], v[84:85], v[104:105] op_sel_hi:[1,0]
	ds_read_b128 v[78:81], v112 offset:14848
	ds_read_b128 v[82:85], v112 offset:14864
	ds_read_b32 v104, v108 offset:21760
	v_pk_fma_f32 v[128:129], v[22:23], v[38:39], v[128:129]
	v_add_f32_dpp v140, v140, v140 quad_perm:[2,3,0,1] row_mask:0xf bank_mask:0xf
	v_add_f32_dpp v142, v142, v142 quad_perm:[2,3,0,1] row_mask:0xf bank_mask:0xf
	v_pk_fma_f32 v[130:131], v[24:25], v[40:41], v[130:131]
	v_pk_fma_f32 v[132:133], v[26:27], v[42:43], v[132:133]
	v_pk_fma_f32 v[134:135], v[28:29], v[44:45], v[134:135]
	ds_read_b128 v[38:41], v112 offset:6656
	ds_read_b128 v[42:45], v112 offset:6672
	s_waitcnt lgkmcnt(10)
	v_pk_fma_f32 v[22:23], v[140:141], v[70:71], v[128:129] op_sel_hi:[0,1,1] neg_lo:[1,0,0] neg_hi:[1,0,0]
	v_pk_fma_f32 v[24:25], v[140:141], v[72:73], v[130:131] op_sel_hi:[0,1,1] neg_lo:[1,0,0] neg_hi:[1,0,0]
	v_pk_fma_f32 v[26:27], v[140:141], v[74:75], v[132:133] op_sel_hi:[0,1,1] neg_lo:[1,0,0] neg_hi:[1,0,0]
	v_pk_fma_f32 v[28:29], v[140:141], v[76:77], v[134:135] op_sel_hi:[0,1,1] neg_lo:[1,0,0] neg_hi:[1,0,0]
	ds_read_b128 v[70:73], v112 offset:10752
	ds_read_b128 v[74:77], v112 offset:10768
	ds_write_b32 v108, v142 offset:25600
	s_waitcnt lgkmcnt(3)
	v_pk_mul_f32 v[136:137], v[22:23], v[30:31]
	v_pk_mul_f32 v[138:139], v[22:23], v[96:97]
	v_pk_fma_f32 v[136:137], v[24:25], v[32:33], v[136:137]
	v_pk_fma_f32 v[138:139], v[24:25], v[98:99], v[138:139]
	v_pk_fma_f32 v[136:137], v[26:27], v[34:35], v[136:137]
	v_pk_fma_f32 v[138:139], v[26:27], v[100:101], v[138:139]
	v_pk_fma_f32 v[136:137], v[28:29], v[36:37], v[136:137]
	v_pk_fma_f32 v[138:139], v[28:29], v[102:103], v[138:139]
	ds_read_b128 v[30:33], v112 offset:2816
	ds_read_b128 v[34:37], v112 offset:2832
	ds_read_b128 v[96:99], v112 offset:18944
	ds_read_b128 v[100:103], v112 offset:18960
	v_add_f32_e32 v140, v136, v137
	v_add_f32_e32 v142, v138, v139
	v_pk_mul_f32 v[128:129], v[78:79], v[104:105] op_sel_hi:[1,0]
	v_add_f32_dpp v140, v140, v140 row_half_mirror row_mask:0xf bank_mask:0xf
	v_add_f32_dpp v142, v142, v142 row_half_mirror row_mask:0xf bank_mask:0xf
	v_pk_mul_f32 v[130:131], v[80:81], v[104:105] op_sel_hi:[1,0]
	v_pk_mul_f32 v[132:133], v[82:83], v[104:105] op_sel_hi:[1,0]
	v_add_f32_dpp v140, v140, v140 quad_perm:[1,0,3,2] row_mask:0xf bank_mask:0xf
	v_add_f32_dpp v142, v142, v142 quad_perm:[1,0,3,2] row_mask:0xf bank_mask:0xf
	v_pk_mul_f32 v[134:135], v[84:85], v[104:105] op_sel_hi:[1,0]
	ds_read_b128 v[78:81], v112 offset:15104
	ds_read_b128 v[82:85], v112 offset:15120
	ds_read_b32 v104, v108 offset:21888
	v_pk_fma_f32 v[128:129], v[22:23], v[38:39], v[128:129]
	v_add_f32_dpp v140, v140, v140 quad_perm:[2,3,0,1] row_mask:0xf bank_mask:0xf
	v_add_f32_dpp v142, v142, v142 quad_perm:[2,3,0,1] row_mask:0xf bank_mask:0xf
	v_pk_fma_f32 v[130:131], v[24:25], v[40:41], v[130:131]
	v_pk_fma_f32 v[132:133], v[26:27], v[42:43], v[132:133]
	v_pk_fma_f32 v[134:135], v[28:29], v[44:45], v[134:135]
	ds_read_b128 v[38:41], v112 offset:6912
	ds_read_b128 v[42:45], v112 offset:6928
	s_waitcnt lgkmcnt(10)
	v_pk_fma_f32 v[22:23], v[140:141], v[70:71], v[128:129] op_sel_hi:[0,1,1] neg_lo:[1,0,0] neg_hi:[1,0,0]
	v_pk_fma_f32 v[24:25], v[140:141], v[72:73], v[130:131] op_sel_hi:[0,1,1] neg_lo:[1,0,0] neg_hi:[1,0,0]
	v_pk_fma_f32 v[26:27], v[140:141], v[74:75], v[132:133] op_sel_hi:[0,1,1] neg_lo:[1,0,0] neg_hi:[1,0,0]
	v_pk_fma_f32 v[28:29], v[140:141], v[76:77], v[134:135] op_sel_hi:[0,1,1] neg_lo:[1,0,0] neg_hi:[1,0,0]
	ds_read_b128 v[70:73], v112 offset:11008
	ds_read_b128 v[74:77], v112 offset:11024
	ds_write_b32 v108, v142 offset:25728
	s_waitcnt lgkmcnt(3)
	v_pk_mul_f32 v[136:137], v[22:23], v[30:31]
	v_pk_mul_f32 v[138:139], v[22:23], v[96:97]
	v_pk_fma_f32 v[136:137], v[24:25], v[32:33], v[136:137]
	v_pk_fma_f32 v[138:139], v[24:25], v[98:99], v[138:139]
	v_pk_fma_f32 v[136:137], v[26:27], v[34:35], v[136:137]
	v_pk_fma_f32 v[138:139], v[26:27], v[100:101], v[138:139]
	v_pk_fma_f32 v[136:137], v[28:29], v[36:37], v[136:137]
	v_pk_fma_f32 v[138:139], v[28:29], v[102:103], v[138:139]
	ds_read_b128 v[30:33], v112 offset:3072
	ds_read_b128 v[34:37], v112 offset:3088
	ds_read_b128 v[96:99], v112 offset:19200
	ds_read_b128 v[100:103], v112 offset:19216
	v_add_f32_e32 v140, v136, v137
	v_add_f32_e32 v142, v138, v139
	v_pk_mul_f32 v[128:129], v[78:79], v[104:105] op_sel_hi:[1,0]
	v_add_f32_dpp v140, v140, v140 row_half_mirror row_mask:0xf bank_mask:0xf
	v_add_f32_dpp v142, v142, v142 row_half_mirror row_mask:0xf bank_mask:0xf
	v_pk_mul_f32 v[130:131], v[80:81], v[104:105] op_sel_hi:[1,0]
	v_pk_mul_f32 v[132:133], v[82:83], v[104:105] op_sel_hi:[1,0]
	v_add_f32_dpp v140, v140, v140 quad_perm:[1,0,3,2] row_mask:0xf bank_mask:0xf
	v_add_f32_dpp v142, v142, v142 quad_perm:[1,0,3,2] row_mask:0xf bank_mask:0xf
	v_pk_mul_f32 v[134:135], v[84:85], v[104:105] op_sel_hi:[1,0]
	ds_read_b128 v[78:81], v112 offset:15360
	ds_read_b128 v[82:85], v112 offset:15376
	ds_read_b32 v104, v108 offset:22016
	v_pk_fma_f32 v[128:129], v[22:23], v[38:39], v[128:129]
	v_add_f32_dpp v140, v140, v140 quad_perm:[2,3,0,1] row_mask:0xf bank_mask:0xf
	v_add_f32_dpp v142, v142, v142 quad_perm:[2,3,0,1] row_mask:0xf bank_mask:0xf
	v_pk_fma_f32 v[130:131], v[24:25], v[40:41], v[130:131]
	v_pk_fma_f32 v[132:133], v[26:27], v[42:43], v[132:133]
	v_pk_fma_f32 v[134:135], v[28:29], v[44:45], v[134:135]
	ds_read_b128 v[38:41], v112 offset:7168
	ds_read_b128 v[42:45], v112 offset:7184
	s_waitcnt lgkmcnt(10)
	v_pk_fma_f32 v[22:23], v[140:141], v[70:71], v[128:129] op_sel_hi:[0,1,1] neg_lo:[1,0,0] neg_hi:[1,0,0]
	v_pk_fma_f32 v[24:25], v[140:141], v[72:73], v[130:131] op_sel_hi:[0,1,1] neg_lo:[1,0,0] neg_hi:[1,0,0]
	v_pk_fma_f32 v[26:27], v[140:141], v[74:75], v[132:133] op_sel_hi:[0,1,1] neg_lo:[1,0,0] neg_hi:[1,0,0]
	v_pk_fma_f32 v[28:29], v[140:141], v[76:77], v[134:135] op_sel_hi:[0,1,1] neg_lo:[1,0,0] neg_hi:[1,0,0]
	ds_read_b128 v[70:73], v112 offset:11264
	ds_read_b128 v[74:77], v112 offset:11280
	ds_write_b32 v108, v142 offset:25856
	s_waitcnt lgkmcnt(3)
	v_pk_mul_f32 v[136:137], v[22:23], v[30:31]
	v_pk_mul_f32 v[138:139], v[22:23], v[96:97]
	v_pk_fma_f32 v[136:137], v[24:25], v[32:33], v[136:137]
	v_pk_fma_f32 v[138:139], v[24:25], v[98:99], v[138:139]
	v_pk_fma_f32 v[136:137], v[26:27], v[34:35], v[136:137]
	v_pk_fma_f32 v[138:139], v[26:27], v[100:101], v[138:139]
	v_pk_fma_f32 v[136:137], v[28:29], v[36:37], v[136:137]
	v_pk_fma_f32 v[138:139], v[28:29], v[102:103], v[138:139]
	ds_read_b128 v[30:33], v112 offset:3328
	ds_read_b128 v[34:37], v112 offset:3344
	ds_read_b128 v[96:99], v112 offset:19456
	ds_read_b128 v[100:103], v112 offset:19472
	v_add_f32_e32 v140, v136, v137
	v_add_f32_e32 v142, v138, v139
	v_pk_mul_f32 v[128:129], v[78:79], v[104:105] op_sel_hi:[1,0]
	v_add_f32_dpp v140, v140, v140 row_half_mirror row_mask:0xf bank_mask:0xf
	v_add_f32_dpp v142, v142, v142 row_half_mirror row_mask:0xf bank_mask:0xf
	v_pk_mul_f32 v[130:131], v[80:81], v[104:105] op_sel_hi:[1,0]
	v_pk_mul_f32 v[132:133], v[82:83], v[104:105] op_sel_hi:[1,0]
	v_add_f32_dpp v140, v140, v140 quad_perm:[1,0,3,2] row_mask:0xf bank_mask:0xf
	v_add_f32_dpp v142, v142, v142 quad_perm:[1,0,3,2] row_mask:0xf bank_mask:0xf
	v_pk_mul_f32 v[134:135], v[84:85], v[104:105] op_sel_hi:[1,0]
	ds_read_b128 v[78:81], v112 offset:15616
	ds_read_b128 v[82:85], v112 offset:15632
	ds_read_b32 v104, v108 offset:22144
	v_pk_fma_f32 v[128:129], v[22:23], v[38:39], v[128:129]
	v_add_f32_dpp v140, v140, v140 quad_perm:[2,3,0,1] row_mask:0xf bank_mask:0xf
	v_add_f32_dpp v142, v142, v142 quad_perm:[2,3,0,1] row_mask:0xf bank_mask:0xf
	v_pk_fma_f32 v[130:131], v[24:25], v[40:41], v[130:131]
	v_pk_fma_f32 v[132:133], v[26:27], v[42:43], v[132:133]
	v_pk_fma_f32 v[134:135], v[28:29], v[44:45], v[134:135]
	ds_read_b128 v[38:41], v112 offset:7424
	ds_read_b128 v[42:45], v112 offset:7440
	s_waitcnt lgkmcnt(10)
	v_pk_fma_f32 v[22:23], v[140:141], v[70:71], v[128:129] op_sel_hi:[0,1,1] neg_lo:[1,0,0] neg_hi:[1,0,0]
	v_pk_fma_f32 v[24:25], v[140:141], v[72:73], v[130:131] op_sel_hi:[0,1,1] neg_lo:[1,0,0] neg_hi:[1,0,0]
	v_pk_fma_f32 v[26:27], v[140:141], v[74:75], v[132:133] op_sel_hi:[0,1,1] neg_lo:[1,0,0] neg_hi:[1,0,0]
	v_pk_fma_f32 v[28:29], v[140:141], v[76:77], v[134:135] op_sel_hi:[0,1,1] neg_lo:[1,0,0] neg_hi:[1,0,0]
	ds_read_b128 v[70:73], v112 offset:11520
	ds_read_b128 v[74:77], v112 offset:11536
	ds_write_b32 v108, v142 offset:25984
	s_waitcnt lgkmcnt(3)
	v_pk_mul_f32 v[136:137], v[22:23], v[30:31]
	v_pk_mul_f32 v[138:139], v[22:23], v[96:97]
	v_pk_fma_f32 v[136:137], v[24:25], v[32:33], v[136:137]
	v_pk_fma_f32 v[138:139], v[24:25], v[98:99], v[138:139]
	v_pk_fma_f32 v[136:137], v[26:27], v[34:35], v[136:137]
	v_pk_fma_f32 v[138:139], v[26:27], v[100:101], v[138:139]
	v_pk_fma_f32 v[136:137], v[28:29], v[36:37], v[136:137]
	v_pk_fma_f32 v[138:139], v[28:29], v[102:103], v[138:139]
	ds_read_b128 v[30:33], v112 offset:3584
	ds_read_b128 v[34:37], v112 offset:3600
	ds_read_b128 v[96:99], v112 offset:19712
	ds_read_b128 v[100:103], v112 offset:19728
	v_add_f32_e32 v140, v136, v137
	v_add_f32_e32 v142, v138, v139
	v_pk_mul_f32 v[128:129], v[78:79], v[104:105] op_sel_hi:[1,0]
	v_add_f32_dpp v140, v140, v140 row_half_mirror row_mask:0xf bank_mask:0xf
	v_add_f32_dpp v142, v142, v142 row_half_mirror row_mask:0xf bank_mask:0xf
	v_pk_mul_f32 v[130:131], v[80:81], v[104:105] op_sel_hi:[1,0]
	v_pk_mul_f32 v[132:133], v[82:83], v[104:105] op_sel_hi:[1,0]
	v_add_f32_dpp v140, v140, v140 quad_perm:[1,0,3,2] row_mask:0xf bank_mask:0xf
	v_add_f32_dpp v142, v142, v142 quad_perm:[1,0,3,2] row_mask:0xf bank_mask:0xf
	v_pk_mul_f32 v[134:135], v[84:85], v[104:105] op_sel_hi:[1,0]
	ds_read_b128 v[78:81], v112 offset:15872
	ds_read_b128 v[82:85], v112 offset:15888
	ds_read_b32 v104, v108 offset:22272
	v_pk_fma_f32 v[128:129], v[22:23], v[38:39], v[128:129]
	v_add_f32_dpp v140, v140, v140 quad_perm:[2,3,0,1] row_mask:0xf bank_mask:0xf
	v_add_f32_dpp v142, v142, v142 quad_perm:[2,3,0,1] row_mask:0xf bank_mask:0xf
	v_pk_fma_f32 v[130:131], v[24:25], v[40:41], v[130:131]
	v_pk_fma_f32 v[132:133], v[26:27], v[42:43], v[132:133]
	v_pk_fma_f32 v[134:135], v[28:29], v[44:45], v[134:135]
	ds_read_b128 v[38:41], v112 offset:7680
	ds_read_b128 v[42:45], v112 offset:7696
	s_waitcnt lgkmcnt(10)
	v_pk_fma_f32 v[22:23], v[140:141], v[70:71], v[128:129] op_sel_hi:[0,1,1] neg_lo:[1,0,0] neg_hi:[1,0,0]
	v_pk_fma_f32 v[24:25], v[140:141], v[72:73], v[130:131] op_sel_hi:[0,1,1] neg_lo:[1,0,0] neg_hi:[1,0,0]
	v_pk_fma_f32 v[26:27], v[140:141], v[74:75], v[132:133] op_sel_hi:[0,1,1] neg_lo:[1,0,0] neg_hi:[1,0,0]
	v_pk_fma_f32 v[28:29], v[140:141], v[76:77], v[134:135] op_sel_hi:[0,1,1] neg_lo:[1,0,0] neg_hi:[1,0,0]
	ds_read_b128 v[70:73], v112 offset:11776
	ds_read_b128 v[74:77], v112 offset:11792
	ds_write_b32 v108, v142 offset:26112
	s_waitcnt lgkmcnt(3)
	v_pk_mul_f32 v[136:137], v[22:23], v[30:31]
	v_pk_mul_f32 v[138:139], v[22:23], v[96:97]
	v_pk_fma_f32 v[136:137], v[24:25], v[32:33], v[136:137]
	v_pk_fma_f32 v[138:139], v[24:25], v[98:99], v[138:139]
	v_pk_fma_f32 v[136:137], v[26:27], v[34:35], v[136:137]
	v_pk_fma_f32 v[138:139], v[26:27], v[100:101], v[138:139]
	v_pk_fma_f32 v[136:137], v[28:29], v[36:37], v[136:137]
	v_pk_fma_f32 v[138:139], v[28:29], v[102:103], v[138:139]
	ds_read_b128 v[30:33], v112 offset:3840
	ds_read_b128 v[34:37], v112 offset:3856
	ds_read_b128 v[96:99], v112 offset:19968
	ds_read_b128 v[100:103], v112 offset:19984
	v_add_f32_e32 v140, v136, v137
	v_add_f32_e32 v142, v138, v139
	v_pk_mul_f32 v[128:129], v[78:79], v[104:105] op_sel_hi:[1,0]
	v_add_f32_dpp v140, v140, v140 row_half_mirror row_mask:0xf bank_mask:0xf
	v_add_f32_dpp v142, v142, v142 row_half_mirror row_mask:0xf bank_mask:0xf
	v_pk_mul_f32 v[130:131], v[80:81], v[104:105] op_sel_hi:[1,0]
	v_pk_mul_f32 v[132:133], v[82:83], v[104:105] op_sel_hi:[1,0]
	v_add_f32_dpp v140, v140, v140 quad_perm:[1,0,3,2] row_mask:0xf bank_mask:0xf
	v_add_f32_dpp v142, v142, v142 quad_perm:[1,0,3,2] row_mask:0xf bank_mask:0xf
	v_pk_mul_f32 v[134:135], v[84:85], v[104:105] op_sel_hi:[1,0]
	ds_read_b128 v[78:81], v112 offset:16128
	ds_read_b128 v[82:85], v112 offset:16144
	ds_read_b32 v104, v108 offset:22400
	v_pk_fma_f32 v[128:129], v[22:23], v[38:39], v[128:129]
	v_add_f32_dpp v140, v140, v140 quad_perm:[2,3,0,1] row_mask:0xf bank_mask:0xf
	v_add_f32_dpp v142, v142, v142 quad_perm:[2,3,0,1] row_mask:0xf bank_mask:0xf
	v_pk_fma_f32 v[130:131], v[24:25], v[40:41], v[130:131]
	v_pk_fma_f32 v[132:133], v[26:27], v[42:43], v[132:133]
	v_pk_fma_f32 v[134:135], v[28:29], v[44:45], v[134:135]
	ds_read_b128 v[38:41], v112 offset:7936
	ds_read_b128 v[42:45], v112 offset:7952
	s_waitcnt lgkmcnt(10)
	v_pk_fma_f32 v[22:23], v[140:141], v[70:71], v[128:129] op_sel_hi:[0,1,1] neg_lo:[1,0,0] neg_hi:[1,0,0]
	v_pk_fma_f32 v[24:25], v[140:141], v[72:73], v[130:131] op_sel_hi:[0,1,1] neg_lo:[1,0,0] neg_hi:[1,0,0]
	v_pk_fma_f32 v[26:27], v[140:141], v[74:75], v[132:133] op_sel_hi:[0,1,1] neg_lo:[1,0,0] neg_hi:[1,0,0]
	v_pk_fma_f32 v[28:29], v[140:141], v[76:77], v[134:135] op_sel_hi:[0,1,1] neg_lo:[1,0,0] neg_hi:[1,0,0]
	ds_read_b128 v[70:73], v112 offset:12032
	ds_read_b128 v[74:77], v112 offset:12048
	ds_write_b32 v108, v142 offset:26240
	s_waitcnt lgkmcnt(3)
	v_pk_mul_f32 v[136:137], v[22:23], v[30:31]
	v_pk_mul_f32 v[138:139], v[22:23], v[96:97]
	v_pk_fma_f32 v[136:137], v[24:25], v[32:33], v[136:137]
	v_pk_fma_f32 v[138:139], v[24:25], v[98:99], v[138:139]
	v_pk_fma_f32 v[136:137], v[26:27], v[34:35], v[136:137]
	v_pk_fma_f32 v[138:139], v[26:27], v[100:101], v[138:139]
	v_pk_fma_f32 v[136:137], v[28:29], v[36:37], v[136:137]
	v_pk_fma_f32 v[138:139], v[28:29], v[102:103], v[138:139]
	ds_read_b128 v[96:99], v112 offset:20224
	ds_read_b128 v[100:103], v112 offset:20240
	v_add_f32_e32 v140, v136, v137
	v_add_f32_e32 v142, v138, v139
	v_pk_mul_f32 v[128:129], v[78:79], v[104:105] op_sel_hi:[1,0]
	v_add_f32_dpp v140, v140, v140 row_half_mirror row_mask:0xf bank_mask:0xf
	v_add_f32_dpp v142, v142, v142 row_half_mirror row_mask:0xf bank_mask:0xf
	v_pk_mul_f32 v[130:131], v[80:81], v[104:105] op_sel_hi:[1,0]
	v_pk_mul_f32 v[132:133], v[82:83], v[104:105] op_sel_hi:[1,0]
	v_add_f32_dpp v140, v140, v140 quad_perm:[1,0,3,2] row_mask:0xf bank_mask:0xf
	v_add_f32_dpp v142, v142, v142 quad_perm:[1,0,3,2] row_mask:0xf bank_mask:0xf
	v_pk_mul_f32 v[134:135], v[84:85], v[104:105] op_sel_hi:[1,0]
	v_pk_fma_f32 v[128:129], v[22:23], v[38:39], v[128:129]
	v_add_f32_dpp v140, v140, v140 quad_perm:[2,3,0,1] row_mask:0xf bank_mask:0xf
	v_add_f32_dpp v142, v142, v142 quad_perm:[2,3,0,1] row_mask:0xf bank_mask:0xf
	v_pk_fma_f32 v[130:131], v[24:25], v[40:41], v[130:131]
	v_pk_fma_f32 v[132:133], v[26:27], v[42:43], v[132:133]
	v_pk_fma_f32 v[134:135], v[28:29], v[44:45], v[134:135]
	s_waitcnt lgkmcnt(3)
	v_pk_fma_f32 v[22:23], v[140:141], v[70:71], v[128:129] op_sel_hi:[0,1,1] neg_lo:[1,0,0] neg_hi:[1,0,0]
	v_pk_fma_f32 v[24:25], v[140:141], v[72:73], v[130:131] op_sel_hi:[0,1,1] neg_lo:[1,0,0] neg_hi:[1,0,0]
	v_pk_fma_f32 v[26:27], v[140:141], v[74:75], v[132:133] op_sel_hi:[0,1,1] neg_lo:[1,0,0] neg_hi:[1,0,0]
	v_pk_fma_f32 v[28:29], v[140:141], v[76:77], v[134:135] op_sel_hi:[0,1,1] neg_lo:[1,0,0] neg_hi:[1,0,0]
	ds_write_b32 v108, v142 offset:26368
	s_waitcnt lgkmcnt(1)
	v_pk_mul_f32 v[138:139], v[22:23], v[96:97]
	v_pk_fma_f32 v[138:139], v[24:25], v[98:99], v[138:139]
	v_pk_fma_f32 v[138:139], v[26:27], v[100:101], v[138:139]
	v_pk_fma_f32 v[138:139], v[28:29], v[102:103], v[138:139]
	v_add_f32_e32 v142, v138, v139
	s_nop 1
	v_add_f32_dpp v142, v142, v142 row_half_mirror row_mask:0xf bank_mask:0xf
	s_nop 1
	v_add_f32_dpp v142, v142, v142 quad_perm:[1,0,3,2] row_mask:0xf bank_mask:0xf
	s_nop 1
	v_add_f32_dpp v142, v142, v142 quad_perm:[2,3,0,1] row_mask:0xf bank_mask:0xf
	ds_write_b32 v108, v142 offset:26496
	s_branch .Lrw0_u2e1
.Lrw0_u2s1:
	ds_read_b128 v[30:33], v112 offset:0
	ds_read_b128 v[34:37], v112 offset:16
	ds_read_b128 v[38:41], v112 offset:4096
	ds_read_b128 v[42:45], v112 offset:4112
	ds_read_b128 v[70:73], v112 offset:8192
	ds_read_b128 v[74:77], v112 offset:8208
	s_waitcnt lgkmcnt(2)
	v_pk_mul_f32 v[136:137], v[22:23], v[30:31]
	v_pk_fma_f32 v[136:137], v[24:25], v[32:33], v[136:137]
	v_pk_fma_f32 v[136:137], v[26:27], v[34:35], v[136:137]
	v_pk_fma_f32 v[136:137], v[28:29], v[36:37], v[136:137]
	ds_read_b128 v[30:33], v112 offset:256
	ds_read_b128 v[34:37], v112 offset:272
	ds_read_b128 v[96:99], v112 offset:16384
	ds_read_b128 v[100:103], v112 offset:16400
	v_add_f32_e32 v140, v136, v137
	v_pk_mul_f32 v[128:129], v[22:23], v[38:39]
	s_nop 0
	v_add_f32_dpp v140, v140, v140 row_half_mirror row_mask:0xf bank_mask:0xf
	v_pk_mul_f32 v[130:131], v[24:25], v[40:41]
	v_pk_mul_f32 v[132:133], v[26:27], v[42:43]
	v_pk_mul_f32 v[134:135], v[28:29], v[44:45]
	ds_read_b128 v[38:41], v112 offset:4352
	ds_read_b128 v[42:45], v112 offset:4368
	v_add_f32_dpp v140, v140, v140 quad_perm:[1,0,3,2] row_mask:0xf bank_mask:0xf
	s_nop 1
	v_add_f32_dpp v140, v140, v140 quad_perm:[2,3,0,1] row_mask:0xf bank_mask:0xf
	s_waitcnt lgkmcnt(6)
	v_pk_fma_f32 v[22:23], v[140:141], v[70:71], v[128:129] op_sel_hi:[0,1,1] neg_lo:[1,0,0] neg_hi:[1,0,0]
	v_pk_fma_f32 v[24:25], v[140:141], v[72:73], v[130:131] op_sel_hi:[0,1,1] neg_lo:[1,0,0] neg_hi:[1,0,0]
	v_pk_fma_f32 v[26:27], v[140:141], v[74:75], v[132:133] op_sel_hi:[0,1,1] neg_lo:[1,0,0] neg_hi:[1,0,0]
	v_pk_fma_f32 v[28:29], v[140:141], v[76:77], v[134:135] op_sel_hi:[0,1,1] neg_lo:[1,0,0] neg_hi:[1,0,0]
	ds_read_b128 v[70:73], v112 offset:8448
	ds_read_b128 v[74:77], v112 offset:8464
	s_waitcnt lgkmcnt(2)
	v_pk_mul_f32 v[136:137], v[22:23], v[30:31]
	v_pk_mul_f32 v[138:139], v[22:23], v[96:97]
	v_pk_fma_f32 v[136:137], v[24:25], v[32:33], v[136:137]
	v_pk_fma_f32 v[138:139], v[24:25], v[98:99], v[138:139]
	v_pk_fma_f32 v[136:137], v[26:27], v[34:35], v[136:137]
	v_pk_fma_f32 v[138:139], v[26:27], v[100:101], v[138:139]
	v_pk_fma_f32 v[136:137], v[28:29], v[36:37], v[136:137]
	v_pk_fma_f32 v[138:139], v[28:29], v[102:103], v[138:139]
	ds_read_b128 v[30:33], v112 offset:512
	ds_read_b128 v[34:37], v112 offset:528
	ds_read_b128 v[96:99], v112 offset:16640
	ds_read_b128 v[100:103], v112 offset:16656
	v_add_f32_e32 v140, v136, v137
	v_add_f32_e32 v142, v138, v139
	v_pk_mul_f32 v[128:129], v[22:23], v[38:39]
	v_add_f32_dpp v140, v140, v140 row_half_mirror row_mask:0xf bank_mask:0xf
	v_add_f32_dpp v142, v142, v142 row_half_mirror row_mask:0xf bank_mask:0xf
	v_pk_mul_f32 v[130:131], v[24:25], v[40:41]
	v_pk_mul_f32 v[132:133], v[26:27], v[42:43]
	v_add_f32_dpp v140, v140, v140 quad_perm:[1,0,3,2] row_mask:0xf bank_mask:0xf
	v_add_f32_dpp v142, v142, v142 quad_perm:[1,0,3,2] row_mask:0xf bank_mask:0xf
	v_pk_mul_f32 v[134:135], v[28:29], v[44:45]
	ds_read_b128 v[38:41], v112 offset:4608
	ds_read_b128 v[42:45], v112 offset:4624
	v_add_f32_dpp v140, v140, v140 quad_perm:[2,3,0,1] row_mask:0xf bank_mask:0xf
	v_add_f32_dpp v142, v142, v142 quad_perm:[2,3,0,1] row_mask:0xf bank_mask:0xf
	s_waitcnt lgkmcnt(6)
	v_pk_fma_f32 v[22:23], v[140:141], v[70:71], v[128:129] op_sel_hi:[0,1,1] neg_lo:[1,0,0] neg_hi:[1,0,0]
	v_pk_fma_f32 v[24:25], v[140:141], v[72:73], v[130:131] op_sel_hi:[0,1,1] neg_lo:[1,0,0] neg_hi:[1,0,0]
	v_pk_fma_f32 v[26:27], v[140:141], v[74:75], v[132:133] op_sel_hi:[0,1,1] neg_lo:[1,0,0] neg_hi:[1,0,0]
	v_pk_fma_f32 v[28:29], v[140:141], v[76:77], v[134:135] op_sel_hi:[0,1,1] neg_lo:[1,0,0] neg_hi:[1,0,0]
	ds_read_b128 v[70:73], v112 offset:8704
	ds_read_b128 v[74:77], v112 offset:8720
	ds_write_b32 v108, v142 offset:24576
	s_waitcnt lgkmcnt(3)
	v_pk_mul_f32 v[136:137], v[22:23], v[30:31]
	v_pk_mul_f32 v[138:139], v[22:23], v[96:97]
	v_pk_fma_f32 v[136:137], v[24:25], v[32:33], v[136:137]
	v_pk_fma_f32 v[138:139], v[24:25], v[98:99], v[138:139]
	v_pk_fma_f32 v[136:137], v[26:27], v[34:35], v[136:137]
	v_pk_fma_f32 v[138:139], v[26:27], v[100:101], v[138:139]
	v_pk_fma_f32 v[136:137], v[28:29], v[36:37], v[136:137]
	v_pk_fma_f32 v[138:139], v[28:29], v[102:103], v[138:139]
	ds_read_b128 v[30:33], v112 offset:768
	ds_read_b128 v[34:37], v112 offset:784
	ds_read_b128 v[96:99], v112 offset:16896
	ds_read_b128 v[100:103], v112 offset:16912
	v_add_f32_e32 v140, v136, v137
	v_add_f32_e32 v142, v138, v139
	v_pk_mul_f32 v[128:129], v[22:23], v[38:39]
	v_add_f32_dpp v140, v140, v140 row_half_mirror row_mask:0xf bank_mask:0xf
	v_add_f32_dpp v142, v142, v142 row_half_mirror row_mask:0xf bank_mask:0xf
	v_pk_mul_f32 v[130:131], v[24:25], v[40:41]
	v_pk_mul_f32 v[132:133], v[26:27], v[42:43]
	v_add_f32_dpp v140, v140, v140 quad_perm:[1,0,3,2] row_mask:0xf bank_mask:0xf
	v_add_f32_dpp v142, v142, v142 quad_perm:[1,0,3,2] row_mask:0xf bank_mask:0xf
	v_pk_mul_f32 v[134:135], v[28:29], v[44:45]
	ds_read_b128 v[38:41], v112 offset:4864
	ds_read_b128 v[42:45], v112 offset:4880
	v_add_f32_dpp v140, v140, v140 quad_perm:[2,3,0,1] row_mask:0xf bank_mask:0xf
	v_add_f32_dpp v142, v142, v142 quad_perm:[2,3,0,1] row_mask:0xf bank_mask:0xf
	s_waitcnt lgkmcnt(7)
	v_pk_fma_f32 v[22:23], v[140:141], v[70:71], v[128:129] op_sel_hi:[0,1,1] neg_lo:[1,0,0] neg_hi:[1,0,0]
	v_pk_fma_f32 v[24:25], v[140:141], v[72:73], v[130:131] op_sel_hi:[0,1,1] neg_lo:[1,0,0] neg_hi:[1,0,0]
	v_pk_fma_f32 v[26:27], v[140:141], v[74:75], v[132:133] op_sel_hi:[0,1,1] neg_lo:[1,0,0] neg_hi:[1,0,0]
	v_pk_fma_f32 v[28:29], v[140:141], v[76:77], v[134:135] op_sel_hi:[0,1,1] neg_lo:[1,0,0] neg_hi:[1,0,0]
	ds_read_b128 v[70:73], v112 offset:8960
	ds_read_b128 v[74:77], v112 offset:8976
	ds_write_b32 v108, v142 offset:24704
	s_waitcnt lgkmcnt(3)
	v_pk_mul_f32 v[136:137], v[22:23], v[30:31]
	v_pk_mul_f32 v[138:139], v[22:23], v[96:97]
	v_pk_fma_f32 v[136:137], v[24:25], v[32:33], v[136:137]
	v_pk_fma_f32 v[138:139], v[24:25], v[98:99], v[138:139]
	v_pk_fma_f32 v[136:137], v[26:27], v[34:35], v[136:137]
	v_pk_fma_f32 v[138:139], v[26:27], v[100:101], v[138:139]
	v_pk_fma_f32 v[136:137], v[28:29], v[36:37], v[136:137]
	v_pk_fma_f32 v[138:139], v[28:29], v[102:103], v[138:139]
	ds_read_b128 v[30:33], v112 offset:1024
	ds_read_b128 v[34:37], v112 offset:1040
	ds_read_b128 v[96:99], v112 offset:17152
	ds_read_b128 v[100:103], v112 offset:17168
	v_add_f32_e32 v140, v136, v137
	v_add_f32_e32 v142, v138, v139
	v_pk_mul_f32 v[128:129], v[22:23], v[38:39]
	v_add_f32_dpp v140, v140, v140 row_half_mirror row_mask:0xf bank_mask:0xf
	v_add_f32_dpp v142, v142, v142 row_half_mirror row_mask:0xf bank_mask:0xf
	v_pk_mul_f32 v[130:131], v[24:25], v[40:41]
	v_pk_mul_f32 v[132:133], v[26:27], v[42:43]
	v_add_f32_dpp v140, v140, v140 quad_perm:[1,0,3,2] row_mask:0xf bank_mask:0xf
	v_add_f32_dpp v142, v142, v142 quad_perm:[1,0,3,2] row_mask:0xf bank_mask:0xf
	v_pk_mul_f32 v[134:135], v[28:29], v[44:45]
	ds_read_b128 v[38:41], v112 offset:5120
	ds_read_b128 v[42:45], v112 offset:5136
	v_add_f32_dpp v140, v140, v140 quad_perm:[2,3,0,1] row_mask:0xf bank_mask:0xf
	v_add_f32_dpp v142, v142, v142 quad_perm:[2,3,0,1] row_mask:0xf bank_mask:0xf
	s_waitcnt lgkmcnt(7)
	v_pk_fma_f32 v[22:23], v[140:141], v[70:71], v[128:129] op_sel_hi:[0,1,1] neg_lo:[1,0,0] neg_hi:[1,0,0]
	v_pk_fma_f32 v[24:25], v[140:141], v[72:73], v[130:131] op_sel_hi:[0,1,1] neg_lo:[1,0,0] neg_hi:[1,0,0]
	v_pk_fma_f32 v[26:27], v[140:141], v[74:75], v[132:133] op_sel_hi:[0,1,1] neg_lo:[1,0,0] neg_hi:[1,0,0]
	v_pk_fma_f32 v[28:29], v[140:141], v[76:77], v[134:135] op_sel_hi:[0,1,1] neg_lo:[1,0,0] neg_hi:[1,0,0]
	ds_read_b128 v[70:73], v112 offset:9216
	ds_read_b128 v[74:77], v112 offset:9232
	ds_write_b32 v108, v142 offset:24832
	s_waitcnt lgkmcnt(3)
	v_pk_mul_f32 v[136:137], v[22:23], v[30:31]
	v_pk_mul_f32 v[138:139], v[22:23], v[96:97]
	v_pk_fma_f32 v[136:137], v[24:25], v[32:33], v[136:137]
	v_pk_fma_f32 v[138:139], v[24:25], v[98:99], v[138:139]
	v_pk_fma_f32 v[136:137], v[26:27], v[34:35], v[136:137]
	v_pk_fma_f32 v[138:139], v[26:27], v[100:101], v[138:139]
	v_pk_fma_f32 v[136:137], v[28:29], v[36:37], v[136:137]
	v_pk_fma_f32 v[138:139], v[28:29], v[102:103], v[138:139]
	ds_read_b128 v[30:33], v112 offset:1280
	ds_read_b128 v[34:37], v112 offset:1296
	ds_read_b128 v[96:99], v112 offset:17408
	ds_read_b128 v[100:103], v112 offset:17424
	v_add_f32_e32 v140, v136, v137
	v_add_f32_e32 v142, v138, v139
	v_pk_mul_f32 v[128:129], v[22:23], v[38:39]
	v_add_f32_dpp v140, v140, v140 row_half_mirror row_mask:0xf bank_mask:0xf
	v_add_f32_dpp v142, v142, v142 row_half_mirror row_mask:0xf bank_mask:0xf
	v_pk_mul_f32 v[130:131], v[24:25], v[40:41]
	v_pk_mul_f32 v[132:133], v[26:27], v[42:43]
	v_add_f32_dpp v140, v140, v140 quad_perm:[1,0,3,2] row_mask:0xf bank_mask:0xf
	v_add_f32_dpp v142, v142, v142 quad_perm:[1,0,3,2] row_mask:0xf bank_mask:0xf
	v_pk_mul_f32 v[134:135], v[28:29], v[44:45]
	ds_read_b128 v[38:41], v112 offset:5376
	ds_read_b128 v[42:45], v112 offset:5392
	v_add_f32_dpp v140, v140, v140 quad_perm:[2,3,0,1] row_mask:0xf bank_mask:0xf
	v_add_f32_dpp v142, v142, v142 quad_perm:[2,3,0,1] row_mask:0xf bank_mask:0xf
	s_waitcnt lgkmcnt(7)
	v_pk_fma_f32 v[22:23], v[140:141], v[70:71], v[128:129] op_sel_hi:[0,1,1] neg_lo:[1,0,0] neg_hi:[1,0,0]
	v_pk_fma_f32 v[24:25], v[140:141], v[72:73], v[130:131] op_sel_hi:[0,1,1] neg_lo:[1,0,0] neg_hi:[1,0,0]
	v_pk_fma_f32 v[26:27], v[140:141], v[74:75], v[132:133] op_sel_hi:[0,1,1] neg_lo:[1,0,0] neg_hi:[1,0,0]
	v_pk_fma_f32 v[28:29], v[140:141], v[76:77], v[134:135] op_sel_hi:[0,1,1] neg_lo:[1,0,0] neg_hi:[1,0,0]
	ds_read_b128 v[70:73], v112 offset:9472
	ds_read_b128 v[74:77], v112 offset:9488
	ds_write_b32 v108, v142 offset:24960
	s_waitcnt lgkmcnt(3)
	v_pk_mul_f32 v[136:137], v[22:23], v[30:31]
	v_pk_mul_f32 v[138:139], v[22:23], v[96:97]
	v_pk_fma_f32 v[136:137], v[24:25], v[32:33], v[136:137]
	v_pk_fma_f32 v[138:139], v[24:25], v[98:99], v[138:139]
	v_pk_fma_f32 v[136:137], v[26:27], v[34:35], v[136:137]
	v_pk_fma_f32 v[138:139], v[26:27], v[100:101], v[138:139]
	v_pk_fma_f32 v[136:137], v[28:29], v[36:37], v[136:137]
	v_pk_fma_f32 v[138:139], v[28:29], v[102:103], v[138:139]
	ds_read_b128 v[30:33], v112 offset:1536
	ds_read_b128 v[34:37], v112 offset:1552
	ds_read_b128 v[96:99], v112 offset:17664
	ds_read_b128 v[100:103], v112 offset:17680
	v_add_f32_e32 v140, v136, v137
	v_add_f32_e32 v142, v138, v139
	v_pk_mul_f32 v[128:129], v[22:23], v[38:39]
	v_add_f32_dpp v140, v140, v140 row_half_mirror row_mask:0xf bank_mask:0xf
	v_add_f32_dpp v142, v142, v142 row_half_mirror row_mask:0xf bank_mask:0xf
	v_pk_mul_f32 v[130:131], v[24:25], v[40:41]
	v_pk_mul_f32 v[132:133], v[26:27], v[42:43]
	v_add_f32_dpp v140, v140, v140 quad_perm:[1,0,3,2] row_mask:0xf bank_mask:0xf
	v_add_f32_dpp v142, v142, v142 quad_perm:[1,0,3,2] row_mask:0xf bank_mask:0xf
	v_pk_mul_f32 v[134:135], v[28:29], v[44:45]
	ds_read_b128 v[38:41], v112 offset:5632
	ds_read_b128 v[42:45], v112 offset:5648
	v_add_f32_dpp v140, v140, v140 quad_perm:[2,3,0,1] row_mask:0xf bank_mask:0xf
	v_add_f32_dpp v142, v142, v142 quad_perm:[2,3,0,1] row_mask:0xf bank_mask:0xf
	s_waitcnt lgkmcnt(7)
	v_pk_fma_f32 v[22:23], v[140:141], v[70:71], v[128:129] op_sel_hi:[0,1,1] neg_lo:[1,0,0] neg_hi:[1,0,0]
	v_pk_fma_f32 v[24:25], v[140:141], v[72:73], v[130:131] op_sel_hi:[0,1,1] neg_lo:[1,0,0] neg_hi:[1,0,0]
	v_pk_fma_f32 v[26:27], v[140:141], v[74:75], v[132:133] op_sel_hi:[0,1,1] neg_lo:[1,0,0] neg_hi:[1,0,0]
	v_pk_fma_f32 v[28:29], v[140:141], v[76:77], v[134:135] op_sel_hi:[0,1,1] neg_lo:[1,0,0] neg_hi:[1,0,0]
	ds_read_b128 v[70:73], v112 offset:9728
	ds_read_b128 v[74:77], v112 offset:9744
	ds_write_b32 v108, v142 offset:25088
	s_waitcnt lgkmcnt(3)
	v_pk_mul_f32 v[136:137], v[22:23], v[30:31]
	v_pk_mul_f32 v[138:139], v[22:23], v[96:97]
	v_pk_fma_f32 v[136:137], v[24:25], v[32:33], v[136:137]
	v_pk_fma_f32 v[138:139], v[24:25], v[98:99], v[138:139]
	v_pk_fma_f32 v[136:137], v[26:27], v[34:35], v[136:137]
	v_pk_fma_f32 v[138:139], v[26:27], v[100:101], v[138:139]
	v_pk_fma_f32 v[136:137], v[28:29], v[36:37], v[136:137]
	v_pk_fma_f32 v[138:139], v[28:29], v[102:103], v[138:139]
	ds_read_b128 v[30:33], v112 offset:1792
	ds_read_b128 v[34:37], v112 offset:1808
	ds_read_b128 v[96:99], v112 offset:17920
	ds_read_b128 v[100:103], v112 offset:17936
	v_add_f32_e32 v140, v136, v137
	v_add_f32_e32 v142, v138, v139
	v_pk_mul_f32 v[128:129], v[22:23], v[38:39]
	v_add_f32_dpp v140, v140, v140 row_half_mirror row_mask:0xf bank_mask:0xf
	v_add_f32_dpp v142, v142, v142 row_half_mirror row_mask:0xf bank_mask:0xf
	v_pk_mul_f32 v[130:131], v[24:25], v[40:41]
	v_pk_mul_f32 v[132:133], v[26:27], v[42:43]
	v_add_f32_dpp v140, v140, v140 quad_perm:[1,0,3,2] row_mask:0xf bank_mask:0xf
	v_add_f32_dpp v142, v142, v142 quad_perm:[1,0,3,2] row_mask:0xf bank_mask:0xf
	v_pk_mul_f32 v[134:135], v[28:29], v[44:45]
	ds_read_b128 v[38:41], v112 offset:5888
	ds_read_b128 v[42:45], v112 offset:5904
	v_add_f32_dpp v140, v140, v140 quad_perm:[2,3,0,1] row_mask:0xf bank_mask:0xf
	v_add_f32_dpp v142, v142, v142 quad_perm:[2,3,0,1] row_mask:0xf bank_mask:0xf
	s_waitcnt lgkmcnt(7)
	v_pk_fma_f32 v[22:23], v[140:141], v[70:71], v[128:129] op_sel_hi:[0,1,1] neg_lo:[1,0,0] neg_hi:[1,0,0]
	v_pk_fma_f32 v[24:25], v[140:141], v[72:73], v[130:131] op_sel_hi:[0,1,1] neg_lo:[1,0,0] neg_hi:[1,0,0]
	v_pk_fma_f32 v[26:27], v[140:141], v[74:75], v[132:133] op_sel_hi:[0,1,1] neg_lo:[1,0,0] neg_hi:[1,0,0]
	v_pk_fma_f32 v[28:29], v[140:141], v[76:77], v[134:135] op_sel_hi:[0,1,1] neg_lo:[1,0,0] neg_hi:[1,0,0]
	ds_read_b128 v[70:73], v112 offset:9984
	ds_read_b128 v[74:77], v112 offset:10000
	ds_write_b32 v108, v142 offset:25216
	s_waitcnt lgkmcnt(3)
	v_pk_mul_f32 v[136:137], v[22:23], v[30:31]
	v_pk_mul_f32 v[138:139], v[22:23], v[96:97]
	v_pk_fma_f32 v[136:137], v[24:25], v[32:33], v[136:137]
	v_pk_fma_f32 v[138:139], v[24:25], v[98:99], v[138:139]
	v_pk_fma_f32 v[136:137], v[26:27], v[34:35], v[136:137]
	v_pk_fma_f32 v[138:139], v[26:27], v[100:101], v[138:139]
	v_pk_fma_f32 v[136:137], v[28:29], v[36:37], v[136:137]
	v_pk_fma_f32 v[138:139], v[28:29], v[102:103], v[138:139]
	ds_read_b128 v[30:33], v112 offset:2048
	ds_read_b128 v[34:37], v112 offset:2064
	ds_read_b128 v[96:99], v112 offset:18176
	ds_read_b128 v[100:103], v112 offset:18192
	v_add_f32_e32 v140, v136, v137
	v_add_f32_e32 v142, v138, v139
	v_pk_mul_f32 v[128:129], v[22:23], v[38:39]
	v_add_f32_dpp v140, v140, v140 row_half_mirror row_mask:0xf bank_mask:0xf
	v_add_f32_dpp v142, v142, v142 row_half_mirror row_mask:0xf bank_mask:0xf
	v_pk_mul_f32 v[130:131], v[24:25], v[40:41]
	v_pk_mul_f32 v[132:133], v[26:27], v[42:43]
	v_add_f32_dpp v140, v140, v140 quad_perm:[1,0,3,2] row_mask:0xf bank_mask:0xf
	v_add_f32_dpp v142, v142, v142 quad_perm:[1,0,3,2] row_mask:0xf bank_mask:0xf
	v_pk_mul_f32 v[134:135], v[28:29], v[44:45]
	ds_read_b128 v[38:41], v112 offset:6144
	ds_read_b128 v[42:45], v112 offset:6160
	v_add_f32_dpp v140, v140, v140 quad_perm:[2,3,0,1] row_mask:0xf bank_mask:0xf
	v_add_f32_dpp v142, v142, v142 quad_perm:[2,3,0,1] row_mask:0xf bank_mask:0xf
	s_waitcnt lgkmcnt(7)
	v_pk_fma_f32 v[22:23], v[140:141], v[70:71], v[128:129] op_sel_hi:[0,1,1] neg_lo:[1,0,0] neg_hi:[1,0,0]
	v_pk_fma_f32 v[24:25], v[140:141], v[72:73], v[130:131] op_sel_hi:[0,1,1] neg_lo:[1,0,0] neg_hi:[1,0,0]
	v_pk_fma_f32 v[26:27], v[140:141], v[74:75], v[132:133] op_sel_hi:[0,1,1] neg_lo:[1,0,0] neg_hi:[1,0,0]
	v_pk_fma_f32 v[28:29], v[140:141], v[76:77], v[134:135] op_sel_hi:[0,1,1] neg_lo:[1,0,0] neg_hi:[1,0,0]
	ds_read_b128 v[70:73], v112 offset:10240
	ds_read_b128 v[74:77], v112 offset:10256
	ds_write_b32 v108, v142 offset:25344
	s_waitcnt lgkmcnt(3)
	v_pk_mul_f32 v[136:137], v[22:23], v[30:31]
	v_pk_mul_f32 v[138:139], v[22:23], v[96:97]
	v_pk_fma_f32 v[136:137], v[24:25], v[32:33], v[136:137]
	v_pk_fma_f32 v[138:139], v[24:25], v[98:99], v[138:139]
	v_pk_fma_f32 v[136:137], v[26:27], v[34:35], v[136:137]
	v_pk_fma_f32 v[138:139], v[26:27], v[100:101], v[138:139]
	v_pk_fma_f32 v[136:137], v[28:29], v[36:37], v[136:137]
	v_pk_fma_f32 v[138:139], v[28:29], v[102:103], v[138:139]
	ds_read_b128 v[30:33], v112 offset:2304
	ds_read_b128 v[34:37], v112 offset:2320
	ds_read_b128 v[96:99], v112 offset:18432
	ds_read_b128 v[100:103], v112 offset:18448
	v_add_f32_e32 v140, v136, v137
	v_add_f32_e32 v142, v138, v139
	v_pk_mul_f32 v[128:129], v[22:23], v[38:39]
	v_add_f32_dpp v140, v140, v140 row_half_mirror row_mask:0xf bank_mask:0xf
	v_add_f32_dpp v142, v142, v142 row_half_mirror row_mask:0xf bank_mask:0xf
	v_pk_mul_f32 v[130:131], v[24:25], v[40:41]
	v_pk_mul_f32 v[132:133], v[26:27], v[42:43]
	v_add_f32_dpp v140, v140, v140 quad_perm:[1,0,3,2] row_mask:0xf bank_mask:0xf
	v_add_f32_dpp v142, v142, v142 quad_perm:[1,0,3,2] row_mask:0xf bank_mask:0xf
	v_pk_mul_f32 v[134:135], v[28:29], v[44:45]
	ds_read_b128 v[38:41], v112 offset:6400
	ds_read_b128 v[42:45], v112 offset:6416
	v_add_f32_dpp v140, v140, v140 quad_perm:[2,3,0,1] row_mask:0xf bank_mask:0xf
	v_add_f32_dpp v142, v142, v142 quad_perm:[2,3,0,1] row_mask:0xf bank_mask:0xf
	s_waitcnt lgkmcnt(7)
	v_pk_fma_f32 v[22:23], v[140:141], v[70:71], v[128:129] op_sel_hi:[0,1,1] neg_lo:[1,0,0] neg_hi:[1,0,0]
	v_pk_fma_f32 v[24:25], v[140:141], v[72:73], v[130:131] op_sel_hi:[0,1,1] neg_lo:[1,0,0] neg_hi:[1,0,0]
	v_pk_fma_f32 v[26:27], v[140:141], v[74:75], v[132:133] op_sel_hi:[0,1,1] neg_lo:[1,0,0] neg_hi:[1,0,0]
	v_pk_fma_f32 v[28:29], v[140:141], v[76:77], v[134:135] op_sel_hi:[0,1,1] neg_lo:[1,0,0] neg_hi:[1,0,0]
	ds_read_b128 v[70:73], v112 offset:10496
	ds_read_b128 v[74:77], v112 offset:10512
	ds_write_b32 v108, v142 offset:25472
	s_waitcnt lgkmcnt(3)
	v_pk_mul_f32 v[136:137], v[22:23], v[30:31]
	v_pk_mul_f32 v[138:139], v[22:23], v[96:97]
	v_pk_fma_f32 v[136:137], v[24:25], v[32:33], v[136:137]
	v_pk_fma_f32 v[138:139], v[24:25], v[98:99], v[138:139]
	v_pk_fma_f32 v[136:137], v[26:27], v[34:35], v[136:137]
	v_pk_fma_f32 v[138:139], v[26:27], v[100:101], v[138:139]
	v_pk_fma_f32 v[136:137], v[28:29], v[36:37], v[136:137]
	v_pk_fma_f32 v[138:139], v[28:29], v[102:103], v[138:139]
	ds_read_b128 v[30:33], v112 offset:2560
	ds_read_b128 v[34:37], v112 offset:2576
	ds_read_b128 v[96:99], v112 offset:18688
	ds_read_b128 v[100:103], v112 offset:18704
	v_add_f32_e32 v140, v136, v137
	v_add_f32_e32 v142, v138, v139
	v_pk_mul_f32 v[128:129], v[22:23], v[38:39]
	v_add_f32_dpp v140, v140, v140 row_half_mirror row_mask:0xf bank_mask:0xf
	v_add_f32_dpp v142, v142, v142 row_half_mirror row_mask:0xf bank_mask:0xf
	v_pk_mul_f32 v[130:131], v[24:25], v[40:41]
	v_pk_mul_f32 v[132:133], v[26:27], v[42:43]
	v_add_f32_dpp v140, v140, v140 quad_perm:[1,0,3,2] row_mask:0xf bank_mask:0xf
	v_add_f32_dpp v142, v142, v142 quad_perm:[1,0,3,2] row_mask:0xf bank_mask:0xf
	v_pk_mul_f32 v[134:135], v[28:29], v[44:45]
	ds_read_b128 v[38:41], v112 offset:6656
	ds_read_b128 v[42:45], v112 offset:6672
	v_add_f32_dpp v140, v140, v140 quad_perm:[2,3,0,1] row_mask:0xf bank_mask:0xf
	v_add_f32_dpp v142, v142, v142 quad_perm:[2,3,0,1] row_mask:0xf bank_mask:0xf
	s_waitcnt lgkmcnt(7)
	v_pk_fma_f32 v[22:23], v[140:141], v[70:71], v[128:129] op_sel_hi:[0,1,1] neg_lo:[1,0,0] neg_hi:[1,0,0]
	v_pk_fma_f32 v[24:25], v[140:141], v[72:73], v[130:131] op_sel_hi:[0,1,1] neg_lo:[1,0,0] neg_hi:[1,0,0]
	v_pk_fma_f32 v[26:27], v[140:141], v[74:75], v[132:133] op_sel_hi:[0,1,1] neg_lo:[1,0,0] neg_hi:[1,0,0]
	v_pk_fma_f32 v[28:29], v[140:141], v[76:77], v[134:135] op_sel_hi:[0,1,1] neg_lo:[1,0,0] neg_hi:[1,0,0]
	ds_read_b128 v[70:73], v112 offset:10752
	ds_read_b128 v[74:77], v112 offset:10768
	ds_write_b32 v108, v142 offset:25600
	s_waitcnt lgkmcnt(3)
	v_pk_mul_f32 v[136:137], v[22:23], v[30:31]
	v_pk_mul_f32 v[138:139], v[22:23], v[96:97]
	v_pk_fma_f32 v[136:137], v[24:25], v[32:33], v[136:137]
	v_pk_fma_f32 v[138:139], v[24:25], v[98:99], v[138:139]
	v_pk_fma_f32 v[136:137], v[26:27], v[34:35], v[136:137]
	v_pk_fma_f32 v[138:139], v[26:27], v[100:101], v[138:139]
	v_pk_fma_f32 v[136:137], v[28:29], v[36:37], v[136:137]
	v_pk_fma_f32 v[138:139], v[28:29], v[102:103], v[138:139]
	ds_read_b128 v[30:33], v112 offset:2816
	ds_read_b128 v[34:37], v112 offset:2832
	ds_read_b128 v[96:99], v112 offset:18944
	ds_read_b128 v[100:103], v112 offset:18960
	v_add_f32_e32 v140, v136, v137
	v_add_f32_e32 v142, v138, v139
	v_pk_mul_f32 v[128:129], v[22:23], v[38:39]
	v_add_f32_dpp v140, v140, v140 row_half_mirror row_mask:0xf bank_mask:0xf
	v_add_f32_dpp v142, v142, v142 row_half_mirror row_mask:0xf bank_mask:0xf
	v_pk_mul_f32 v[130:131], v[24:25], v[40:41]
	v_pk_mul_f32 v[132:133], v[26:27], v[42:43]
	v_add_f32_dpp v140, v140, v140 quad_perm:[1,0,3,2] row_mask:0xf bank_mask:0xf
	v_add_f32_dpp v142, v142, v142 quad_perm:[1,0,3,2] row_mask:0xf bank_mask:0xf
	v_pk_mul_f32 v[134:135], v[28:29], v[44:45]
	ds_read_b128 v[38:41], v112 offset:6912
	ds_read_b128 v[42:45], v112 offset:6928
	v_add_f32_dpp v140, v140, v140 quad_perm:[2,3,0,1] row_mask:0xf bank_mask:0xf
	v_add_f32_dpp v142, v142, v142 quad_perm:[2,3,0,1] row_mask:0xf bank_mask:0xf
	s_waitcnt lgkmcnt(7)
	v_pk_fma_f32 v[22:23], v[140:141], v[70:71], v[128:129] op_sel_hi:[0,1,1] neg_lo:[1,0,0] neg_hi:[1,0,0]
	v_pk_fma_f32 v[24:25], v[140:141], v[72:73], v[130:131] op_sel_hi:[0,1,1] neg_lo:[1,0,0] neg_hi:[1,0,0]
	v_pk_fma_f32 v[26:27], v[140:141], v[74:75], v[132:133] op_sel_hi:[0,1,1] neg_lo:[1,0,0] neg_hi:[1,0,0]
	v_pk_fma_f32 v[28:29], v[140:141], v[76:77], v[134:135] op_sel_hi:[0,1,1] neg_lo:[1,0,0] neg_hi:[1,0,0]
	ds_read_b128 v[70:73], v112 offset:11008
	ds_read_b128 v[74:77], v112 offset:11024
	ds_write_b32 v108, v142 offset:25728
	s_waitcnt lgkmcnt(3)
	v_pk_mul_f32 v[136:137], v[22:23], v[30:31]
	v_pk_mul_f32 v[138:139], v[22:23], v[96:97]
	v_pk_fma_f32 v[136:137], v[24:25], v[32:33], v[136:137]
	v_pk_fma_f32 v[138:139], v[24:25], v[98:99], v[138:139]
	v_pk_fma_f32 v[136:137], v[26:27], v[34:35], v[136:137]
	v_pk_fma_f32 v[138:139], v[26:27], v[100:101], v[138:139]
	v_pk_fma_f32 v[136:137], v[28:29], v[36:37], v[136:137]
	v_pk_fma_f32 v[138:139], v[28:29], v[102:103], v[138:139]
	ds_read_b128 v[30:33], v112 offset:3072
	ds_read_b128 v[34:37], v112 offset:3088
	ds_read_b128 v[96:99], v112 offset:19200
	ds_read_b128 v[100:103], v112 offset:19216
	v_add_f32_e32 v140, v136, v137
	v_add_f32_e32 v142, v138, v139
	v_pk_mul_f32 v[128:129], v[22:23], v[38:39]
	v_add_f32_dpp v140, v140, v140 row_half_mirror row_mask:0xf bank_mask:0xf
	v_add_f32_dpp v142, v142, v142 row_half_mirror row_mask:0xf bank_mask:0xf
	v_pk_mul_f32 v[130:131], v[24:25], v[40:41]
	v_pk_mul_f32 v[132:133], v[26:27], v[42:43]
	v_add_f32_dpp v140, v140, v140 quad_perm:[1,0,3,2] row_mask:0xf bank_mask:0xf
	v_add_f32_dpp v142, v142, v142 quad_perm:[1,0,3,2] row_mask:0xf bank_mask:0xf
	v_pk_mul_f32 v[134:135], v[28:29], v[44:45]
	ds_read_b128 v[38:41], v112 offset:7168
	ds_read_b128 v[42:45], v112 offset:7184
	v_add_f32_dpp v140, v140, v140 quad_perm:[2,3,0,1] row_mask:0xf bank_mask:0xf
	v_add_f32_dpp v142, v142, v142 quad_perm:[2,3,0,1] row_mask:0xf bank_mask:0xf
	s_waitcnt lgkmcnt(7)
	v_pk_fma_f32 v[22:23], v[140:141], v[70:71], v[128:129] op_sel_hi:[0,1,1] neg_lo:[1,0,0] neg_hi:[1,0,0]
	v_pk_fma_f32 v[24:25], v[140:141], v[72:73], v[130:131] op_sel_hi:[0,1,1] neg_lo:[1,0,0] neg_hi:[1,0,0]
	v_pk_fma_f32 v[26:27], v[140:141], v[74:75], v[132:133] op_sel_hi:[0,1,1] neg_lo:[1,0,0] neg_hi:[1,0,0]
	v_pk_fma_f32 v[28:29], v[140:141], v[76:77], v[134:135] op_sel_hi:[0,1,1] neg_lo:[1,0,0] neg_hi:[1,0,0]
	ds_read_b128 v[70:73], v112 offset:11264
	ds_read_b128 v[74:77], v112 offset:11280
	ds_write_b32 v108, v142 offset:25856
	s_waitcnt lgkmcnt(3)
	v_pk_mul_f32 v[136:137], v[22:23], v[30:31]
	v_pk_mul_f32 v[138:139], v[22:23], v[96:97]
	v_pk_fma_f32 v[136:137], v[24:25], v[32:33], v[136:137]
	v_pk_fma_f32 v[138:139], v[24:25], v[98:99], v[138:139]
	v_pk_fma_f32 v[136:137], v[26:27], v[34:35], v[136:137]
	v_pk_fma_f32 v[138:139], v[26:27], v[100:101], v[138:139]
	v_pk_fma_f32 v[136:137], v[28:29], v[36:37], v[136:137]
	v_pk_fma_f32 v[138:139], v[28:29], v[102:103], v[138:139]
	ds_read_b128 v[30:33], v112 offset:3328
	ds_read_b128 v[34:37], v112 offset:3344
	ds_read_b128 v[96:99], v112 offset:19456
	ds_read_b128 v[100:103], v112 offset:19472
	v_add_f32_e32 v140, v136, v137
	v_add_f32_e32 v142, v138, v139
	v_pk_mul_f32 v[128:129], v[22:23], v[38:39]
	v_add_f32_dpp v140, v140, v140 row_half_mirror row_mask:0xf bank_mask:0xf
	v_add_f32_dpp v142, v142, v142 row_half_mirror row_mask:0xf bank_mask:0xf
	v_pk_mul_f32 v[130:131], v[24:25], v[40:41]
	v_pk_mul_f32 v[132:133], v[26:27], v[42:43]
	v_add_f32_dpp v140, v140, v140 quad_perm:[1,0,3,2] row_mask:0xf bank_mask:0xf
	v_add_f32_dpp v142, v142, v142 quad_perm:[1,0,3,2] row_mask:0xf bank_mask:0xf
	v_pk_mul_f32 v[134:135], v[28:29], v[44:45]
	ds_read_b128 v[38:41], v112 offset:7424
	ds_read_b128 v[42:45], v112 offset:7440
	v_add_f32_dpp v140, v140, v140 quad_perm:[2,3,0,1] row_mask:0xf bank_mask:0xf
	v_add_f32_dpp v142, v142, v142 quad_perm:[2,3,0,1] row_mask:0xf bank_mask:0xf
	s_waitcnt lgkmcnt(7)
	v_pk_fma_f32 v[22:23], v[140:141], v[70:71], v[128:129] op_sel_hi:[0,1,1] neg_lo:[1,0,0] neg_hi:[1,0,0]
	v_pk_fma_f32 v[24:25], v[140:141], v[72:73], v[130:131] op_sel_hi:[0,1,1] neg_lo:[1,0,0] neg_hi:[1,0,0]
	v_pk_fma_f32 v[26:27], v[140:141], v[74:75], v[132:133] op_sel_hi:[0,1,1] neg_lo:[1,0,0] neg_hi:[1,0,0]
	v_pk_fma_f32 v[28:29], v[140:141], v[76:77], v[134:135] op_sel_hi:[0,1,1] neg_lo:[1,0,0] neg_hi:[1,0,0]
	ds_read_b128 v[70:73], v112 offset:11520
	ds_read_b128 v[74:77], v112 offset:11536
	ds_write_b32 v108, v142 offset:25984
	s_waitcnt lgkmcnt(3)
	v_pk_mul_f32 v[136:137], v[22:23], v[30:31]
	v_pk_mul_f32 v[138:139], v[22:23], v[96:97]
	v_pk_fma_f32 v[136:137], v[24:25], v[32:33], v[136:137]
	v_pk_fma_f32 v[138:139], v[24:25], v[98:99], v[138:139]
	v_pk_fma_f32 v[136:137], v[26:27], v[34:35], v[136:137]
	v_pk_fma_f32 v[138:139], v[26:27], v[100:101], v[138:139]
	v_pk_fma_f32 v[136:137], v[28:29], v[36:37], v[136:137]
	v_pk_fma_f32 v[138:139], v[28:29], v[102:103], v[138:139]
	ds_read_b128 v[30:33], v112 offset:3584
	ds_read_b128 v[34:37], v112 offset:3600
	ds_read_b128 v[96:99], v112 offset:19712
	ds_read_b128 v[100:103], v112 offset:19728
	v_add_f32_e32 v140, v136, v137
	v_add_f32_e32 v142, v138, v139
	v_pk_mul_f32 v[128:129], v[22:23], v[38:39]
	v_add_f32_dpp v140, v140, v140 row_half_mirror row_mask:0xf bank_mask:0xf
	v_add_f32_dpp v142, v142, v142 row_half_mirror row_mask:0xf bank_mask:0xf
	v_pk_mul_f32 v[130:131], v[24:25], v[40:41]
	v_pk_mul_f32 v[132:133], v[26:27], v[42:43]
	v_add_f32_dpp v140, v140, v140 quad_perm:[1,0,3,2] row_mask:0xf bank_mask:0xf
	v_add_f32_dpp v142, v142, v142 quad_perm:[1,0,3,2] row_mask:0xf bank_mask:0xf
	v_pk_mul_f32 v[134:135], v[28:29], v[44:45]
	ds_read_b128 v[38:41], v112 offset:7680
	ds_read_b128 v[42:45], v112 offset:7696
	v_add_f32_dpp v140, v140, v140 quad_perm:[2,3,0,1] row_mask:0xf bank_mask:0xf
	v_add_f32_dpp v142, v142, v142 quad_perm:[2,3,0,1] row_mask:0xf bank_mask:0xf
	s_waitcnt lgkmcnt(7)
	v_pk_fma_f32 v[22:23], v[140:141], v[70:71], v[128:129] op_sel_hi:[0,1,1] neg_lo:[1,0,0] neg_hi:[1,0,0]
	v_pk_fma_f32 v[24:25], v[140:141], v[72:73], v[130:131] op_sel_hi:[0,1,1] neg_lo:[1,0,0] neg_hi:[1,0,0]
	v_pk_fma_f32 v[26:27], v[140:141], v[74:75], v[132:133] op_sel_hi:[0,1,1] neg_lo:[1,0,0] neg_hi:[1,0,0]
	v_pk_fma_f32 v[28:29], v[140:141], v[76:77], v[134:135] op_sel_hi:[0,1,1] neg_lo:[1,0,0] neg_hi:[1,0,0]
	ds_read_b128 v[70:73], v112 offset:11776
	ds_read_b128 v[74:77], v112 offset:11792
	ds_write_b32 v108, v142 offset:26112
	s_waitcnt lgkmcnt(3)
	v_pk_mul_f32 v[136:137], v[22:23], v[30:31]
	v_pk_mul_f32 v[138:139], v[22:23], v[96:97]
	v_pk_fma_f32 v[136:137], v[24:25], v[32:33], v[136:137]
	v_pk_fma_f32 v[138:139], v[24:25], v[98:99], v[138:139]
	v_pk_fma_f32 v[136:137], v[26:27], v[34:35], v[136:137]
	v_pk_fma_f32 v[138:139], v[26:27], v[100:101], v[138:139]
	v_pk_fma_f32 v[136:137], v[28:29], v[36:37], v[136:137]
	v_pk_fma_f32 v[138:139], v[28:29], v[102:103], v[138:139]
	ds_read_b128 v[30:33], v112 offset:3840
	ds_read_b128 v[34:37], v112 offset:3856
	ds_read_b128 v[96:99], v112 offset:19968
	ds_read_b128 v[100:103], v112 offset:19984
	v_add_f32_e32 v140, v136, v137
	v_add_f32_e32 v142, v138, v139
	v_pk_mul_f32 v[128:129], v[22:23], v[38:39]
	v_add_f32_dpp v140, v140, v140 row_half_mirror row_mask:0xf bank_mask:0xf
	v_add_f32_dpp v142, v142, v142 row_half_mirror row_mask:0xf bank_mask:0xf
	v_pk_mul_f32 v[130:131], v[24:25], v[40:41]
	v_pk_mul_f32 v[132:133], v[26:27], v[42:43]
	v_add_f32_dpp v140, v140, v140 quad_perm:[1,0,3,2] row_mask:0xf bank_mask:0xf
	v_add_f32_dpp v142, v142, v142 quad_perm:[1,0,3,2] row_mask:0xf bank_mask:0xf
	v_pk_mul_f32 v[134:135], v[28:29], v[44:45]
	ds_read_b128 v[38:41], v112 offset:7936
	ds_read_b128 v[42:45], v112 offset:7952
	v_add_f32_dpp v140, v140, v140 quad_perm:[2,3,0,1] row_mask:0xf bank_mask:0xf
	v_add_f32_dpp v142, v142, v142 quad_perm:[2,3,0,1] row_mask:0xf bank_mask:0xf
	s_waitcnt lgkmcnt(7)
	v_pk_fma_f32 v[22:23], v[140:141], v[70:71], v[128:129] op_sel_hi:[0,1,1] neg_lo:[1,0,0] neg_hi:[1,0,0]
	v_pk_fma_f32 v[24:25], v[140:141], v[72:73], v[130:131] op_sel_hi:[0,1,1] neg_lo:[1,0,0] neg_hi:[1,0,0]
	v_pk_fma_f32 v[26:27], v[140:141], v[74:75], v[132:133] op_sel_hi:[0,1,1] neg_lo:[1,0,0] neg_hi:[1,0,0]
	v_pk_fma_f32 v[28:29], v[140:141], v[76:77], v[134:135] op_sel_hi:[0,1,1] neg_lo:[1,0,0] neg_hi:[1,0,0]
	ds_read_b128 v[70:73], v112 offset:12032
	ds_read_b128 v[74:77], v112 offset:12048
	ds_write_b32 v108, v142 offset:26240
	s_waitcnt lgkmcnt(3)
	v_pk_mul_f32 v[136:137], v[22:23], v[30:31]
	v_pk_mul_f32 v[138:139], v[22:23], v[96:97]
	v_pk_fma_f32 v[136:137], v[24:25], v[32:33], v[136:137]
	v_pk_fma_f32 v[138:139], v[24:25], v[98:99], v[138:139]
	v_pk_fma_f32 v[136:137], v[26:27], v[34:35], v[136:137]
	v_pk_fma_f32 v[138:139], v[26:27], v[100:101], v[138:139]
	v_pk_fma_f32 v[136:137], v[28:29], v[36:37], v[136:137]
	v_pk_fma_f32 v[138:139], v[28:29], v[102:103], v[138:139]
	ds_read_b128 v[96:99], v112 offset:20224
	ds_read_b128 v[100:103], v112 offset:20240
	v_add_f32_e32 v140, v136, v137
	v_add_f32_e32 v142, v138, v139
	v_pk_mul_f32 v[128:129], v[22:23], v[38:39]
	v_add_f32_dpp v140, v140, v140 row_half_mirror row_mask:0xf bank_mask:0xf
	v_add_f32_dpp v142, v142, v142 row_half_mirror row_mask:0xf bank_mask:0xf
	v_pk_mul_f32 v[130:131], v[24:25], v[40:41]
	v_pk_mul_f32 v[132:133], v[26:27], v[42:43]
	v_add_f32_dpp v140, v140, v140 quad_perm:[1,0,3,2] row_mask:0xf bank_mask:0xf
	v_add_f32_dpp v142, v142, v142 quad_perm:[1,0,3,2] row_mask:0xf bank_mask:0xf
	v_pk_mul_f32 v[134:135], v[28:29], v[44:45]
	v_add_f32_dpp v140, v140, v140 quad_perm:[2,3,0,1] row_mask:0xf bank_mask:0xf
	v_add_f32_dpp v142, v142, v142 quad_perm:[2,3,0,1] row_mask:0xf bank_mask:0xf
	s_waitcnt lgkmcnt(3)
	v_pk_fma_f32 v[22:23], v[140:141], v[70:71], v[128:129] op_sel_hi:[0,1,1] neg_lo:[1,0,0] neg_hi:[1,0,0]
	v_pk_fma_f32 v[24:25], v[140:141], v[72:73], v[130:131] op_sel_hi:[0,1,1] neg_lo:[1,0,0] neg_hi:[1,0,0]
	v_pk_fma_f32 v[26:27], v[140:141], v[74:75], v[132:133] op_sel_hi:[0,1,1] neg_lo:[1,0,0] neg_hi:[1,0,0]
	v_pk_fma_f32 v[28:29], v[140:141], v[76:77], v[134:135] op_sel_hi:[0,1,1] neg_lo:[1,0,0] neg_hi:[1,0,0]
	ds_write_b32 v108, v142 offset:26368
	s_waitcnt lgkmcnt(1)
	v_pk_mul_f32 v[138:139], v[22:23], v[96:97]
	v_pk_fma_f32 v[138:139], v[24:25], v[98:99], v[138:139]
	v_pk_fma_f32 v[138:139], v[26:27], v[100:101], v[138:139]
	v_pk_fma_f32 v[138:139], v[28:29], v[102:103], v[138:139]
	v_add_f32_e32 v142, v138, v139
	s_nop 1
	v_add_f32_dpp v142, v142, v142 row_half_mirror row_mask:0xf bank_mask:0xf
	s_nop 1
	v_add_f32_dpp v142, v142, v142 quad_perm:[1,0,3,2] row_mask:0xf bank_mask:0xf
	s_nop 1
	v_add_f32_dpp v142, v142, v142 quad_perm:[2,3,0,1] row_mask:0xf bank_mask:0xf
	ds_write_b32 v108, v142 offset:26496
